# speedup vs baseline: 1.0064x; 1.0064x over previous
.LBB0_110:
	ds_read_b128 v[140:143], v138
	ds_read_b128 v[144:147], v138 offset:1024
	ds_read_b128 v[148:151], v138 offset:2048
	ds_read_b128 v[152:155], v138 offset:3072
	ds_read_b128 v[156:159], v192
	ds_read_b128 v[160:163], v192 offset:1024
	ds_read_b128 v[194:197], v191
	ds_read_b128 v[198:201], v191 offset:1024
	ds_read_b128 v[202:205], v190
	ds_read_b128 v[206:209], v190 offset:1024
	ds_read_b128 v[210:213], v189
	ds_read_b128 v[214:217], v189 offset:1024
	s_waitcnt lgkmcnt(8)
	s_waitcnt vmcnt(10)
	s_barrier
	s_waitcnt lgkmcnt(0)
	s_waitcnt lgkmcnt(0)
	v_mfma_f32_16x16x32_bf16 v[124:127], v[140:143], v[156:159], v[124:127]
	v_mfma_f32_16x16x32_bf16 v[120:123], v[148:151], v[156:159], v[120:123]
	v_mfma_f32_16x16x32_bf16 v[116:119], v[140:143], v[194:197], v[116:119]
	v_mfma_f32_16x16x32_bf16 v[112:115], v[148:151], v[194:197], v[112:115]
	v_mfma_f32_16x16x32_bf16 v[108:111], v[140:143], v[202:205], v[108:111]
	v_mfma_f32_16x16x32_bf16 v[104:107], v[148:151], v[202:205], v[104:107]
	v_mfma_f32_16x16x32_bf16 v[100:103], v[140:143], v[210:213], v[100:103]
	v_mfma_f32_16x16x32_bf16 v[96:99], v[148:151], v[210:213], v[96:99]
	v_mfma_f32_16x16x32_bf16 v[124:127], v[144:147], v[160:163], v[124:127]
	v_mfma_f32_16x16x32_bf16 v[120:123], v[152:155], v[160:163], v[120:123]
	v_mfma_f32_16x16x32_bf16 v[116:119], v[144:147], v[198:201], v[116:119]
	v_mfma_f32_16x16x32_bf16 v[112:115], v[152:155], v[198:201], v[112:115]
	v_mfma_f32_16x16x32_bf16 v[108:111], v[144:147], v[206:209], v[108:111]
	v_mfma_f32_16x16x32_bf16 v[104:107], v[152:155], v[206:209], v[104:107]
	v_mfma_f32_16x16x32_bf16 v[100:103], v[144:147], v[214:217], v[100:103]
	v_mfma_f32_16x16x32_bf16 v[96:99], v[152:155], v[214:217], v[96:99]
	s_barrier
	v_readfirstlane_b32 s63, v188
	v_lshl_add_u64 v[234:235], s[66:67], 0, v[164:165]
	s_mov_b32 m0, s63
	v_readfirstlane_b32 s63, v187
	ds_read_b128 v[218:221], v135
	ds_read_b128 v[222:225], v135 offset:1024
	ds_read_b128 v[226:229], v135 offset:2048
	ds_read_b128 v[230:233], v135 offset:3072
	global_load_lds_dwordx4 v[234:235], off
	v_lshl_add_u64 v[236:237], v[234:235], 0, s[10:11]
	s_mov_b32 m0, s63
	s_nop 0
	global_load_lds_dwordx4 v[236:237], off
	v_readfirstlane_b32 s63, v169
	v_lshl_add_u64 v[236:237], v[128:129], 0, s[26:27]
	s_mov_b32 m0, s63
	v_readfirstlane_b32 s63, v186
	global_load_lds_dwordx4 v[236:237], off
	v_lshl_add_u64 v[236:237], v[128:129], 0, s[28:29]
	s_mov_b32 m0, s63
	s_nop 0
	global_load_lds_dwordx4 v[236:237], off
	s_waitcnt vmcnt(12)
	s_barrier
	s_waitcnt lgkmcnt(0)
	s_waitcnt lgkmcnt(0)
	v_mfma_f32_16x16x32_bf16 v[92:95], v[218:221], v[156:159], v[92:95]
	v_mfma_f32_16x16x32_bf16 v[88:91], v[226:229], v[156:159], v[88:91]
	v_mfma_f32_16x16x32_bf16 v[84:87], v[218:221], v[194:197], v[84:87]
	v_mfma_f32_16x16x32_bf16 v[80:83], v[226:229], v[194:197], v[80:83]
	v_mfma_f32_16x16x32_bf16 v[76:79], v[218:221], v[202:205], v[76:79]
	v_mfma_f32_16x16x32_bf16 v[72:75], v[226:229], v[202:205], v[72:75]
	v_mfma_f32_16x16x32_bf16 v[68:71], v[218:221], v[210:213], v[68:71]
	v_mfma_f32_16x16x32_bf16 v[64:67], v[226:229], v[210:213], v[64:67]
	v_mfma_f32_16x16x32_bf16 v[92:95], v[222:225], v[160:163], v[92:95]
	v_mfma_f32_16x16x32_bf16 v[88:91], v[230:233], v[160:163], v[88:91]
	v_mfma_f32_16x16x32_bf16 v[84:87], v[222:225], v[198:201], v[84:87]
	v_mfma_f32_16x16x32_bf16 v[80:83], v[230:233], v[198:201], v[80:83]
	v_mfma_f32_16x16x32_bf16 v[76:79], v[222:225], v[206:209], v[76:79]
	v_mfma_f32_16x16x32_bf16 v[72:75], v[230:233], v[206:209], v[72:75]
	v_mfma_f32_16x16x32_bf16 v[68:71], v[222:225], v[214:217], v[68:71]
	v_mfma_f32_16x16x32_bf16 v[64:67], v[230:233], v[214:217], v[64:67]
	s_barrier
	ds_read_b128 v[156:159], v192 offset:16384
	ds_read_b128 v[160:163], v192 offset:17408
	ds_read_b128 v[194:197], v191 offset:16384
	ds_read_b128 v[198:201], v191 offset:17408
	ds_read_b128 v[202:205], v190 offset:16384
	ds_read_b128 v[206:209], v190 offset:17408
	ds_read_b128 v[210:213], v189 offset:16384
	ds_read_b128 v[214:217], v189 offset:17408
	v_readfirstlane_b32 s63, v185
	v_lshl_add_u64 v[236:237], v[234:235], 0, s[30:31]
	s_mov_b32 m0, s63
	v_readfirstlane_b32 s63, v184
	global_load_lds_dwordx4 v[236:237], off
	v_lshl_add_u64 v[236:237], v[234:235], 0, s[34:35]
	s_mov_b32 m0, s63
	s_nop 0
	global_load_lds_dwordx4 v[236:237], off
	s_barrier
	s_waitcnt lgkmcnt(0)
	s_waitcnt lgkmcnt(0)
	v_mfma_f32_16x16x32_bf16 v[60:63], v[140:143], v[156:159], v[60:63]
	v_mfma_f32_16x16x32_bf16 v[56:59], v[148:151], v[156:159], v[56:59]
	v_mfma_f32_16x16x32_bf16 v[52:55], v[140:143], v[194:197], v[52:55]
	v_mfma_f32_16x16x32_bf16 v[48:51], v[148:151], v[194:197], v[48:51]
	v_mfma_f32_16x16x32_bf16 v[44:47], v[140:143], v[202:205], v[44:47]
	v_mfma_f32_16x16x32_bf16 v[40:43], v[148:151], v[202:205], v[40:43]
	v_mfma_f32_16x16x32_bf16 v[36:39], v[140:143], v[210:213], v[36:39]
	v_mfma_f32_16x16x32_bf16 v[32:35], v[148:151], v[210:213], v[32:35]
	v_mfma_f32_16x16x32_bf16 v[60:63], v[144:147], v[160:163], v[60:63]
	v_mfma_f32_16x16x32_bf16 v[56:59], v[152:155], v[160:163], v[56:59]
	v_mfma_f32_16x16x32_bf16 v[52:55], v[144:147], v[198:201], v[52:55]
	v_mfma_f32_16x16x32_bf16 v[48:51], v[152:155], v[198:201], v[48:51]
	v_mfma_f32_16x16x32_bf16 v[44:47], v[144:147], v[206:209], v[44:47]
	v_mfma_f32_16x16x32_bf16 v[40:43], v[152:155], v[206:209], v[40:43]
	v_mfma_f32_16x16x32_bf16 v[36:39], v[144:147], v[214:217], v[36:39]
	v_mfma_f32_16x16x32_bf16 v[32:35], v[152:155], v[214:217], v[32:35]
	s_barrier
	v_readfirstlane_b32 s63, v183
	v_lshl_add_u64 v[142:143], v[128:129], 0, s[40:41]
	s_mov_b32 m0, s63
	v_readfirstlane_b32 s63, v182
	global_load_lds_dwordx4 v[142:143], off
	s_mov_b32 m0, s63
	s_nop 0
	global_load_lds_dwordx4 v[128:129], off
	s_waitcnt vmcnt(12)
	s_barrier
	v_mfma_f32_16x16x32_bf16 v[28:31], v[218:221], v[156:159], v[28:31]
	v_mfma_f32_16x16x32_bf16 v[24:27], v[226:229], v[156:159], v[24:27]
	v_mfma_f32_16x16x32_bf16 v[20:23], v[218:221], v[194:197], v[20:23]
	v_mfma_f32_16x16x32_bf16 v[16:19], v[226:229], v[194:197], v[16:19]
	v_mfma_f32_16x16x32_bf16 v[12:15], v[218:221], v[202:205], v[12:15]
	v_mfma_f32_16x16x32_bf16 v[8:11], v[226:229], v[202:205], v[8:11]
	v_mfma_f32_16x16x32_bf16 v[4:7], v[218:221], v[210:213], v[4:7]
	v_mfma_f32_16x16x32_bf16 v[0:3], v[226:229], v[210:213], v[0:3]
	v_mfma_f32_16x16x32_bf16 v[28:31], v[222:225], v[160:163], v[28:31]
	v_mfma_f32_16x16x32_bf16 v[24:27], v[230:233], v[160:163], v[24:27]
	v_mfma_f32_16x16x32_bf16 v[20:23], v[222:225], v[198:201], v[20:23]
	v_mfma_f32_16x16x32_bf16 v[16:19], v[230:233], v[198:201], v[16:19]
	v_mfma_f32_16x16x32_bf16 v[12:15], v[222:225], v[206:209], v[12:15]
	v_mfma_f32_16x16x32_bf16 v[8:11], v[230:233], v[206:209], v[8:11]
	v_mfma_f32_16x16x32_bf16 v[4:7], v[222:225], v[214:217], v[4:7]
	v_mfma_f32_16x16x32_bf16 v[0:3], v[230:233], v[214:217], v[0:3]
	s_barrier
	ds_read_b128 v[140:143], v130
	ds_read_b128 v[144:147], v130 offset:1024
	ds_read_b128 v[148:151], v130 offset:2048
	ds_read_b128 v[152:155], v130 offset:3072
	ds_read_b128 v[156:159], v192 offset:32768
	ds_read_b128 v[160:163], v192 offset:33792
	ds_read_b128 v[194:197], v191 offset:32768
	ds_read_b128 v[198:201], v191 offset:33792
	ds_read_b128 v[202:205], v190 offset:32768
	ds_read_b128 v[206:209], v190 offset:33792
	ds_read_b128 v[210:213], v189 offset:32768
	ds_read_b128 v[214:217], v189 offset:33792
	s_waitcnt lgkmcnt(8)
	s_waitcnt vmcnt(10)
	s_barrier
	s_waitcnt lgkmcnt(0)
	s_waitcnt lgkmcnt(0)
	v_mfma_f32_16x16x32_bf16 v[124:127], v[140:143], v[156:159], v[124:127]
	v_mfma_f32_16x16x32_bf16 v[120:123], v[148:151], v[156:159], v[120:123]
	v_mfma_f32_16x16x32_bf16 v[116:119], v[140:143], v[194:197], v[116:119]
	v_mfma_f32_16x16x32_bf16 v[112:115], v[148:151], v[194:197], v[112:115]
	v_mfma_f32_16x16x32_bf16 v[108:111], v[140:143], v[202:205], v[108:111]
	v_mfma_f32_16x16x32_bf16 v[104:107], v[148:151], v[202:205], v[104:107]
	v_mfma_f32_16x16x32_bf16 v[100:103], v[140:143], v[210:213], v[100:103]
	v_mfma_f32_16x16x32_bf16 v[96:99], v[148:151], v[210:213], v[96:99]
	v_mfma_f32_16x16x32_bf16 v[124:127], v[144:147], v[160:163], v[124:127]
	v_mfma_f32_16x16x32_bf16 v[120:123], v[152:155], v[160:163], v[120:123]
	v_mfma_f32_16x16x32_bf16 v[116:119], v[144:147], v[198:201], v[116:119]
	v_mfma_f32_16x16x32_bf16 v[112:115], v[152:155], v[198:201], v[112:115]
	v_mfma_f32_16x16x32_bf16 v[108:111], v[144:147], v[206:209], v[108:111]
	v_mfma_f32_16x16x32_bf16 v[104:107], v[152:155], v[206:209], v[104:107]
	v_mfma_f32_16x16x32_bf16 v[100:103], v[144:147], v[214:217], v[100:103]
	v_mfma_f32_16x16x32_bf16 v[96:99], v[152:155], v[214:217], v[96:99]
	s_barrier
	v_readfirstlane_b32 s63, v181
	v_lshl_add_u64 v[234:235], s[64:65], 0, v[164:165]
	s_mov_b32 m0, s63
	v_readfirstlane_b32 s63, v180
	ds_read_b128 v[218:221], v132
	ds_read_b128 v[222:225], v132 offset:1024
	ds_read_b128 v[226:229], v132 offset:2048
	ds_read_b128 v[230:233], v132 offset:3072
	global_load_lds_dwordx4 v[234:235], off
	v_lshl_add_u64 v[236:237], v[234:235], 0, s[10:11]
	s_mov_b32 m0, s63
	s_nop 0
	global_load_lds_dwordx4 v[236:237], off
	v_readfirstlane_b32 s63, v179
	v_lshl_add_u64 v[236:237], v[128:129], 0, s[44:45]
	s_mov_b32 m0, s63
	v_readfirstlane_b32 s63, v177
	global_load_lds_dwordx4 v[236:237], off
	v_lshl_add_u64 v[236:237], v[128:129], 0, s[46:47]
	s_mov_b32 m0, s63
	s_nop 0
	global_load_lds_dwordx4 v[236:237], off
	s_waitcnt vmcnt(12)
	s_barrier
	s_waitcnt lgkmcnt(0)
	s_waitcnt lgkmcnt(0)
	v_mfma_f32_16x16x32_bf16 v[92:95], v[218:221], v[156:159], v[92:95]
	v_mfma_f32_16x16x32_bf16 v[88:91], v[226:229], v[156:159], v[88:91]
	v_mfma_f32_16x16x32_bf16 v[84:87], v[218:221], v[194:197], v[84:87]
	v_mfma_f32_16x16x32_bf16 v[80:83], v[226:229], v[194:197], v[80:83]
	v_mfma_f32_16x16x32_bf16 v[76:79], v[218:221], v[202:205], v[76:79]
	v_mfma_f32_16x16x32_bf16 v[72:75], v[226:229], v[202:205], v[72:75]
	v_mfma_f32_16x16x32_bf16 v[68:71], v[218:221], v[210:213], v[68:71]
	v_mfma_f32_16x16x32_bf16 v[64:67], v[226:229], v[210:213], v[64:67]
	v_mfma_f32_16x16x32_bf16 v[92:95], v[222:225], v[160:163], v[92:95]
	v_mfma_f32_16x16x32_bf16 v[88:91], v[230:233], v[160:163], v[88:91]
	v_mfma_f32_16x16x32_bf16 v[84:87], v[222:225], v[198:201], v[84:87]
	v_mfma_f32_16x16x32_bf16 v[80:83], v[230:233], v[198:201], v[80:83]
	v_mfma_f32_16x16x32_bf16 v[76:79], v[222:225], v[206:209], v[76:79]
	v_mfma_f32_16x16x32_bf16 v[72:75], v[230:233], v[206:209], v[72:75]
	v_mfma_f32_16x16x32_bf16 v[68:71], v[222:225], v[214:217], v[68:71]
	v_mfma_f32_16x16x32_bf16 v[64:67], v[230:233], v[214:217], v[64:67]
	s_barrier
	ds_read_b128 v[156:159], v192 offset:49152
	ds_read_b128 v[160:163], v192 offset:50176
	ds_read_b128 v[194:197], v191 offset:49152
	ds_read_b128 v[198:201], v191 offset:50176
	ds_read_b128 v[202:205], v190 offset:49152
	ds_read_b128 v[206:209], v190 offset:50176
	ds_read_b128 v[210:213], v189 offset:49152
	ds_read_b128 v[214:217], v189 offset:50176
	v_readfirstlane_b32 s63, v175
	v_lshl_add_u64 v[236:237], v[234:235], 0, s[30:31]
	s_mov_b32 m0, s63
	v_readfirstlane_b32 s63, v173
	global_load_lds_dwordx4 v[236:237], off
	v_lshl_add_u64 v[236:237], v[234:235], 0, s[34:35]
	s_mov_b32 m0, s63
	s_nop 0
	global_load_lds_dwordx4 v[236:237], off
	s_barrier
	s_waitcnt lgkmcnt(0)
	s_waitcnt lgkmcnt(0)
	v_mfma_f32_16x16x32_bf16 v[60:63], v[140:143], v[156:159], v[60:63]
	v_mfma_f32_16x16x32_bf16 v[56:59], v[148:151], v[156:159], v[56:59]
	v_mfma_f32_16x16x32_bf16 v[52:55], v[140:143], v[194:197], v[52:55]
	v_mfma_f32_16x16x32_bf16 v[48:51], v[148:151], v[194:197], v[48:51]
	v_mfma_f32_16x16x32_bf16 v[44:47], v[140:143], v[202:205], v[44:47]
	v_mfma_f32_16x16x32_bf16 v[40:43], v[148:151], v[202:205], v[40:43]
	v_mfma_f32_16x16x32_bf16 v[36:39], v[140:143], v[210:213], v[36:39]
	v_mfma_f32_16x16x32_bf16 v[32:35], v[148:151], v[210:213], v[32:35]
	v_mfma_f32_16x16x32_bf16 v[60:63], v[144:147], v[160:163], v[60:63]
	v_mfma_f32_16x16x32_bf16 v[56:59], v[152:155], v[160:163], v[56:59]
	v_mfma_f32_16x16x32_bf16 v[52:55], v[144:147], v[198:201], v[52:55]
	v_mfma_f32_16x16x32_bf16 v[48:51], v[152:155], v[198:201], v[48:51]
	v_mfma_f32_16x16x32_bf16 v[44:47], v[144:147], v[206:209], v[44:47]
	v_mfma_f32_16x16x32_bf16 v[40:43], v[152:155], v[206:209], v[40:43]
	v_mfma_f32_16x16x32_bf16 v[36:39], v[144:147], v[214:217], v[36:39]
	v_mfma_f32_16x16x32_bf16 v[32:35], v[152:155], v[214:217], v[32:35]
	s_barrier
	v_lshl_add_u64 v[128:129], v[128:129], 0, s[56:57]
	v_readfirstlane_b32 s63, v137
	v_lshl_add_u64 v[142:143], v[128:129], 0, s[22:23]
	s_mov_b32 m0, s63
	v_readfirstlane_b32 s63, v136
	global_load_lds_dwordx4 v[142:143], off
	v_lshl_add_u64 v[142:143], v[128:129], 0, s[24:25]
	s_mov_b32 m0, s63
	s_nop 0
	global_load_lds_dwordx4 v[142:143], off
	s_waitcnt vmcnt(12)
	s_barrier
	v_mfma_f32_16x16x32_bf16 v[28:31], v[218:221], v[156:159], v[28:31]
	v_mfma_f32_16x16x32_bf16 v[24:27], v[226:229], v[156:159], v[24:27]
	v_mfma_f32_16x16x32_bf16 v[20:23], v[218:221], v[194:197], v[20:23]
	v_mfma_f32_16x16x32_bf16 v[16:19], v[226:229], v[194:197], v[16:19]
	v_mfma_f32_16x16x32_bf16 v[12:15], v[218:221], v[202:205], v[12:15]
	v_mfma_f32_16x16x32_bf16 v[8:11], v[226:229], v[202:205], v[8:11]
	v_mfma_f32_16x16x32_bf16 v[4:7], v[218:221], v[210:213], v[4:7]
	v_mfma_f32_16x16x32_bf16 v[0:3], v[226:229], v[210:213], v[0:3]
	v_mfma_f32_16x16x32_bf16 v[28:31], v[222:225], v[160:163], v[28:31]
	v_mfma_f32_16x16x32_bf16 v[24:27], v[230:233], v[160:163], v[24:27]
	v_mfma_f32_16x16x32_bf16 v[20:23], v[222:225], v[198:201], v[20:23]
	v_mfma_f32_16x16x32_bf16 v[16:19], v[230:233], v[198:201], v[16:19]
	v_mfma_f32_16x16x32_bf16 v[12:15], v[222:225], v[206:209], v[12:15]
	v_mfma_f32_16x16x32_bf16 v[8:11], v[230:233], v[206:209], v[8:11]
	v_mfma_f32_16x16x32_bf16 v[4:7], v[222:225], v[214:217], v[4:7]
	v_mfma_f32_16x16x32_bf16 v[0:3], v[230:233], v[214:217], v[0:3]
	s_add_i32 s4, s4, 2
	s_add_u32 s64, s64, s68
	s_addc_u32 s65, s65, s69
	s_add_u32 s66, s66, s68
	s_addc_u32 s67, s67, s69
	s_cmp_lt_u32 s4, 28
	s_barrier
	s_cbranch_scc1 .LBB0_110
	s_lshl_b32 s4, s70, 11
	s_or_b32 s64, s71, s4
	s_or_b32 s66, s64, 0x80
	v_lshlrev_b32_e32 v128, 3, v131
	v_lshlrev_b32_e32 v129, 5, v131
	s_ashr_i32 s67, s66, 31
	v_and_b32_e32 v128, 0xffff0, v128
	v_and_b32_e32 v129, 32, v129
	s_lshl_b64 s[66:67], s[66:67], 12
	v_add_u32_e32 v129, v129, v134
	v_add_lshl_u32 v128, v133, v128, 12
	s_add_u32 s66, s54, s66
	v_lshl_add_u32 v164, v129, 1, v128
	s_addc_u32 s67, s55, s67
	v_lshl_add_u64 v[128:129], s[66:67], 0, v[164:165]
	v_readfirstlane_b32 s4, v137
	ds_read_b128 v[140:143], v138
	ds_read_b128 v[144:147], v138 offset:1024
	ds_read_b128 v[148:151], v138 offset:2048
	ds_read_b128 v[152:155], v138 offset:3072
	ds_read_b128 v[156:159], v192
	ds_read_b128 v[160:163], v192 offset:1024
	ds_read_b128 v[194:197], v191
	ds_read_b128 v[198:201], v191 offset:1024
	ds_read_b128 v[202:205], v190
	ds_read_b128 v[206:209], v190 offset:1024
	ds_read_b128 v[210:213], v189
	ds_read_b128 v[214:217], v189 offset:1024
	v_lshl_add_u64 v[138:139], v[128:129], 0, s[58:59]
	s_mov_b32 m0, s4
	v_readfirstlane_b32 s4, v136
	global_load_lds_dwordx4 v[138:139], off
	v_lshl_add_u64 v[128:129], v[128:129], 0, s[60:61]
	s_mov_b32 m0, s4
	s_ashr_i32 s65, s64, 31
	global_load_lds_dwordx4 v[128:129], off
	s_waitcnt vmcnt(10)
	s_barrier
	s_waitcnt lgkmcnt(0)
	s_setprio 1
	s_waitcnt lgkmcnt(0)
	v_mfma_f32_16x16x32_bf16 v[124:127], v[140:143], v[156:159], v[124:127]
	v_mfma_f32_16x16x32_bf16 v[120:123], v[148:151], v[156:159], v[120:123]
	v_mfma_f32_16x16x32_bf16 v[116:119], v[140:143], v[194:197], v[116:119]
	v_mfma_f32_16x16x32_bf16 v[112:115], v[148:151], v[194:197], v[112:115]
	v_mfma_f32_16x16x32_bf16 v[108:111], v[140:143], v[202:205], v[108:111]
	v_mfma_f32_16x16x32_bf16 v[104:107], v[148:151], v[202:205], v[104:107]
	v_mfma_f32_16x16x32_bf16 v[100:103], v[140:143], v[210:213], v[100:103]
	v_mfma_f32_16x16x32_bf16 v[96:99], v[148:151], v[210:213], v[96:99]
	v_mfma_f32_16x16x32_bf16 v[124:127], v[144:147], v[160:163], v[124:127]
	v_mfma_f32_16x16x32_bf16 v[120:123], v[152:155], v[160:163], v[120:123]
	v_mfma_f32_16x16x32_bf16 v[116:119], v[144:147], v[198:201], v[116:119]
	v_mfma_f32_16x16x32_bf16 v[112:115], v[152:155], v[198:201], v[112:115]
	v_mfma_f32_16x16x32_bf16 v[108:111], v[144:147], v[206:209], v[108:111]
	v_mfma_f32_16x16x32_bf16 v[104:107], v[152:155], v[206:209], v[104:107]
	v_mfma_f32_16x16x32_bf16 v[100:103], v[144:147], v[214:217], v[100:103]
	v_mfma_f32_16x16x32_bf16 v[96:99], v[152:155], v[214:217], v[96:99]
	s_setprio 0
	s_barrier
	ds_read_b128 v[136:139], v135
	ds_read_b128 v[218:221], v135 offset:1024
	ds_read_b128 v[222:225], v135 offset:2048
	ds_read_b128 v[226:229], v135 offset:3072
	s_barrier
	s_waitcnt lgkmcnt(0)
	s_setprio 1
	s_waitcnt lgkmcnt(0)
	v_mfma_f32_16x16x32_bf16 v[92:95], v[136:139], v[156:159], v[92:95]
	v_mfma_f32_16x16x32_bf16 v[88:91], v[222:225], v[156:159], v[88:91]
	v_mfma_f32_16x16x32_bf16 v[84:87], v[136:139], v[194:197], v[84:87]
	v_mfma_f32_16x16x32_bf16 v[80:83], v[222:225], v[194:197], v[80:83]
	v_mfma_f32_16x16x32_bf16 v[76:79], v[136:139], v[202:205], v[76:79]
	v_mfma_f32_16x16x32_bf16 v[72:75], v[222:225], v[202:205], v[72:75]
	v_mfma_f32_16x16x32_bf16 v[68:71], v[136:139], v[210:213], v[68:71]
	v_mfma_f32_16x16x32_bf16 v[64:67], v[222:225], v[210:213], v[64:67]
	v_mfma_f32_16x16x32_bf16 v[156:159], v[218:221], v[160:163], v[92:95]
	v_mfma_f32_16x16x32_bf16 v[160:163], v[226:229], v[160:163], v[88:91]
	v_mfma_f32_16x16x32_bf16 v[194:197], v[218:221], v[198:201], v[84:87]
	v_mfma_f32_16x16x32_bf16 v[198:201], v[226:229], v[198:201], v[80:83]
	v_mfma_f32_16x16x32_bf16 v[202:205], v[218:221], v[206:209], v[76:79]
	v_mfma_f32_16x16x32_bf16 v[206:209], v[226:229], v[206:209], v[72:75]
	v_mfma_f32_16x16x32_bf16 v[210:213], v[218:221], v[214:217], v[68:71]
	v_mfma_f32_16x16x32_bf16 v[214:217], v[226:229], v[214:217], v[64:67]
	s_setprio 0
	s_barrier
	s_nop 0
	ds_read_b128 v[64:67], v192 offset:16384
	ds_read_b128 v[68:71], v192 offset:17408
	ds_read_b128 v[72:75], v191 offset:16384
	ds_read_b128 v[76:79], v191 offset:17408
	ds_read_b128 v[80:83], v190 offset:16384
	ds_read_b128 v[84:87], v190 offset:17408
	ds_read_b128 v[88:91], v189 offset:16384
	ds_read_b128 v[92:95], v189 offset:17408
	s_waitcnt vmcnt(4)
	s_barrier
	s_waitcnt lgkmcnt(0)
	s_setprio 1
	s_waitcnt lgkmcnt(0)
	v_mfma_f32_16x16x32_bf16 v[60:63], v[140:143], v[64:67], v[60:63]
	v_mfma_f32_16x16x32_bf16 v[56:59], v[148:151], v[64:67], v[56:59]
	v_mfma_f32_16x16x32_bf16 v[52:55], v[140:143], v[72:75], v[52:55]
	v_mfma_f32_16x16x32_bf16 v[48:51], v[148:151], v[72:75], v[48:51]
	v_mfma_f32_16x16x32_bf16 v[230:233], v[140:143], v[80:83], v[44:47]
	v_mfma_f32_16x16x32_bf16 v[234:237], v[148:151], v[80:83], v[40:43]
	v_mfma_f32_16x16x32_bf16 v[140:143], v[140:143], v[88:91], v[36:39]
	v_mfma_f32_16x16x32_bf16 v[148:151], v[148:151], v[88:91], v[32:35]
	v_mfma_f32_16x16x32_bf16 v[32:35], v[144:147], v[68:71], v[60:63]
	v_mfma_f32_16x16x32_bf16 v[36:39], v[152:155], v[68:71], v[56:59]
	v_mfma_f32_16x16x32_bf16 v[40:43], v[144:147], v[76:79], v[52:55]
	v_mfma_f32_16x16x32_bf16 v[44:47], v[152:155], v[76:79], v[48:51]
	v_mfma_f32_16x16x32_bf16 v[48:51], v[144:147], v[84:87], v[230:233]
	v_mfma_f32_16x16x32_bf16 v[52:55], v[152:155], v[84:87], v[234:237]
	v_mfma_f32_16x16x32_bf16 v[56:59], v[144:147], v[92:95], v[140:143]
	v_mfma_f32_16x16x32_bf16 v[60:63], v[152:155], v[92:95], v[148:151]
	s_setprio 0
	s_setprio 1
	v_mfma_f32_16x16x32_bf16 v[28:31], v[136:139], v[64:67], v[28:31]
	v_mfma_f32_16x16x32_bf16 v[24:27], v[222:225], v[64:67], v[24:27]
	v_mfma_f32_16x16x32_bf16 v[20:23], v[136:139], v[72:75], v[20:23]
	v_mfma_f32_16x16x32_bf16 v[64:67], v[222:225], v[72:75], v[16:19]
	v_mfma_f32_16x16x32_bf16 v[12:15], v[136:139], v[80:83], v[12:15]
	v_mfma_f32_16x16x32_bf16 v[8:11], v[222:225], v[80:83], v[8:11]
	v_mfma_f32_16x16x32_bf16 v[72:75], v[136:139], v[88:91], v[4:7]
	v_mfma_f32_16x16x32_bf16 v[80:83], v[222:225], v[88:91], v[0:3]
	v_mfma_f32_16x16x32_bf16 v[0:3], v[218:221], v[68:71], v[28:31]
	v_mfma_f32_16x16x32_bf16 v[4:7], v[226:229], v[68:71], v[24:27]
	v_mfma_f32_16x16x32_bf16 v[16:19], v[218:221], v[76:79], v[20:23]
	v_mfma_f32_16x16x32_bf16 v[20:23], v[226:229], v[76:79], v[64:67]
	v_mfma_f32_16x16x32_bf16 v[64:67], v[218:221], v[84:87], v[12:15]
	v_mfma_f32_16x16x32_bf16 v[68:71], v[226:229], v[84:87], v[8:11]
	v_mfma_f32_16x16x32_bf16 v[72:75], v[218:221], v[92:95], v[72:75]
	v_mfma_f32_16x16x32_bf16 v[76:79], v[226:229], v[92:95], v[80:83]
	s_setprio 0
	s_barrier
	ds_read_b128 v[12:15], v130
	ds_read_b128 v[8:11], v130 offset:1024
	ds_read_b128 v[24:27], v130 offset:2048
	ds_read_b128 v[80:83], v130 offset:3072
	ds_read_b128 v[140:143], v192 offset:32768
	ds_read_b128 v[148:151], v192 offset:33792
	ds_read_b128 v[218:221], v191 offset:32768
	ds_read_b128 v[222:225], v191 offset:33792
	ds_read_b128 v[226:229], v190 offset:32768
	ds_read_b128 v[230:233], v190 offset:33792
	ds_read_b128 v[234:237], v189 offset:32768
	ds_read_b128 v[238:241], v189 offset:33792
	s_waitcnt vmcnt(2)
	s_barrier
	s_waitcnt lgkmcnt(0)
	s_setprio 1
	s_waitcnt lgkmcnt(0)
	v_mfma_f32_16x16x32_bf16 v[28:31], v[12:15], v[140:143], v[124:127]
	v_mfma_f32_16x16x32_bf16 v[84:87], v[24:27], v[140:143], v[120:123]
	v_mfma_f32_16x16x32_bf16 v[88:91], v[12:15], v[218:221], v[116:119]
	v_mfma_f32_16x16x32_bf16 v[92:95], v[24:27], v[218:221], v[112:115]
	v_mfma_f32_16x16x32_bf16 v[108:111], v[12:15], v[226:229], v[108:111]
	v_mfma_f32_16x16x32_bf16 v[104:107], v[24:27], v[226:229], v[104:107]
	v_mfma_f32_16x16x32_bf16 v[100:103], v[12:15], v[234:237], v[100:103]
	v_mfma_f32_16x16x32_bf16 v[96:99], v[24:27], v[234:237], v[96:99]
	v_mfma_f32_16x16x32_bf16 v[152:155], v[8:11], v[148:151], v[28:31]
	v_mfma_f32_16x16x32_bf16 v[144:147], v[80:83], v[148:151], v[84:87]
	v_mfma_f32_16x16x32_bf16 v[136:139], v[8:11], v[222:225], v[88:91]
	v_mfma_f32_16x16x32_bf16 v[128:131], v[80:83], v[222:225], v[92:95]
	v_mfma_f32_16x16x32_bf16 v[120:123], v[8:11], v[230:233], v[108:111]
	v_mfma_f32_16x16x32_bf16 v[112:115], v[80:83], v[230:233], v[104:107]
	v_mfma_f32_16x16x32_bf16 v[104:107], v[8:11], v[238:241], v[100:103]
	v_mfma_f32_16x16x32_bf16 v[28:31], v[80:83], v[238:241], v[96:99]
	s_setprio 0
	s_barrier
	ds_read_b128 v[92:95], v132
	ds_read_b128 v[84:87], v132 offset:1024
	ds_read_b128 v[96:99], v132 offset:2048
	ds_read_b128 v[88:91], v132 offset:3072
	s_waitcnt vmcnt(0)
	s_barrier
	s_waitcnt lgkmcnt(0)
	s_setprio 1
	s_waitcnt lgkmcnt(0)
	v_mfma_f32_16x16x32_bf16 v[100:103], v[92:95], v[140:143], v[156:159]
	v_mfma_f32_16x16x32_bf16 v[108:111], v[96:99], v[140:143], v[160:163]
	v_mfma_f32_16x16x32_bf16 v[116:119], v[92:95], v[218:221], v[194:197]
	v_mfma_f32_16x16x32_bf16 v[124:127], v[96:99], v[218:221], v[198:201]
	v_mfma_f32_16x16x32_bf16 v[160:163], v[92:95], v[226:229], v[202:205]
	v_mfma_f32_16x16x32_bf16 v[194:197], v[96:99], v[226:229], v[206:209]
	v_mfma_f32_16x16x32_bf16 v[198:201], v[92:95], v[234:237], v[210:213]
	v_mfma_f32_16x16x32_bf16 v[202:205], v[96:99], v[234:237], v[214:217]
	v_mfma_f32_16x16x32_bf16 v[156:159], v[84:87], v[148:151], v[100:103]
	v_mfma_f32_16x16x32_bf16 v[148:151], v[88:91], v[148:151], v[108:111]
	v_mfma_f32_16x16x32_bf16 v[140:143], v[84:87], v[222:225], v[116:119]
	v_mfma_f32_16x16x32_bf16 v[132:135], v[88:91], v[222:225], v[124:127]
	v_mfma_f32_16x16x32_bf16 v[124:127], v[84:87], v[230:233], v[160:163]
	v_mfma_f32_16x16x32_bf16 v[116:119], v[88:91], v[230:233], v[194:197]
	v_mfma_f32_16x16x32_bf16 v[108:111], v[84:87], v[238:241], v[198:201]
	v_mfma_f32_16x16x32_bf16 v[100:103], v[88:91], v[238:241], v[202:205]
	s_setprio 0
	s_lshl_b64 s[66:67], s[64:65], 2
	s_barrier
	v_mbcnt_lo_u32_b32 v162, -1, 0
	v_mbcnt_hi_u32_b32 v162, -1, v162
	s_add_u32 s66, s87, s66
	v_add_u32_e32 v160, s76, v162
	s_addc_u32 s67, s88, s67
	v_and_b32_e32 v164, 0x100, v160
	v_and_b32_e32 v162, 15, v162
	v_lshl_add_u64 v[160:161], s[66:67], 0, v[164:165]
	v_lshlrev_b32_e32 v164, 2, v162
	v_lshl_add_u64 v[160:161], v[160:161], 0, v[164:165]
	global_load_dword v178, v[160:161], off
	global_load_dword v176, v[160:161], off offset:64
	global_load_dword v174, v[160:161], off offset:128
	global_load_dword v164, v[160:161], off offset:192
	global_load_dword v172, v[160:161], off offset:512
	global_load_dword v170, v[160:161], off offset:576
	global_load_dword v168, v[160:161], off offset:640
	global_load_dword v166, v[160:161], off offset:704
	v_mbcnt_lo_u32_b32 v194, -1, 0
	v_mbcnt_hi_u32_b32 v194, -1, v194
	s_mov_b64 s[66:67], -1
	v_add_u32_e32 v160, s76, v194
	v_bfe_u32 v161, v160, 8, 1
	v_ashrrev_i32_e32 v196, 6, v160
	v_bfe_u32 v160, v194, 4, 2
	v_and_b32_e32 v198, 3, v196
	v_and_b32_e32 v195, 15, v194
	s_cmp_gt_i32 s74, 1
	v_lshlrev_b32_e32 v193, 6, v161
	v_lshlrev_b32_e32 v197, 4, v160
	s_cbranch_scc0 .LBB0_113
	v_lshlrev_b32_e32 v161, 6, v198
	v_or3_b32 v160, v193, v195, s64
	v_or3_b32 v161, v161, v197, s62
	v_lshl_add_u32 v199, v160, 12, v161
	s_waitcnt vmcnt(0)
	v_mul_f32_e32 v160, v178, v178
	v_pk_mul_f32 v[200:201], v[152:153], v[160:161] op_sel_hi:[1,0]
	v_pk_mul_f32 v[162:163], v[154:155], v[160:161] op_sel_hi:[1,0]
	v_pk_mul_f32 v[202:203], v[158:159], v[160:161] op_sel_hi:[1,0]
	v_pk_mul_f32 v[204:205], v[156:157], v[160:161] op_sel_hi:[1,0]
	v_mul_f32_e32 v160, v144, v200
	v_mul_f32_e32 v161, v145, v201
	v_cvt_pk_bf16_f32 v160, v160, v161
	v_mul_f32_e32 v161, v146, v162
	v_mul_f32_e32 v162, v147, v163
	v_cvt_pk_bf16_f32 v161, v161, v162
	v_mul_f32_e32 v162, v148, v204
	v_mul_f32_e32 v163, v149, v205
	v_cvt_pk_bf16_f32 v162, v162, v163
	v_mul_f32_e32 v163, v150, v202
	v_mul_f32_e32 v200, v151, v203
	v_cvt_pk_bf16_f32 v163, v163, v200
	global_store_dwordx4 v199, v[160:163], s[6:7]
	v_add_u32_e32 v206, 0x10000, v199
	s_mov_b64 s[66:67], 0
	v_mul_f32_e32 v160, v176, v176
	v_pk_mul_f32 v[200:201], v[136:137], v[160:161] op_sel_hi:[1,0]
	v_pk_mul_f32 v[162:163], v[138:139], v[160:161] op_sel_hi:[1,0]
	v_pk_mul_f32 v[202:203], v[142:143], v[160:161] op_sel_hi:[1,0]
	v_pk_mul_f32 v[204:205], v[140:141], v[160:161] op_sel_hi:[1,0]
	v_mul_f32_e32 v160, v128, v200
	v_mul_f32_e32 v161, v129, v201
	v_cvt_pk_bf16_f32 v160, v160, v161
	v_mul_f32_e32 v161, v130, v162
	v_mul_f32_e32 v162, v131, v163
	v_cvt_pk_bf16_f32 v161, v161, v162
	v_mul_f32_e32 v162, v132, v204
	v_mul_f32_e32 v163, v133, v205
	v_cvt_pk_bf16_f32 v162, v162, v163
	v_mul_f32_e32 v163, v134, v202
	v_mul_f32_e32 v200, v135, v203
	v_cvt_pk_bf16_f32 v163, v163, v200
	global_store_dwordx4 v206, v[160:163], s[6:7]
	v_add_u32_e32 v206, 0x20000, v199
	v_add_u32_e32 v199, 0x30000, v199
	v_mul_f32_e32 v160, v174, v174
	v_pk_mul_f32 v[200:201], v[120:121], v[160:161] op_sel_hi:[1,0]
	v_pk_mul_f32 v[162:163], v[122:123], v[160:161] op_sel_hi:[1,0]
	v_pk_mul_f32 v[202:203], v[126:127], v[160:161] op_sel_hi:[1,0]
	v_pk_mul_f32 v[204:205], v[124:125], v[160:161] op_sel_hi:[1,0]
	v_mul_f32_e32 v160, v112, v200
	v_mul_f32_e32 v161, v113, v201
	v_cvt_pk_bf16_f32 v160, v160, v161
	v_mul_f32_e32 v161, v114, v162
	v_mul_f32_e32 v162, v115, v163
	v_cvt_pk_bf16_f32 v161, v161, v162
	v_mul_f32_e32 v162, v116, v204
	v_mul_f32_e32 v163, v117, v205
	v_cvt_pk_bf16_f32 v162, v162, v163
	v_mul_f32_e32 v163, v118, v202
	v_mul_f32_e32 v200, v119, v203
	v_cvt_pk_bf16_f32 v163, v163, v200
	global_store_dwordx4 v206, v[160:163], s[6:7]
	s_nop 1
	v_mul_f32_e32 v160, v164, v164
	v_pk_mul_f32 v[200:201], v[104:105], v[160:161] op_sel_hi:[1,0]
	v_pk_mul_f32 v[162:163], v[106:107], v[160:161] op_sel_hi:[1,0]
	v_pk_mul_f32 v[202:203], v[110:111], v[160:161] op_sel_hi:[1,0]
	v_pk_mul_f32 v[204:205], v[108:109], v[160:161] op_sel_hi:[1,0]
	v_mul_f32_e32 v160, v28, v200
	v_mul_f32_e32 v161, v29, v201
	v_cvt_pk_bf16_f32 v160, v160, v161
	v_mul_f32_e32 v161, v30, v162
	v_mul_f32_e32 v162, v31, v163
	v_cvt_pk_bf16_f32 v161, v161, v162
	v_mul_f32_e32 v162, v100, v204
	v_mul_f32_e32 v163, v101, v205
	v_cvt_pk_bf16_f32 v162, v162, v163
	v_mul_f32_e32 v163, v102, v202
	v_mul_f32_e32 v200, v103, v203
	v_cvt_pk_bf16_f32 v163, v163, v200

.LBB0_178:
	ds_read_b128 v[164:167], v162
	ds_read_b128 v[168:171], v162 offset:1024
	ds_read_b128 v[172:175], v162 offset:2048
	ds_read_b128 v[176:179], v162 offset:3072
	ds_read_b128 v[180:183], v153
	ds_read_b128 v[184:187], v153 offset:1024
	ds_read_b128 v[188:191], v152
	ds_read_b128 v[192:195], v152 offset:1024
	ds_read_b128 v[196:199], v151
	ds_read_b128 v[200:203], v151 offset:1024
	ds_read_b128 v[204:207], v150
	ds_read_b128 v[208:211], v150 offset:1024
	s_waitcnt lgkmcnt(8)
	s_waitcnt vmcnt(10)
	s_barrier
	s_waitcnt lgkmcnt(0)
	s_waitcnt lgkmcnt(0)
	v_mfma_f32_16x16x32_bf16 v[124:127], v[164:167], v[180:183], v[124:127]
	v_mfma_f32_16x16x32_bf16 v[120:123], v[172:175], v[180:183], v[120:123]
	v_mfma_f32_16x16x32_bf16 v[116:119], v[164:167], v[188:191], v[116:119]
	v_mfma_f32_16x16x32_bf16 v[112:115], v[172:175], v[188:191], v[112:115]
	v_mfma_f32_16x16x32_bf16 v[108:111], v[164:167], v[196:199], v[108:111]
	v_mfma_f32_16x16x32_bf16 v[104:107], v[172:175], v[196:199], v[104:107]
	v_mfma_f32_16x16x32_bf16 v[100:103], v[164:167], v[204:207], v[100:103]
	v_mfma_f32_16x16x32_bf16 v[96:99], v[172:175], v[204:207], v[96:99]
	v_mfma_f32_16x16x32_bf16 v[124:127], v[168:171], v[184:187], v[124:127]
	v_mfma_f32_16x16x32_bf16 v[120:123], v[176:179], v[184:187], v[120:123]
	v_mfma_f32_16x16x32_bf16 v[116:119], v[168:171], v[192:195], v[116:119]
	v_mfma_f32_16x16x32_bf16 v[112:115], v[176:179], v[192:195], v[112:115]
	v_mfma_f32_16x16x32_bf16 v[108:111], v[168:171], v[200:203], v[108:111]
	v_mfma_f32_16x16x32_bf16 v[104:107], v[176:179], v[200:203], v[104:107]
	v_mfma_f32_16x16x32_bf16 v[100:103], v[168:171], v[208:211], v[100:103]
	v_mfma_f32_16x16x32_bf16 v[96:99], v[176:179], v[208:211], v[96:99]
	s_barrier
	v_lshl_add_u64 v[230:231], s[50:51], 0, v[130:131]
	s_mov_b64 s[66:67], 0x1880000
	v_readfirstlane_b32 s65, v149
	v_lshl_add_u64 v[232:233], v[230:231], 0, s[66:67]
	s_mov_b32 m0, s65
	s_mov_b64 s[66:67], 0x1881000
	v_readfirstlane_b32 s65, v148
	ds_read_b128 v[212:215], v159
	ds_read_b128 v[216:219], v159 offset:1024
	ds_read_b128 v[220:223], v159 offset:2048
	ds_read_b128 v[224:227], v159 offset:3072
	global_load_lds_dwordx4 v[232:233], off
	v_lshl_add_u64 v[232:233], v[230:231], 0, s[66:67]
	s_mov_b32 m0, s65
	s_nop 0
	global_load_lds_dwordx4 v[232:233], off
	s_mov_b64 s[66:67], 0xe000100
	v_readfirstlane_b32 s65, v135
	v_lshl_add_u64 v[232:233], v[228:229], 0, s[66:67]
	s_mov_b32 m0, s65
	s_mov_b64 s[66:67], 0xe040100
	v_readfirstlane_b32 s65, v147
	global_load_lds_dwordx4 v[232:233], off
	v_lshl_add_u64 v[232:233], v[228:229], 0, s[66:67]
	s_mov_b32 m0, s65
	s_nop 0
	global_load_lds_dwordx4 v[232:233], off
	s_waitcnt vmcnt(12)
	s_barrier
	s_waitcnt lgkmcnt(0)
	s_waitcnt lgkmcnt(0)
	v_mfma_f32_16x16x32_bf16 v[92:95], v[212:215], v[180:183], v[92:95]
	v_mfma_f32_16x16x32_bf16 v[88:91], v[220:223], v[180:183], v[88:91]
	v_mfma_f32_16x16x32_bf16 v[84:87], v[212:215], v[188:191], v[84:87]
	v_mfma_f32_16x16x32_bf16 v[80:83], v[220:223], v[188:191], v[80:83]
	v_mfma_f32_16x16x32_bf16 v[76:79], v[212:215], v[196:199], v[76:79]
	v_mfma_f32_16x16x32_bf16 v[72:75], v[220:223], v[196:199], v[72:75]
	v_mfma_f32_16x16x32_bf16 v[68:71], v[212:215], v[204:207], v[68:71]
	v_mfma_f32_16x16x32_bf16 v[64:67], v[220:223], v[204:207], v[64:67]
	v_mfma_f32_16x16x32_bf16 v[92:95], v[216:219], v[184:187], v[92:95]
	v_mfma_f32_16x16x32_bf16 v[88:91], v[224:227], v[184:187], v[88:91]
	v_mfma_f32_16x16x32_bf16 v[84:87], v[216:219], v[192:195], v[84:87]
	v_mfma_f32_16x16x32_bf16 v[80:83], v[224:227], v[192:195], v[80:83]
	v_mfma_f32_16x16x32_bf16 v[76:79], v[216:219], v[200:203], v[76:79]
	v_mfma_f32_16x16x32_bf16 v[72:75], v[224:227], v[200:203], v[72:75]
	v_mfma_f32_16x16x32_bf16 v[68:71], v[216:219], v[208:211], v[68:71]
	v_mfma_f32_16x16x32_bf16 v[64:67], v[224:227], v[208:211], v[64:67]
	s_barrier
	ds_read_b128 v[180:183], v153 offset:16384
	ds_read_b128 v[184:187], v153 offset:17408
	ds_read_b128 v[188:191], v152 offset:16384
	ds_read_b128 v[192:195], v152 offset:17408
	ds_read_b128 v[196:199], v151 offset:16384
	ds_read_b128 v[200:203], v151 offset:17408
	ds_read_b128 v[204:207], v150 offset:16384
	ds_read_b128 v[208:211], v150 offset:17408
	s_mov_b64 s[66:67], 0x1882000
	v_readfirstlane_b32 s65, v146
	v_lshl_add_u64 v[232:233], v[230:231], 0, s[66:67]
	s_mov_b32 m0, s65
	s_mov_b64 s[66:67], 0x1883000
	v_readfirstlane_b32 s65, v145
	global_load_lds_dwordx4 v[232:233], off
	v_lshl_add_u64 v[232:233], v[230:231], 0, s[66:67]
	s_mov_b32 m0, s65
	s_nop 0
	global_load_lds_dwordx4 v[232:233], off
	s_barrier
	s_waitcnt lgkmcnt(0)
	s_waitcnt lgkmcnt(0)
	v_mfma_f32_16x16x32_bf16 v[60:63], v[164:167], v[180:183], v[60:63]
	v_mfma_f32_16x16x32_bf16 v[56:59], v[172:175], v[180:183], v[56:59]
	v_mfma_f32_16x16x32_bf16 v[52:55], v[164:167], v[188:191], v[52:55]
	v_mfma_f32_16x16x32_bf16 v[48:51], v[172:175], v[188:191], v[48:51]
	v_mfma_f32_16x16x32_bf16 v[44:47], v[164:167], v[196:199], v[44:47]
	v_mfma_f32_16x16x32_bf16 v[40:43], v[172:175], v[196:199], v[40:43]
	v_mfma_f32_16x16x32_bf16 v[36:39], v[164:167], v[204:207], v[36:39]
	v_mfma_f32_16x16x32_bf16 v[32:35], v[172:175], v[204:207], v[32:35]
	v_mfma_f32_16x16x32_bf16 v[60:63], v[168:171], v[184:187], v[60:63]
	v_mfma_f32_16x16x32_bf16 v[56:59], v[176:179], v[184:187], v[56:59]
	v_mfma_f32_16x16x32_bf16 v[52:55], v[168:171], v[192:195], v[52:55]
	v_mfma_f32_16x16x32_bf16 v[48:51], v[176:179], v[192:195], v[48:51]
	v_mfma_f32_16x16x32_bf16 v[44:47], v[168:171], v[200:203], v[44:47]
	v_mfma_f32_16x16x32_bf16 v[40:43], v[176:179], v[200:203], v[40:43]
	v_mfma_f32_16x16x32_bf16 v[36:39], v[168:171], v[208:211], v[36:39]
	v_mfma_f32_16x16x32_bf16 v[32:35], v[176:179], v[208:211], v[32:35]
	s_barrier
	v_readfirstlane_b32 s65, v144
	v_lshl_add_u64 v[166:167], v[228:229], 0, s[26:27]
	s_mov_b32 m0, s65
	v_readfirstlane_b32 s65, v143
	global_load_lds_dwordx4 v[166:167], off
	v_lshl_add_u64 v[166:167], v[228:229], 0, s[28:29]
	s_mov_b32 m0, s65
	s_nop 0
	global_load_lds_dwordx4 v[166:167], off
	s_waitcnt vmcnt(12)
	s_barrier
	v_mfma_f32_16x16x32_bf16 v[28:31], v[212:215], v[180:183], v[28:31]
	v_mfma_f32_16x16x32_bf16 v[24:27], v[220:223], v[180:183], v[24:27]
	v_mfma_f32_16x16x32_bf16 v[20:23], v[212:215], v[188:191], v[20:23]
	v_mfma_f32_16x16x32_bf16 v[16:19], v[220:223], v[188:191], v[16:19]
	v_mfma_f32_16x16x32_bf16 v[12:15], v[212:215], v[196:199], v[12:15]
	v_mfma_f32_16x16x32_bf16 v[8:11], v[220:223], v[196:199], v[8:11]
	v_mfma_f32_16x16x32_bf16 v[4:7], v[212:215], v[204:207], v[4:7]
	v_mfma_f32_16x16x32_bf16 v[0:3], v[220:223], v[204:207], v[0:3]
	v_mfma_f32_16x16x32_bf16 v[28:31], v[216:219], v[184:187], v[28:31]
	v_mfma_f32_16x16x32_bf16 v[24:27], v[224:227], v[184:187], v[24:27]
	v_mfma_f32_16x16x32_bf16 v[20:23], v[216:219], v[192:195], v[20:23]
	v_mfma_f32_16x16x32_bf16 v[16:19], v[224:227], v[192:195], v[16:19]
	v_mfma_f32_16x16x32_bf16 v[12:15], v[216:219], v[200:203], v[12:15]
	v_mfma_f32_16x16x32_bf16 v[8:11], v[224:227], v[200:203], v[8:11]
	v_mfma_f32_16x16x32_bf16 v[4:7], v[216:219], v[208:211], v[4:7]
	v_mfma_f32_16x16x32_bf16 v[0:3], v[224:227], v[208:211], v[0:3]
	s_barrier
	ds_read_b128 v[164:167], v155
	ds_read_b128 v[168:171], v155 offset:1024
	ds_read_b128 v[172:175], v155 offset:2048
	ds_read_b128 v[176:179], v155 offset:3072
	ds_read_b128 v[180:183], v153 offset:32768
	ds_read_b128 v[184:187], v153 offset:33792
	ds_read_b128 v[188:191], v152 offset:32768
	ds_read_b128 v[192:195], v152 offset:33792
	ds_read_b128 v[196:199], v151 offset:32768
	ds_read_b128 v[200:203], v151 offset:33792
	ds_read_b128 v[204:207], v150 offset:32768
	ds_read_b128 v[208:211], v150 offset:33792
	s_waitcnt lgkmcnt(8)
	s_waitcnt vmcnt(10)
	s_barrier
	s_waitcnt lgkmcnt(0)
	s_waitcnt lgkmcnt(0)
	v_mfma_f32_16x16x32_bf16 v[124:127], v[164:167], v[180:183], v[124:127]
	v_mfma_f32_16x16x32_bf16 v[120:123], v[172:175], v[180:183], v[120:123]
	v_mfma_f32_16x16x32_bf16 v[116:119], v[164:167], v[188:191], v[116:119]
	v_mfma_f32_16x16x32_bf16 v[112:115], v[172:175], v[188:191], v[112:115]
	v_mfma_f32_16x16x32_bf16 v[108:111], v[164:167], v[196:199], v[108:111]
	v_mfma_f32_16x16x32_bf16 v[104:107], v[172:175], v[196:199], v[104:107]
	v_mfma_f32_16x16x32_bf16 v[100:103], v[164:167], v[204:207], v[100:103]
	v_mfma_f32_16x16x32_bf16 v[96:99], v[172:175], v[204:207], v[96:99]
	v_mfma_f32_16x16x32_bf16 v[124:127], v[168:171], v[184:187], v[124:127]
	v_mfma_f32_16x16x32_bf16 v[120:123], v[176:179], v[184:187], v[120:123]
	v_mfma_f32_16x16x32_bf16 v[116:119], v[168:171], v[192:195], v[116:119]
	v_mfma_f32_16x16x32_bf16 v[112:115], v[176:179], v[192:195], v[112:115]
	v_mfma_f32_16x16x32_bf16 v[108:111], v[168:171], v[200:203], v[108:111]
	v_mfma_f32_16x16x32_bf16 v[104:107], v[176:179], v[200:203], v[104:107]
	v_mfma_f32_16x16x32_bf16 v[100:103], v[168:171], v[208:211], v[100:103]
	v_mfma_f32_16x16x32_bf16 v[96:99], v[176:179], v[208:211], v[96:99]
	s_barrier
	v_readfirstlane_b32 s65, v142
	v_lshl_add_u64 v[232:233], v[230:231], 0, s[30:31]
	s_mov_b32 m0, s65
	v_readfirstlane_b32 s65, v141
	ds_read_b128 v[212:215], v154
	ds_read_b128 v[216:219], v154 offset:1024
	ds_read_b128 v[220:223], v154 offset:2048
	ds_read_b128 v[224:227], v154 offset:3072
	global_load_lds_dwordx4 v[232:233], off
	v_lshl_add_u64 v[232:233], v[230:231], 0, s[34:35]
	s_mov_b32 m0, s65
	s_nop 0
	global_load_lds_dwordx4 v[232:233], off
	v_readfirstlane_b32 s65, v140
	v_lshl_add_u64 v[232:233], v[228:229], 0, s[40:41]
	s_mov_b32 m0, s65
	v_readfirstlane_b32 s65, v139
	global_load_lds_dwordx4 v[232:233], off
	v_lshl_add_u64 v[228:229], v[228:229], 0, s[44:45]
	s_mov_b32 m0, s65
	s_nop 0
	global_load_lds_dwordx4 v[228:229], off
	s_waitcnt vmcnt(12)
	s_barrier
	s_waitcnt lgkmcnt(0)
	s_waitcnt lgkmcnt(0)
	v_mfma_f32_16x16x32_bf16 v[92:95], v[212:215], v[180:183], v[92:95]
	v_mfma_f32_16x16x32_bf16 v[88:91], v[220:223], v[180:183], v[88:91]
	v_mfma_f32_16x16x32_bf16 v[84:87], v[212:215], v[188:191], v[84:87]
	v_mfma_f32_16x16x32_bf16 v[80:83], v[220:223], v[188:191], v[80:83]
	v_mfma_f32_16x16x32_bf16 v[76:79], v[212:215], v[196:199], v[76:79]
	v_mfma_f32_16x16x32_bf16 v[72:75], v[220:223], v[196:199], v[72:75]
	v_mfma_f32_16x16x32_bf16 v[68:71], v[212:215], v[204:207], v[68:71]
	v_mfma_f32_16x16x32_bf16 v[64:67], v[220:223], v[204:207], v[64:67]
	v_mfma_f32_16x16x32_bf16 v[92:95], v[216:219], v[184:187], v[92:95]
	v_mfma_f32_16x16x32_bf16 v[88:91], v[224:227], v[184:187], v[88:91]
	v_mfma_f32_16x16x32_bf16 v[84:87], v[216:219], v[192:195], v[84:87]
	v_mfma_f32_16x16x32_bf16 v[80:83], v[224:227], v[192:195], v[80:83]
	v_mfma_f32_16x16x32_bf16 v[76:79], v[216:219], v[200:203], v[76:79]
	v_mfma_f32_16x16x32_bf16 v[72:75], v[224:227], v[200:203], v[72:75]
	v_mfma_f32_16x16x32_bf16 v[68:71], v[216:219], v[208:211], v[68:71]
	v_mfma_f32_16x16x32_bf16 v[64:67], v[224:227], v[208:211], v[64:67]
	s_barrier
	ds_read_b128 v[180:183], v153 offset:49152
	ds_read_b128 v[184:187], v153 offset:50176
	ds_read_b128 v[188:191], v152 offset:49152
	ds_read_b128 v[192:195], v152 offset:50176
	ds_read_b128 v[196:199], v151 offset:49152
	ds_read_b128 v[200:203], v151 offset:50176
	ds_read_b128 v[204:207], v150 offset:49152
	ds_read_b128 v[208:211], v150 offset:50176
	v_readfirstlane_b32 s65, v138
	v_lshl_add_u64 v[232:233], v[230:231], 0, s[46:47]
	s_mov_b32 m0, s65
	v_readfirstlane_b32 s65, v137
	global_load_lds_dwordx4 v[232:233], off
	v_lshl_add_u64 v[232:233], v[230:231], 0, s[56:57]
	s_mov_b32 m0, s65
	s_nop 0
	global_load_lds_dwordx4 v[232:233], off
	s_barrier
	s_waitcnt lgkmcnt(0)
	s_waitcnt lgkmcnt(0)
	v_mfma_f32_16x16x32_bf16 v[60:63], v[164:167], v[180:183], v[60:63]
	v_mfma_f32_16x16x32_bf16 v[56:59], v[172:175], v[180:183], v[56:59]
	v_mfma_f32_16x16x32_bf16 v[52:55], v[164:167], v[188:191], v[52:55]
	v_mfma_f32_16x16x32_bf16 v[48:51], v[172:175], v[188:191], v[48:51]
	v_mfma_f32_16x16x32_bf16 v[44:47], v[164:167], v[196:199], v[44:47]
	v_mfma_f32_16x16x32_bf16 v[40:43], v[172:175], v[196:199], v[40:43]
	v_mfma_f32_16x16x32_bf16 v[36:39], v[164:167], v[204:207], v[36:39]
	v_mfma_f32_16x16x32_bf16 v[32:35], v[172:175], v[204:207], v[32:35]
	v_mfma_f32_16x16x32_bf16 v[60:63], v[168:171], v[184:187], v[60:63]
	v_mfma_f32_16x16x32_bf16 v[56:59], v[176:179], v[184:187], v[56:59]
	v_mfma_f32_16x16x32_bf16 v[52:55], v[168:171], v[192:195], v[52:55]
	v_mfma_f32_16x16x32_bf16 v[48:51], v[176:179], v[192:195], v[48:51]
	v_mfma_f32_16x16x32_bf16 v[44:47], v[168:171], v[200:203], v[44:47]
	v_mfma_f32_16x16x32_bf16 v[40:43], v[176:179], v[200:203], v[40:43]
	v_mfma_f32_16x16x32_bf16 v[36:39], v[168:171], v[208:211], v[36:39]
	v_mfma_f32_16x16x32_bf16 v[32:35], v[176:179], v[208:211], v[32:35]
	s_barrier
	v_lshl_add_u64 v[132:133], v[132:133], 0, s[58:59]
	v_lshl_add_u64 v[228:229], s[50:51], 0, v[132:133]
	s_mov_b64 s[66:67], 0xe080080
	v_readfirstlane_b32 s65, v161
	v_lshl_add_u64 v[166:167], v[228:229], 0, s[66:67]
	s_mov_b32 m0, s65
	s_mov_b64 s[66:67], 0xe0c0080
	v_readfirstlane_b32 s65, v160
	global_load_lds_dwordx4 v[166:167], off
	v_lshl_add_u64 v[166:167], v[228:229], 0, s[66:67]
	s_mov_b32 m0, s65
	s_nop 0
	global_load_lds_dwordx4 v[166:167], off
	s_waitcnt vmcnt(12)
	s_barrier
	v_mfma_f32_16x16x32_bf16 v[28:31], v[212:215], v[180:183], v[28:31]
	v_mfma_f32_16x16x32_bf16 v[24:27], v[220:223], v[180:183], v[24:27]
	v_mfma_f32_16x16x32_bf16 v[20:23], v[212:215], v[188:191], v[20:23]
	v_mfma_f32_16x16x32_bf16 v[16:19], v[220:223], v[188:191], v[16:19]
	v_mfma_f32_16x16x32_bf16 v[12:15], v[212:215], v[196:199], v[12:15]
	v_mfma_f32_16x16x32_bf16 v[8:11], v[220:223], v[196:199], v[8:11]
	v_mfma_f32_16x16x32_bf16 v[4:7], v[212:215], v[204:207], v[4:7]
	v_mfma_f32_16x16x32_bf16 v[0:3], v[220:223], v[204:207], v[0:3]
	v_mfma_f32_16x16x32_bf16 v[28:31], v[216:219], v[184:187], v[28:31]
	v_mfma_f32_16x16x32_bf16 v[24:27], v[224:227], v[184:187], v[24:27]
	v_mfma_f32_16x16x32_bf16 v[20:23], v[216:219], v[192:195], v[20:23]
	v_mfma_f32_16x16x32_bf16 v[16:19], v[224:227], v[192:195], v[16:19]
	v_mfma_f32_16x16x32_bf16 v[12:15], v[216:219], v[200:203], v[12:15]
	v_mfma_f32_16x16x32_bf16 v[8:11], v[224:227], v[200:203], v[8:11]
	v_mfma_f32_16x16x32_bf16 v[4:7], v[216:219], v[208:211], v[4:7]
	v_mfma_f32_16x16x32_bf16 v[0:3], v[224:227], v[208:211], v[0:3]
	s_add_i32 s24, s24, 2
	v_lshl_add_u64 v[130:131], v[130:131], 0, s[10:11]
	s_cmp_lt_u32 s24, 28
	s_barrier
	s_cbranch_scc1 .LBB0_178
	s_lshl_b32 s24, s85, 5
	s_lshl_b32 s65, s85, 8
	s_and_b32 s24, s24, 0x1800
	s_and_b32 s65, s65, 0x700
	s_or_b32 s24, s65, s24
	v_lshlrev_b32_e32 v128, 3, v156
	v_lshlrev_b32_e32 v130, 5, v156
	v_and_b32_e32 v128, 0xffff0, v128
	v_and_b32_e32 v130, 32, v130
	s_lshl_b32 s65, s24, 12
	v_add_u32_e32 v130, v130, v158
	v_add_lshl_u32 v128, v157, v128, 12
	s_add_u32 s66, s68, s65
	v_lshl_add_u32 v128, v130, 1, v128
	s_addc_u32 s67, s69, 0
	v_lshl_add_u64 v[156:157], s[66:67], 0, v[128:129]
	v_readfirstlane_b32 s65, v161
	ds_read_b128 v[130:133], v162
	ds_read_b128 v[164:167], v162 offset:1024
	ds_read_b128 v[168:171], v162 offset:2048
	ds_read_b128 v[172:175], v162 offset:3072
	ds_read_b128 v[176:179], v153
	ds_read_b128 v[180:183], v153 offset:1024
	ds_read_b128 v[184:187], v152
	ds_read_b128 v[188:191], v152 offset:1024
	ds_read_b128 v[192:195], v151
	ds_read_b128 v[196:199], v151 offset:1024
	ds_read_b128 v[200:203], v150
	ds_read_b128 v[204:207], v150 offset:1024
	v_lshl_add_u64 v[162:163], v[156:157], 0, s[60:61]
	s_mov_b32 m0, s65
	v_readfirstlane_b32 s65, v160
	global_load_lds_dwordx4 v[162:163], off
	v_lshl_add_u64 v[156:157], v[156:157], 0, s[62:63]
	s_mov_b32 m0, s65
	s_nop 0
	global_load_lds_dwordx4 v[156:157], off
	s_waitcnt vmcnt(10)
	s_barrier
	s_waitcnt lgkmcnt(0)
	s_setprio 1
	s_waitcnt lgkmcnt(0)
	v_mfma_f32_16x16x32_bf16 v[124:127], v[130:133], v[176:179], v[124:127]
	v_mfma_f32_16x16x32_bf16 v[120:123], v[168:171], v[176:179], v[120:123]
	v_mfma_f32_16x16x32_bf16 v[116:119], v[130:133], v[184:187], v[116:119]
	v_mfma_f32_16x16x32_bf16 v[112:115], v[168:171], v[184:187], v[112:115]
	v_mfma_f32_16x16x32_bf16 v[108:111], v[130:133], v[192:195], v[108:111]
	v_mfma_f32_16x16x32_bf16 v[104:107], v[168:171], v[192:195], v[104:107]
	v_mfma_f32_16x16x32_bf16 v[100:103], v[130:133], v[200:203], v[100:103]
	v_mfma_f32_16x16x32_bf16 v[96:99], v[168:171], v[200:203], v[96:99]
	v_mfma_f32_16x16x32_bf16 v[124:127], v[164:167], v[180:183], v[124:127]
	v_mfma_f32_16x16x32_bf16 v[120:123], v[172:175], v[180:183], v[120:123]
	v_mfma_f32_16x16x32_bf16 v[116:119], v[164:167], v[188:191], v[116:119]
	v_mfma_f32_16x16x32_bf16 v[112:115], v[172:175], v[188:191], v[112:115]
	v_mfma_f32_16x16x32_bf16 v[108:111], v[164:167], v[196:199], v[108:111]
	v_mfma_f32_16x16x32_bf16 v[104:107], v[172:175], v[196:199], v[104:107]
	v_mfma_f32_16x16x32_bf16 v[100:103], v[164:167], v[204:207], v[100:103]
	v_mfma_f32_16x16x32_bf16 v[96:99], v[172:175], v[204:207], v[96:99]
	s_setprio 0
	s_barrier
	ds_read_b128 v[160:163], v159
	ds_read_b128 v[208:211], v159 offset:1024
	ds_read_b128 v[212:215], v159 offset:2048
	ds_read_b128 v[156:159], v159 offset:3072
	s_barrier
	s_waitcnt lgkmcnt(0)
	s_setprio 1
	s_waitcnt lgkmcnt(0)
	v_mfma_f32_16x16x32_bf16 v[92:95], v[160:163], v[176:179], v[92:95]
	v_mfma_f32_16x16x32_bf16 v[88:91], v[212:215], v[176:179], v[88:91]
	v_mfma_f32_16x16x32_bf16 v[84:87], v[160:163], v[184:187], v[84:87]
	v_mfma_f32_16x16x32_bf16 v[80:83], v[212:215], v[184:187], v[80:83]
	v_mfma_f32_16x16x32_bf16 v[76:79], v[160:163], v[192:195], v[76:79]
	v_mfma_f32_16x16x32_bf16 v[72:75], v[212:215], v[192:195], v[72:75]
	v_mfma_f32_16x16x32_bf16 v[68:71], v[160:163], v[200:203], v[68:71]
	v_mfma_f32_16x16x32_bf16 v[64:67], v[212:215], v[200:203], v[64:67]
	v_mfma_f32_16x16x32_bf16 v[176:179], v[208:211], v[180:183], v[92:95]
	v_mfma_f32_16x16x32_bf16 v[180:183], v[156:159], v[180:183], v[88:91]
	v_mfma_f32_16x16x32_bf16 v[184:187], v[208:211], v[188:191], v[84:87]
	v_mfma_f32_16x16x32_bf16 v[188:191], v[156:159], v[188:191], v[80:83]
	v_mfma_f32_16x16x32_bf16 v[192:195], v[208:211], v[196:199], v[76:79]
	v_mfma_f32_16x16x32_bf16 v[196:199], v[156:159], v[196:199], v[72:75]
	v_mfma_f32_16x16x32_bf16 v[200:203], v[208:211], v[204:207], v[68:71]
	v_mfma_f32_16x16x32_bf16 v[204:207], v[156:159], v[204:207], v[64:67]
	s_setprio 0
	s_barrier
	s_nop 0
	ds_read_b128 v[64:67], v153 offset:16384
	ds_read_b128 v[68:71], v153 offset:17408
	ds_read_b128 v[72:75], v152 offset:16384
	ds_read_b128 v[76:79], v152 offset:17408
	ds_read_b128 v[80:83], v151 offset:16384
	ds_read_b128 v[84:87], v151 offset:17408
	ds_read_b128 v[88:91], v150 offset:16384
	ds_read_b128 v[92:95], v150 offset:17408
	s_waitcnt vmcnt(4)
	s_barrier
	s_waitcnt lgkmcnt(0)
	s_setprio 1
	s_waitcnt lgkmcnt(0)
	v_mfma_f32_16x16x32_bf16 v[60:63], v[130:133], v[64:67], v[60:63]
	v_mfma_f32_16x16x32_bf16 v[56:59], v[168:171], v[64:67], v[56:59]
	v_mfma_f32_16x16x32_bf16 v[52:55], v[130:133], v[72:75], v[52:55]
	v_mfma_f32_16x16x32_bf16 v[48:51], v[168:171], v[72:75], v[48:51]
	v_mfma_f32_16x16x32_bf16 v[216:219], v[130:133], v[80:83], v[44:47]
	v_mfma_f32_16x16x32_bf16 v[220:223], v[168:171], v[80:83], v[40:43]
	v_mfma_f32_16x16x32_bf16 v[130:133], v[130:133], v[88:91], v[36:39]
	v_mfma_f32_16x16x32_bf16 v[168:171], v[168:171], v[88:91], v[32:35]
	v_mfma_f32_16x16x32_bf16 v[32:35], v[164:167], v[68:71], v[60:63]
	v_mfma_f32_16x16x32_bf16 v[36:39], v[172:175], v[68:71], v[56:59]
	v_mfma_f32_16x16x32_bf16 v[40:43], v[164:167], v[76:79], v[52:55]
	v_mfma_f32_16x16x32_bf16 v[44:47], v[172:175], v[76:79], v[48:51]
	v_mfma_f32_16x16x32_bf16 v[48:51], v[164:167], v[84:87], v[216:219]
	v_mfma_f32_16x16x32_bf16 v[52:55], v[172:175], v[84:87], v[220:223]
	v_mfma_f32_16x16x32_bf16 v[56:59], v[164:167], v[92:95], v[130:133]
	v_mfma_f32_16x16x32_bf16 v[60:63], v[172:175], v[92:95], v[168:171]
	s_setprio 0
	s_setprio 1
	v_mfma_f32_16x16x32_bf16 v[28:31], v[160:163], v[64:67], v[28:31]
	v_mfma_f32_16x16x32_bf16 v[24:27], v[212:215], v[64:67], v[24:27]
	v_mfma_f32_16x16x32_bf16 v[20:23], v[160:163], v[72:75], v[20:23]
	v_mfma_f32_16x16x32_bf16 v[64:67], v[212:215], v[72:75], v[16:19]
	v_mfma_f32_16x16x32_bf16 v[72:75], v[160:163], v[80:83], v[12:15]
	v_mfma_f32_16x16x32_bf16 v[8:11], v[212:215], v[80:83], v[8:11]
	v_mfma_f32_16x16x32_bf16 v[80:83], v[160:163], v[88:91], v[4:7]
	v_mfma_f32_16x16x32_bf16 v[0:3], v[212:215], v[88:91], v[0:3]
	v_mfma_f32_16x16x32_bf16 v[4:7], v[208:211], v[68:71], v[28:31]
	v_mfma_f32_16x16x32_bf16 v[12:15], v[156:159], v[68:71], v[24:27]
	v_mfma_f32_16x16x32_bf16 v[16:19], v[208:211], v[76:79], v[20:23]
	v_mfma_f32_16x16x32_bf16 v[20:23], v[156:159], v[76:79], v[64:67]
	v_mfma_f32_16x16x32_bf16 v[24:27], v[208:211], v[84:87], v[72:75]
	v_mfma_f32_16x16x32_bf16 v[28:31], v[156:159], v[84:87], v[8:11]
	v_mfma_f32_16x16x32_bf16 v[64:67], v[208:211], v[92:95], v[80:83]
	v_mfma_f32_16x16x32_bf16 v[68:71], v[156:159], v[92:95], v[0:3]
	s_setprio 0
	s_barrier
	ds_read_b128 v[8:11], v155
	ds_read_b128 v[0:3], v155 offset:1024
	ds_read_b128 v[76:79], v155 offset:2048
	ds_read_b128 v[72:75], v155 offset:3072
	ds_read_b128 v[130:133], v153 offset:32768
	ds_read_b128 v[156:159], v153 offset:33792
	ds_read_b128 v[160:163], v152 offset:32768
	ds_read_b128 v[164:167], v152 offset:33792
	ds_read_b128 v[168:171], v151 offset:32768
	ds_read_b128 v[172:175], v151 offset:33792
	ds_read_b128 v[208:211], v150 offset:32768
	ds_read_b128 v[212:215], v150 offset:33792
	s_waitcnt vmcnt(2)
	s_barrier
	s_waitcnt lgkmcnt(0)
	s_setprio 1
	s_waitcnt lgkmcnt(0)
	v_mfma_f32_16x16x32_bf16 v[80:83], v[8:11], v[130:133], v[124:127]
	v_mfma_f32_16x16x32_bf16 v[84:87], v[76:79], v[130:133], v[120:123]
	v_mfma_f32_16x16x32_bf16 v[88:91], v[8:11], v[160:163], v[116:119]
	v_mfma_f32_16x16x32_bf16 v[92:95], v[76:79], v[160:163], v[112:115]
	v_mfma_f32_16x16x32_bf16 v[108:111], v[8:11], v[168:171], v[108:111]
	v_mfma_f32_16x16x32_bf16 v[104:107], v[76:79], v[168:171], v[104:107]
	v_mfma_f32_16x16x32_bf16 v[100:103], v[8:11], v[208:211], v[100:103]
	v_mfma_f32_16x16x32_bf16 v[96:99], v[76:79], v[208:211], v[96:99]
	v_mfma_f32_16x16x32_bf16 v[112:115], v[0:3], v[156:159], v[80:83]
	v_mfma_f32_16x16x32_bf16 v[116:119], v[72:75], v[156:159], v[84:87]
	v_mfma_f32_16x16x32_bf16 v[120:123], v[0:3], v[164:167], v[88:91]
	v_mfma_f32_16x16x32_bf16 v[124:127], v[72:75], v[164:167], v[92:95]
	v_mfma_f32_16x16x32_bf16 v[108:111], v[0:3], v[172:175], v[108:111]
	v_mfma_f32_16x16x32_bf16 v[104:107], v[72:75], v[172:175], v[104:107]
	v_mfma_f32_16x16x32_bf16 v[100:103], v[0:3], v[212:215], v[100:103]
	v_mfma_f32_16x16x32_bf16 v[96:99], v[72:75], v[212:215], v[96:99]
	s_setprio 0
	s_barrier
	ds_read_b128 v[88:91], v154
	ds_read_b128 v[80:83], v154 offset:1024
	ds_read_b128 v[92:95], v154 offset:2048
	ds_read_b128 v[84:87], v154 offset:3072
	s_waitcnt vmcnt(0)
	s_barrier
	s_waitcnt lgkmcnt(0)
	s_setprio 1
	s_waitcnt lgkmcnt(0)
	v_mfma_f32_16x16x32_bf16 v[176:179], v[88:91], v[130:133], v[176:179]
	v_mfma_f32_16x16x32_bf16 v[130:133], v[92:95], v[130:133], v[180:183]
	v_mfma_f32_16x16x32_bf16 v[180:183], v[88:91], v[160:163], v[184:187]
	v_mfma_f32_16x16x32_bf16 v[160:163], v[92:95], v[160:163], v[188:191]
	v_mfma_f32_16x16x32_bf16 v[184:187], v[88:91], v[168:171], v[192:195]
	v_mfma_f32_16x16x32_bf16 v[168:171], v[92:95], v[168:171], v[196:199]
	v_mfma_f32_16x16x32_bf16 v[188:191], v[88:91], v[208:211], v[200:203]
	v_mfma_f32_16x16x32_bf16 v[192:195], v[92:95], v[208:211], v[204:207]
	v_mfma_f32_16x16x32_bf16 v[176:179], v[80:83], v[156:159], v[176:179]
	v_mfma_f32_16x16x32_bf16 v[130:133], v[84:87], v[156:159], v[130:133]
	v_mfma_f32_16x16x32_bf16 v[154:157], v[80:83], v[164:167], v[180:183]
	v_mfma_f32_16x16x32_bf16 v[158:161], v[84:87], v[164:167], v[160:163]
	v_mfma_f32_16x16x32_bf16 v[162:165], v[80:83], v[172:175], v[184:187]
	v_mfma_f32_16x16x32_bf16 v[166:169], v[84:87], v[172:175], v[168:171]
	v_mfma_f32_16x16x32_bf16 v[170:173], v[80:83], v[212:215], v[188:191]
	v_mfma_f32_16x16x32_bf16 v[180:183], v[84:87], v[212:215], v[192:195]
	s_setprio 0
	s_barrier
	v_mbcnt_lo_u32_b32 v128, -1, 0
	v_mbcnt_hi_u32_b32 v128, -1, v128
	v_cvt_pk_bf16_f32 v112, v112, v113
	v_cvt_pk_bf16_f32 v113, v114, v115
	v_cvt_pk_bf16_f32 v114, v116, v117
	v_cvt_pk_bf16_f32 v115, v118, v119
	s_lshl_b32 s66, s64, 9
	v_add_u32_e32 v174, s72, v128
	v_ashrrev_i32_e32 v175, 6, v174
	v_and_b32_e32 v184, 15, v128
	v_and_b32_e32 v185, 48, v128
	v_mul_lo_u32 v186, v175, s77
	v_bfe_u32 v187, v128, 3, 3
	v_lshlrev_b32_e32 v128, 4, v128
	v_add_u32_e32 v186, 0x20000, v186
	v_lshrrev_b32_e32 v174, 2, v174
	v_and_b32_e32 v128, 0x70, v128
	v_mul_u32_u24_e32 v184, 0x90, v184
	v_and_b32_e32 v174, 64, v174
	v_add3_u32 v184, v186, v184, v185
	v_or_b32_e32 v185, v186, v128
	v_or3_b32 v174, s24, v174, v187
	v_mad_u32_u24 v185, v187, s78, v185
	ds_write_b128 v184, v[112:115]
	v_cvt_pk_bf16_f32 v112, v176, v177
	v_cvt_pk_bf16_f32 v113, v178, v179
	v_cvt_pk_bf16_f32 v114, v130, v131
	v_cvt_pk_bf16_f32 v115, v132, v133
	ds_write_b128 v184, v[112:115] offset:64
	v_lshlrev_b32_e32 v175, 7, v175
	ds_read_b128 v[112:115], v185
	v_lshlrev_b32_e32 v116, 12, v174
	v_and_or_b32 v116, v175, s79, v116
	v_or3_b32 v128, v116, s66, v128
	ds_read_b128 v[116:119], v185 offset:1152
	v_lshl_add_u64 v[130:131], s[0:1], 0, v[128:129]
	s_mov_b32 s64, 0x8000
	s_waitcnt lgkmcnt(0)
	global_store_dwordx4 v128, v[112:115], s[0:1]
	v_cvt_pk_bf16_f32 v108, v108, v109
	v_cvt_pk_bf16_f32 v109, v110, v111
	v_cvt_pk_bf16_f32 v110, v104, v105
	v_cvt_pk_bf16_f32 v111, v106, v107
	v_cvt_pk_bf16_f32 v104, v162, v163
	s_nop 1
	v_add_co_u32_e32 v112, vcc, s64, v130
	v_cvt_pk_bf16_f32 v114, v124, v125
	v_cvt_pk_bf16_f32 v115, v126, v127
	v_cvt_pk_bf16_f32 v105, v164, v165
	v_cvt_pk_bf16_f32 v106, v166, v167
	s_nop 1
	v_addc_co_u32_e32 v113, vcc, 0, v131, vcc
	global_store_dwordx4 v[112:113], v[116:119], off
	v_cvt_pk_bf16_f32 v112, v120, v121
	v_cvt_pk_bf16_f32 v113, v122, v123
	ds_write_b128 v184, v[112:115]
	v_cvt_pk_bf16_f32 v112, v154, v155
	v_cvt_pk_bf16_f32 v113, v156, v157
	v_cvt_pk_bf16_f32 v114, v158, v159
	v_cvt_pk_bf16_f32 v115, v160, v161
	ds_write_b128 v184, v[112:115] offset:64
	ds_read_b128 v[112:115], v185
	ds_read_b128 v[116:119], v185 offset:1152
	v_add_co_u32_e32 v120, vcc, s74, v130
	ds_write_b128 v184, v[108:111]
	v_cvt_pk_bf16_f32 v107, v168, v169
	ds_write_b128 v184, v[104:107] offset:64
	v_addc_co_u32_e32 v121, vcc, 0, v131, vcc
	ds_read_b128 v[104:107], v185
	ds_read_b128 v[108:111], v185 offset:1152
	s_waitcnt lgkmcnt(0)
	global_store_dwordx4 v[120:121], v[112:115], off
	v_cvt_pk_bf16_f32 v100, v100, v101
	v_cvt_pk_bf16_f32 v101, v102, v103
	v_cvt_pk_bf16_f32 v102, v96, v97
	v_cvt_pk_bf16_f32 v103, v98, v99
	ds_write_b128 v184, v[100:103]
	s_nop 0
	v_add_co_u32_e32 v112, vcc, s75, v130
	v_cvt_pk_bf16_f32 v96, v170, v171
	v_cvt_pk_bf16_f32 v97, v172, v173
	v_cvt_pk_bf16_f32 v98, v180, v181
	v_cvt_pk_bf16_f32 v99, v182, v183
	s_nop 1
	v_addc_co_u32_e32 v113, vcc, 0, v131, vcc
	global_store_dwordx4 v[112:113], v[116:119], off
	v_add_co_u32_e32 v112, vcc, s76, v130
	ds_write_b128 v184, v[96:99] offset:64
	s_nop 0
	v_addc_co_u32_e32 v113, vcc, 0, v131, vcc
	ds_read_b128 v[96:99], v185
	ds_read_b128 v[100:103], v185 offset:1152
	global_store_dwordx4 v[112:113], v[104:107], off
	s_nop 1
	v_add_co_u32_e32 v104, vcc, s80, v130
	s_nop 1
	v_addc_co_u32_e32 v105, vcc, 0, v131, vcc
	global_store_dwordx4 v[104:105], v[108:111], off
	v_add_co_u32_e32 v104, vcc, s81, v130
	s_nop 1
	v_addc_co_u32_e32 v105, vcc, 0, v131, vcc
	s_waitcnt lgkmcnt(0)
	global_store_dwordx4 v[104:105], v[96:99], off
	s_nop 1
	v_add_co_u32_e32 v96, vcc, s82, v130
	s_nop 1
	v_addc_co_u32_e32 v97, vcc, 0, v131, vcc
	global_store_dwordx4 v[96:97], v[100:103], off
	ds_read_b128 v[96:99], v153 offset:49152
	ds_read_b128 v[100:103], v153 offset:50176
	ds_read_b128 v[104:107], v152 offset:49152
	ds_read_b128 v[108:111], v152 offset:50176
	ds_read_b128 v[112:115], v151 offset:49152
	ds_read_b128 v[116:119], v151 offset:50176
	ds_read_b128 v[120:123], v150 offset:49152
	ds_read_b128 v[124:127], v150 offset:50176
	s_barrier
	s_waitcnt lgkmcnt(0)
	s_setprio 1
	s_waitcnt lgkmcnt(0)
	v_mfma_f32_16x16x32_bf16 v[32:35], v[8:11], v[96:99], v[32:35]
	v_mfma_f32_16x16x32_bf16 v[36:39], v[76:79], v[96:99], v[36:39]
	v_mfma_f32_16x16x32_bf16 v[40:43], v[8:11], v[104:107], v[40:43]
	v_mfma_f32_16x16x32_bf16 v[130:133], v[76:79], v[104:107], v[44:47]
	v_mfma_f32_16x16x32_bf16 v[150:153], v[8:11], v[112:115], v[48:51]
	v_mfma_f32_16x16x32_bf16 v[52:55], v[76:79], v[112:115], v[52:55]
	v_mfma_f32_16x16x32_bf16 v[8:11], v[8:11], v[120:123], v[56:59]
	v_mfma_f32_16x16x32_bf16 v[60:63], v[76:79], v[120:123], v[60:63]
	v_mfma_f32_16x16x32_bf16 v[56:59], v[0:3], v[100:103], v[32:35]
	v_mfma_f32_16x16x32_bf16 v[48:51], v[72:75], v[100:103], v[36:39]
	v_mfma_f32_16x16x32_bf16 v[44:47], v[0:3], v[108:111], v[40:43]
	v_mfma_f32_16x16x32_bf16 v[40:43], v[72:75], v[108:111], v[130:133]
	v_mfma_f32_16x16x32_bf16 v[36:39], v[0:3], v[116:119], v[150:153]
	v_mfma_f32_16x16x32_bf16 v[32:35], v[72:75], v[116:119], v[52:55]
	v_mfma_f32_16x16x32_bf16 v[8:11], v[0:3], v[124:127], v[8:11]
	v_mfma_f32_16x16x32_bf16 v[0:3], v[72:75], v[124:127], v[60:63]
	s_setprio 0
	s_setprio 1
	v_mfma_f32_16x16x32_bf16 v[4:7], v[88:91], v[96:99], v[4:7]
	v_mfma_f32_16x16x32_bf16 v[12:15], v[92:95], v[96:99], v[12:15]
	v_mfma_f32_16x16x32_bf16 v[16:19], v[88:91], v[104:107], v[16:19]
	v_mfma_f32_16x16x32_bf16 v[20:23], v[92:95], v[104:107], v[20:23]
	v_mfma_f32_16x16x32_bf16 v[72:75], v[88:91], v[112:115], v[24:27]
	v_mfma_f32_16x16x32_bf16 v[76:79], v[92:95], v[112:115], v[28:31]
	v_mfma_f32_16x16x32_bf16 v[64:67], v[88:91], v[120:123], v[64:67]
	v_mfma_f32_16x16x32_bf16 v[68:71], v[92:95], v[120:123], v[68:71]
	v_mfma_f32_16x16x32_bf16 v[60:63], v[80:83], v[100:103], v[4:7]
	v_mfma_f32_16x16x32_bf16 v[52:55], v[84:87], v[100:103], v[12:15]
	v_mfma_f32_16x16x32_bf16 v[28:31], v[80:83], v[108:111], v[16:19]
	v_mfma_f32_16x16x32_bf16 v[24:27], v[84:87], v[108:111], v[20:23]
	v_mfma_f32_16x16x32_bf16 v[20:23], v[80:83], v[116:119], v[72:75]
	v_mfma_f32_16x16x32_bf16 v[16:19], v[84:87], v[116:119], v[76:79]
	v_mfma_f32_16x16x32_bf16 v[12:15], v[80:83], v[124:127], v[64:67]
	v_mfma_f32_16x16x32_bf16 v[4:7], v[84:87], v[124:127], v[68:71]
	s_setprio 0
	v_cmp_gt_u32_e32 vcc, s83, v136
	s_barrier
	s_and_saveexec_b64 s[64:65], vcc
	s_cbranch_execz .LBB0_181
	s_barrier

.LBB0_234:
	ds_read_b128 v[140:143], v138
	ds_read_b128 v[144:147], v138 offset:1024
	ds_read_b128 v[148:151], v138 offset:2048
	ds_read_b128 v[152:155], v138 offset:3072
	ds_read_b128 v[156:159], v193
	ds_read_b128 v[160:163], v193 offset:1024
	ds_read_b128 v[194:197], v192
	ds_read_b128 v[198:201], v192 offset:1024
	ds_read_b128 v[202:205], v191
	ds_read_b128 v[206:209], v191 offset:1024
	ds_read_b128 v[210:213], v190
	ds_read_b128 v[214:217], v190 offset:1024
	s_waitcnt lgkmcnt(8)
	s_waitcnt vmcnt(10)
	s_barrier
	s_waitcnt lgkmcnt(0)
	s_waitcnt lgkmcnt(0)
	v_mfma_f32_16x16x32_bf16 v[124:127], v[140:143], v[156:159], v[124:127]
	v_mfma_f32_16x16x32_bf16 v[120:123], v[148:151], v[156:159], v[120:123]
	v_mfma_f32_16x16x32_bf16 v[116:119], v[140:143], v[194:197], v[116:119]
	v_mfma_f32_16x16x32_bf16 v[112:115], v[148:151], v[194:197], v[112:115]
	v_mfma_f32_16x16x32_bf16 v[108:111], v[140:143], v[202:205], v[108:111]
	v_mfma_f32_16x16x32_bf16 v[104:107], v[148:151], v[202:205], v[104:107]
	v_mfma_f32_16x16x32_bf16 v[100:103], v[140:143], v[210:213], v[100:103]
	v_mfma_f32_16x16x32_bf16 v[96:99], v[148:151], v[210:213], v[96:99]
	v_mfma_f32_16x16x32_bf16 v[124:127], v[144:147], v[160:163], v[124:127]
	v_mfma_f32_16x16x32_bf16 v[120:123], v[152:155], v[160:163], v[120:123]
	v_mfma_f32_16x16x32_bf16 v[116:119], v[144:147], v[198:201], v[116:119]
	v_mfma_f32_16x16x32_bf16 v[112:115], v[152:155], v[198:201], v[112:115]
	v_mfma_f32_16x16x32_bf16 v[108:111], v[144:147], v[206:209], v[108:111]
	v_mfma_f32_16x16x32_bf16 v[104:107], v[152:155], v[206:209], v[104:107]
	v_mfma_f32_16x16x32_bf16 v[100:103], v[144:147], v[214:217], v[100:103]
	v_mfma_f32_16x16x32_bf16 v[96:99], v[152:155], v[214:217], v[96:99]
	s_barrier
	v_readfirstlane_b32 s82, v189
	v_lshl_add_u64 v[234:235], s[60:61], 0, v[164:165]
	s_mov_b32 m0, s82
	v_readfirstlane_b32 s82, v188
	ds_read_b128 v[218:221], v135
	ds_read_b128 v[222:225], v135 offset:1024
	ds_read_b128 v[226:229], v135 offset:2048
	ds_read_b128 v[230:233], v135 offset:3072
	global_load_lds_dwordx4 v[234:235], off
	v_lshl_add_u64 v[236:237], v[234:235], 0, s[2:3]
	s_mov_b32 m0, s82
	s_nop 0
	global_load_lds_dwordx4 v[236:237], off
	v_readfirstlane_b32 s82, v169
	v_lshl_add_u64 v[236:237], v[128:129], 0, s[22:23]
	s_mov_b32 m0, s82
	v_readfirstlane_b32 s82, v187
	global_load_lds_dwordx4 v[236:237], off
	v_lshl_add_u64 v[236:237], v[128:129], 0, s[24:25]
	s_mov_b32 m0, s82
	s_nop 0
	global_load_lds_dwordx4 v[236:237], off
	s_waitcnt vmcnt(12)
	s_barrier
	s_waitcnt lgkmcnt(0)
	s_waitcnt lgkmcnt(0)
	v_mfma_f32_16x16x32_bf16 v[92:95], v[218:221], v[156:159], v[92:95]
	v_mfma_f32_16x16x32_bf16 v[88:91], v[226:229], v[156:159], v[88:91]
	v_mfma_f32_16x16x32_bf16 v[84:87], v[218:221], v[194:197], v[84:87]
	v_mfma_f32_16x16x32_bf16 v[80:83], v[226:229], v[194:197], v[80:83]
	v_mfma_f32_16x16x32_bf16 v[76:79], v[218:221], v[202:205], v[76:79]
	v_mfma_f32_16x16x32_bf16 v[72:75], v[226:229], v[202:205], v[72:75]
	v_mfma_f32_16x16x32_bf16 v[68:71], v[218:221], v[210:213], v[68:71]
	v_mfma_f32_16x16x32_bf16 v[64:67], v[226:229], v[210:213], v[64:67]
	v_mfma_f32_16x16x32_bf16 v[92:95], v[222:225], v[160:163], v[92:95]
	v_mfma_f32_16x16x32_bf16 v[88:91], v[230:233], v[160:163], v[88:91]
	v_mfma_f32_16x16x32_bf16 v[84:87], v[222:225], v[198:201], v[84:87]
	v_mfma_f32_16x16x32_bf16 v[80:83], v[230:233], v[198:201], v[80:83]
	v_mfma_f32_16x16x32_bf16 v[76:79], v[222:225], v[206:209], v[76:79]
	v_mfma_f32_16x16x32_bf16 v[72:75], v[230:233], v[206:209], v[72:75]
	v_mfma_f32_16x16x32_bf16 v[68:71], v[222:225], v[214:217], v[68:71]
	v_mfma_f32_16x16x32_bf16 v[64:67], v[230:233], v[214:217], v[64:67]
	s_barrier
	ds_read_b128 v[156:159], v193 offset:16384
	ds_read_b128 v[160:163], v193 offset:17408
	ds_read_b128 v[194:197], v192 offset:16384
	ds_read_b128 v[198:201], v192 offset:17408
	ds_read_b128 v[202:205], v191 offset:16384
	ds_read_b128 v[206:209], v191 offset:17408
	ds_read_b128 v[210:213], v190 offset:16384
	ds_read_b128 v[214:217], v190 offset:17408
	v_readfirstlane_b32 s82, v186
	v_lshl_add_u64 v[236:237], v[234:235], 0, s[6:7]
	s_mov_b32 m0, s82
	v_readfirstlane_b32 s82, v185
	global_load_lds_dwordx4 v[236:237], off
	v_lshl_add_u64 v[236:237], v[234:235], 0, s[8:9]
	s_mov_b32 m0, s82
	s_nop 0
	global_load_lds_dwordx4 v[236:237], off
	s_barrier
	s_waitcnt lgkmcnt(0)
	s_waitcnt lgkmcnt(0)
	v_mfma_f32_16x16x32_bf16 v[60:63], v[140:143], v[156:159], v[60:63]
	v_mfma_f32_16x16x32_bf16 v[56:59], v[148:151], v[156:159], v[56:59]
	v_mfma_f32_16x16x32_bf16 v[52:55], v[140:143], v[194:197], v[52:55]
	v_mfma_f32_16x16x32_bf16 v[48:51], v[148:151], v[194:197], v[48:51]
	v_mfma_f32_16x16x32_bf16 v[44:47], v[140:143], v[202:205], v[44:47]
	v_mfma_f32_16x16x32_bf16 v[40:43], v[148:151], v[202:205], v[40:43]
	v_mfma_f32_16x16x32_bf16 v[36:39], v[140:143], v[210:213], v[36:39]
	v_mfma_f32_16x16x32_bf16 v[32:35], v[148:151], v[210:213], v[32:35]
	v_mfma_f32_16x16x32_bf16 v[60:63], v[144:147], v[160:163], v[60:63]
	v_mfma_f32_16x16x32_bf16 v[56:59], v[152:155], v[160:163], v[56:59]
	v_mfma_f32_16x16x32_bf16 v[52:55], v[144:147], v[198:201], v[52:55]
	v_mfma_f32_16x16x32_bf16 v[48:51], v[152:155], v[198:201], v[48:51]
	v_mfma_f32_16x16x32_bf16 v[44:47], v[144:147], v[206:209], v[44:47]
	v_mfma_f32_16x16x32_bf16 v[40:43], v[152:155], v[206:209], v[40:43]
	v_mfma_f32_16x16x32_bf16 v[36:39], v[144:147], v[214:217], v[36:39]
	v_mfma_f32_16x16x32_bf16 v[32:35], v[152:155], v[214:217], v[32:35]
	s_barrier
	v_readfirstlane_b32 s82, v184
	v_lshl_add_u64 v[142:143], v[128:129], 0, s[26:27]
	s_mov_b32 m0, s82
	v_readfirstlane_b32 s82, v183
	global_load_lds_dwordx4 v[142:143], off
	s_mov_b32 m0, s82
	s_nop 0
	global_load_lds_dwordx4 v[128:129], off
	s_waitcnt vmcnt(12)
	s_barrier
	v_mfma_f32_16x16x32_bf16 v[28:31], v[218:221], v[156:159], v[28:31]
	v_mfma_f32_16x16x32_bf16 v[24:27], v[226:229], v[156:159], v[24:27]
	v_mfma_f32_16x16x32_bf16 v[20:23], v[218:221], v[194:197], v[20:23]
	v_mfma_f32_16x16x32_bf16 v[16:19], v[226:229], v[194:197], v[16:19]
	v_mfma_f32_16x16x32_bf16 v[12:15], v[218:221], v[202:205], v[12:15]
	v_mfma_f32_16x16x32_bf16 v[8:11], v[226:229], v[202:205], v[8:11]
	v_mfma_f32_16x16x32_bf16 v[4:7], v[218:221], v[210:213], v[4:7]
	v_mfma_f32_16x16x32_bf16 v[0:3], v[226:229], v[210:213], v[0:3]
	v_mfma_f32_16x16x32_bf16 v[28:31], v[222:225], v[160:163], v[28:31]
	v_mfma_f32_16x16x32_bf16 v[24:27], v[230:233], v[160:163], v[24:27]
	v_mfma_f32_16x16x32_bf16 v[20:23], v[222:225], v[198:201], v[20:23]
	v_mfma_f32_16x16x32_bf16 v[16:19], v[230:233], v[198:201], v[16:19]
	v_mfma_f32_16x16x32_bf16 v[12:15], v[222:225], v[206:209], v[12:15]
	v_mfma_f32_16x16x32_bf16 v[8:11], v[230:233], v[206:209], v[8:11]
	v_mfma_f32_16x16x32_bf16 v[4:7], v[222:225], v[214:217], v[4:7]
	v_mfma_f32_16x16x32_bf16 v[0:3], v[230:233], v[214:217], v[0:3]
	s_barrier
	ds_read_b128 v[140:143], v130
	ds_read_b128 v[144:147], v130 offset:1024
	ds_read_b128 v[148:151], v130 offset:2048
	ds_read_b128 v[152:155], v130 offset:3072
	ds_read_b128 v[156:159], v193 offset:32768
	ds_read_b128 v[160:163], v193 offset:33792
	ds_read_b128 v[194:197], v192 offset:32768
	ds_read_b128 v[198:201], v192 offset:33792
	ds_read_b128 v[202:205], v191 offset:32768
	ds_read_b128 v[206:209], v191 offset:33792
	ds_read_b128 v[210:213], v190 offset:32768
	ds_read_b128 v[214:217], v190 offset:33792
	s_waitcnt lgkmcnt(8)
	s_waitcnt vmcnt(10)
	s_barrier
	s_waitcnt lgkmcnt(0)
	s_waitcnt lgkmcnt(0)
	v_mfma_f32_16x16x32_bf16 v[124:127], v[140:143], v[156:159], v[124:127]
	v_mfma_f32_16x16x32_bf16 v[120:123], v[148:151], v[156:159], v[120:123]
	v_mfma_f32_16x16x32_bf16 v[116:119], v[140:143], v[194:197], v[116:119]
	v_mfma_f32_16x16x32_bf16 v[112:115], v[148:151], v[194:197], v[112:115]
	v_mfma_f32_16x16x32_bf16 v[108:111], v[140:143], v[202:205], v[108:111]
	v_mfma_f32_16x16x32_bf16 v[104:107], v[148:151], v[202:205], v[104:107]
	v_mfma_f32_16x16x32_bf16 v[100:103], v[140:143], v[210:213], v[100:103]
	v_mfma_f32_16x16x32_bf16 v[96:99], v[148:151], v[210:213], v[96:99]
	v_mfma_f32_16x16x32_bf16 v[124:127], v[144:147], v[160:163], v[124:127]
	v_mfma_f32_16x16x32_bf16 v[120:123], v[152:155], v[160:163], v[120:123]
	v_mfma_f32_16x16x32_bf16 v[116:119], v[144:147], v[198:201], v[116:119]
	v_mfma_f32_16x16x32_bf16 v[112:115], v[152:155], v[198:201], v[112:115]
	v_mfma_f32_16x16x32_bf16 v[108:111], v[144:147], v[206:209], v[108:111]
	v_mfma_f32_16x16x32_bf16 v[104:107], v[152:155], v[206:209], v[104:107]
	v_mfma_f32_16x16x32_bf16 v[100:103], v[144:147], v[214:217], v[100:103]
	v_mfma_f32_16x16x32_bf16 v[96:99], v[152:155], v[214:217], v[96:99]
	s_barrier
	v_readfirstlane_b32 s82, v182
	v_lshl_add_u64 v[234:235], s[56:57], 0, v[164:165]
	s_mov_b32 m0, s82
	v_readfirstlane_b32 s82, v181
	ds_read_b128 v[218:221], v132
	ds_read_b128 v[222:225], v132 offset:1024
	ds_read_b128 v[226:229], v132 offset:2048
	ds_read_b128 v[230:233], v132 offset:3072
	global_load_lds_dwordx4 v[234:235], off
	v_lshl_add_u64 v[236:237], v[234:235], 0, s[2:3]
	s_mov_b32 m0, s82
	s_nop 0
	global_load_lds_dwordx4 v[236:237], off
	v_readfirstlane_b32 s82, v177
	v_lshl_add_u64 v[236:237], v[128:129], 0, s[28:29]
	s_mov_b32 m0, s82
	v_readfirstlane_b32 s82, v175
	global_load_lds_dwordx4 v[236:237], off
	v_lshl_add_u64 v[236:237], v[128:129], 0, s[30:31]
	s_mov_b32 m0, s82
	s_nop 0
	global_load_lds_dwordx4 v[236:237], off
	s_waitcnt vmcnt(12)
	s_barrier
	s_waitcnt lgkmcnt(0)
	s_waitcnt lgkmcnt(0)
	v_mfma_f32_16x16x32_bf16 v[92:95], v[218:221], v[156:159], v[92:95]
	v_mfma_f32_16x16x32_bf16 v[88:91], v[226:229], v[156:159], v[88:91]
	v_mfma_f32_16x16x32_bf16 v[84:87], v[218:221], v[194:197], v[84:87]
	v_mfma_f32_16x16x32_bf16 v[80:83], v[226:229], v[194:197], v[80:83]
	v_mfma_f32_16x16x32_bf16 v[76:79], v[218:221], v[202:205], v[76:79]
	v_mfma_f32_16x16x32_bf16 v[72:75], v[226:229], v[202:205], v[72:75]
	v_mfma_f32_16x16x32_bf16 v[68:71], v[218:221], v[210:213], v[68:71]
	v_mfma_f32_16x16x32_bf16 v[64:67], v[226:229], v[210:213], v[64:67]
	v_mfma_f32_16x16x32_bf16 v[92:95], v[222:225], v[160:163], v[92:95]
	v_mfma_f32_16x16x32_bf16 v[88:91], v[230:233], v[160:163], v[88:91]
	v_mfma_f32_16x16x32_bf16 v[84:87], v[222:225], v[198:201], v[84:87]
	v_mfma_f32_16x16x32_bf16 v[80:83], v[230:233], v[198:201], v[80:83]
	v_mfma_f32_16x16x32_bf16 v[76:79], v[222:225], v[206:209], v[76:79]
	v_mfma_f32_16x16x32_bf16 v[72:75], v[230:233], v[206:209], v[72:75]
	v_mfma_f32_16x16x32_bf16 v[68:71], v[222:225], v[214:217], v[68:71]
	v_mfma_f32_16x16x32_bf16 v[64:67], v[230:233], v[214:217], v[64:67]
	s_barrier
	ds_read_b128 v[156:159], v193 offset:49152
	ds_read_b128 v[160:163], v193 offset:50176
	ds_read_b128 v[194:197], v192 offset:49152
	ds_read_b128 v[198:201], v192 offset:50176
	ds_read_b128 v[202:205], v191 offset:49152
	ds_read_b128 v[206:209], v191 offset:50176
	ds_read_b128 v[210:213], v190 offset:49152
	ds_read_b128 v[214:217], v190 offset:50176
	v_readfirstlane_b32 s82, v173
	v_lshl_add_u64 v[236:237], v[234:235], 0, s[6:7]
	s_mov_b32 m0, s82
	v_readfirstlane_b32 s82, v171
	global_load_lds_dwordx4 v[236:237], off
	v_lshl_add_u64 v[236:237], v[234:235], 0, s[8:9]
	s_mov_b32 m0, s82
	s_nop 0
	global_load_lds_dwordx4 v[236:237], off
	s_barrier
	s_waitcnt lgkmcnt(0)
	s_waitcnt lgkmcnt(0)
	v_mfma_f32_16x16x32_bf16 v[60:63], v[140:143], v[156:159], v[60:63]
	v_mfma_f32_16x16x32_bf16 v[56:59], v[148:151], v[156:159], v[56:59]
	v_mfma_f32_16x16x32_bf16 v[52:55], v[140:143], v[194:197], v[52:55]
	v_mfma_f32_16x16x32_bf16 v[48:51], v[148:151], v[194:197], v[48:51]
	v_mfma_f32_16x16x32_bf16 v[44:47], v[140:143], v[202:205], v[44:47]
	v_mfma_f32_16x16x32_bf16 v[40:43], v[148:151], v[202:205], v[40:43]
	v_mfma_f32_16x16x32_bf16 v[36:39], v[140:143], v[210:213], v[36:39]
	v_mfma_f32_16x16x32_bf16 v[32:35], v[148:151], v[210:213], v[32:35]
	v_mfma_f32_16x16x32_bf16 v[60:63], v[144:147], v[160:163], v[60:63]
	v_mfma_f32_16x16x32_bf16 v[56:59], v[152:155], v[160:163], v[56:59]
	v_mfma_f32_16x16x32_bf16 v[52:55], v[144:147], v[198:201], v[52:55]
	v_mfma_f32_16x16x32_bf16 v[48:51], v[152:155], v[198:201], v[48:51]
	v_mfma_f32_16x16x32_bf16 v[44:47], v[144:147], v[206:209], v[44:47]
	v_mfma_f32_16x16x32_bf16 v[40:43], v[152:155], v[206:209], v[40:43]
	v_mfma_f32_16x16x32_bf16 v[36:39], v[144:147], v[214:217], v[36:39]
	v_mfma_f32_16x16x32_bf16 v[32:35], v[152:155], v[214:217], v[32:35]
	s_barrier
	v_lshl_add_u64 v[128:129], v[128:129], 0, s[34:35]
	v_readfirstlane_b32 s82, v137
	v_lshl_add_u64 v[142:143], v[128:129], 0, s[18:19]
	s_mov_b32 m0, s82
	v_readfirstlane_b32 s82, v136
	global_load_lds_dwordx4 v[142:143], off
	v_lshl_add_u64 v[142:143], v[128:129], 0, s[20:21]
	s_mov_b32 m0, s82
	s_nop 0
	global_load_lds_dwordx4 v[142:143], off
	s_waitcnt vmcnt(12)
	s_barrier
	v_mfma_f32_16x16x32_bf16 v[28:31], v[218:221], v[156:159], v[28:31]
	v_mfma_f32_16x16x32_bf16 v[24:27], v[226:229], v[156:159], v[24:27]
	v_mfma_f32_16x16x32_bf16 v[20:23], v[218:221], v[194:197], v[20:23]
	v_mfma_f32_16x16x32_bf16 v[16:19], v[226:229], v[194:197], v[16:19]
	v_mfma_f32_16x16x32_bf16 v[12:15], v[218:221], v[202:205], v[12:15]
	v_mfma_f32_16x16x32_bf16 v[8:11], v[226:229], v[202:205], v[8:11]
	v_mfma_f32_16x16x32_bf16 v[4:7], v[218:221], v[210:213], v[4:7]
	v_mfma_f32_16x16x32_bf16 v[0:3], v[226:229], v[210:213], v[0:3]
	v_mfma_f32_16x16x32_bf16 v[28:31], v[222:225], v[160:163], v[28:31]
	v_mfma_f32_16x16x32_bf16 v[24:27], v[230:233], v[160:163], v[24:27]
	v_mfma_f32_16x16x32_bf16 v[20:23], v[222:225], v[198:201], v[20:23]
	v_mfma_f32_16x16x32_bf16 v[16:19], v[230:233], v[198:201], v[16:19]
	v_mfma_f32_16x16x32_bf16 v[12:15], v[222:225], v[206:209], v[12:15]
	v_mfma_f32_16x16x32_bf16 v[8:11], v[230:233], v[206:209], v[8:11]
	v_mfma_f32_16x16x32_bf16 v[4:7], v[222:225], v[214:217], v[4:7]
	v_mfma_f32_16x16x32_bf16 v[0:3], v[230:233], v[214:217], v[0:3]
	s_add_i32 s14, s14, 2
	s_add_u32 s56, s56, s58
	s_addc_u32 s57, s57, s59
	s_add_u32 s60, s60, s58
	s_addc_u32 s61, s61, s59
	s_cmp_lt_u32 s14, 28
	s_barrier
	s_cbranch_scc1 .LBB0_234
	s_lshl_b32 s14, s62, 3
	s_or_b32 s82, s63, s14
	s_lshl_b32 s56, s82, 8
	v_lshlrev_b32_e32 v128, 3, v131
	v_lshlrev_b32_e32 v129, 5, v131
	s_or_b32 s14, s56, 0x80
	v_and_b32_e32 v128, 0x7fff0, v128
	v_and_b32_e32 v129, 32, v129
	s_lshl_b64 s[58:59], s[14:15], 13
	v_add_u32_e32 v129, v129, v134
	v_add_lshl_u32 v128, v133, v128, 13
	s_add_u32 s58, s40, s58
	v_lshl_add_u32 v164, v129, 1, v128
	s_addc_u32 s59, s41, s59
	v_lshl_add_u64 v[128:129], s[58:59], 0, v[164:165]
	v_readfirstlane_b32 s14, v137
	ds_read_b128 v[140:143], v138
	ds_read_b128 v[144:147], v138 offset:1024
	ds_read_b128 v[148:151], v138 offset:2048
	ds_read_b128 v[152:155], v138 offset:3072
	ds_read_b128 v[156:159], v193
	ds_read_b128 v[160:163], v193 offset:1024
	ds_read_b128 v[194:197], v192
	ds_read_b128 v[198:201], v192 offset:1024
	ds_read_b128 v[202:205], v191
	ds_read_b128 v[206:209], v191 offset:1024
	ds_read_b128 v[210:213], v190
	ds_read_b128 v[214:217], v190 offset:1024
	v_lshl_add_u64 v[138:139], v[128:129], 0, s[44:45]
	s_mov_b32 m0, s14
	v_readfirstlane_b32 s14, v136
	global_load_lds_dwordx4 v[138:139], off
	v_lshl_add_u64 v[128:129], v[128:129], 0, s[46:47]
	s_mov_b32 m0, s14
	s_mov_b32 s57, s15
	global_load_lds_dwordx4 v[128:129], off
	s_waitcnt vmcnt(10)
	s_barrier
	s_waitcnt lgkmcnt(0)
	s_setprio 1
	s_waitcnt lgkmcnt(0)
	v_mfma_f32_16x16x32_bf16 v[124:127], v[140:143], v[156:159], v[124:127]
	v_mfma_f32_16x16x32_bf16 v[120:123], v[148:151], v[156:159], v[120:123]
	v_mfma_f32_16x16x32_bf16 v[116:119], v[140:143], v[194:197], v[116:119]
	v_mfma_f32_16x16x32_bf16 v[112:115], v[148:151], v[194:197], v[112:115]
	v_mfma_f32_16x16x32_bf16 v[108:111], v[140:143], v[202:205], v[108:111]
	v_mfma_f32_16x16x32_bf16 v[104:107], v[148:151], v[202:205], v[104:107]
	v_mfma_f32_16x16x32_bf16 v[100:103], v[140:143], v[210:213], v[100:103]
	v_mfma_f32_16x16x32_bf16 v[96:99], v[148:151], v[210:213], v[96:99]
	v_mfma_f32_16x16x32_bf16 v[124:127], v[144:147], v[160:163], v[124:127]
	v_mfma_f32_16x16x32_bf16 v[120:123], v[152:155], v[160:163], v[120:123]
	v_mfma_f32_16x16x32_bf16 v[116:119], v[144:147], v[198:201], v[116:119]
	v_mfma_f32_16x16x32_bf16 v[112:115], v[152:155], v[198:201], v[112:115]
	v_mfma_f32_16x16x32_bf16 v[108:111], v[144:147], v[206:209], v[108:111]
	v_mfma_f32_16x16x32_bf16 v[104:107], v[152:155], v[206:209], v[104:107]
	v_mfma_f32_16x16x32_bf16 v[100:103], v[144:147], v[214:217], v[100:103]
	v_mfma_f32_16x16x32_bf16 v[96:99], v[152:155], v[214:217], v[96:99]
	s_setprio 0
	s_barrier
	ds_read_b128 v[136:139], v135
	ds_read_b128 v[218:221], v135 offset:1024
	ds_read_b128 v[222:225], v135 offset:2048
	ds_read_b128 v[226:229], v135 offset:3072
	s_barrier
	s_waitcnt lgkmcnt(0)
	s_setprio 1
	s_waitcnt lgkmcnt(0)
	v_mfma_f32_16x16x32_bf16 v[92:95], v[136:139], v[156:159], v[92:95]
	v_mfma_f32_16x16x32_bf16 v[84:87], v[136:139], v[194:197], v[84:87]
	v_mfma_f32_16x16x32_bf16 v[80:83], v[222:225], v[194:197], v[80:83]
	v_mfma_f32_16x16x32_bf16 v[88:91], v[222:225], v[156:159], v[88:91]
	v_mfma_f32_16x16x32_bf16 v[76:79], v[136:139], v[202:205], v[76:79]
	v_mfma_f32_16x16x32_bf16 v[72:75], v[222:225], v[202:205], v[72:75]
	v_mfma_f32_16x16x32_bf16 v[68:71], v[136:139], v[210:213], v[68:71]
	v_mfma_f32_16x16x32_bf16 v[64:67], v[222:225], v[210:213], v[64:67]
	v_mfma_f32_16x16x32_bf16 v[156:159], v[218:221], v[160:163], v[92:95]
	v_mfma_f32_16x16x32_bf16 v[194:197], v[218:221], v[198:201], v[84:87]
	v_mfma_f32_16x16x32_bf16 v[198:201], v[226:229], v[198:201], v[80:83]
	v_mfma_f32_16x16x32_bf16 v[160:163], v[226:229], v[160:163], v[88:91]
	v_mfma_f32_16x16x32_bf16 v[202:205], v[218:221], v[206:209], v[76:79]
	v_mfma_f32_16x16x32_bf16 v[206:209], v[226:229], v[206:209], v[72:75]
	v_mfma_f32_16x16x32_bf16 v[210:213], v[218:221], v[214:217], v[68:71]
	v_mfma_f32_16x16x32_bf16 v[214:217], v[226:229], v[214:217], v[64:67]
	s_setprio 0
	s_barrier
	s_nop 0
	ds_read_b128 v[64:67], v193 offset:16384
	ds_read_b128 v[68:71], v193 offset:17408
	ds_read_b128 v[72:75], v192 offset:16384
	ds_read_b128 v[76:79], v192 offset:17408
	ds_read_b128 v[80:83], v191 offset:16384
	ds_read_b128 v[84:87], v191 offset:17408
	ds_read_b128 v[88:91], v190 offset:16384
	ds_read_b128 v[92:95], v190 offset:17408
	s_waitcnt vmcnt(4)
	s_barrier
	s_waitcnt lgkmcnt(0)
	s_setprio 1
	s_waitcnt lgkmcnt(0)
	v_mfma_f32_16x16x32_bf16 v[60:63], v[140:143], v[64:67], v[60:63]
	v_mfma_f32_16x16x32_bf16 v[56:59], v[148:151], v[64:67], v[56:59]
	v_mfma_f32_16x16x32_bf16 v[52:55], v[140:143], v[72:75], v[52:55]
	v_mfma_f32_16x16x32_bf16 v[48:51], v[148:151], v[72:75], v[48:51]
	v_mfma_f32_16x16x32_bf16 v[230:233], v[140:143], v[80:83], v[44:47]
	v_mfma_f32_16x16x32_bf16 v[234:237], v[148:151], v[80:83], v[40:43]
	v_mfma_f32_16x16x32_bf16 v[140:143], v[140:143], v[88:91], v[36:39]
	v_mfma_f32_16x16x32_bf16 v[148:151], v[148:151], v[88:91], v[32:35]
	v_mfma_f32_16x16x32_bf16 v[32:35], v[144:147], v[68:71], v[60:63]
	v_mfma_f32_16x16x32_bf16 v[36:39], v[152:155], v[68:71], v[56:59]
	v_mfma_f32_16x16x32_bf16 v[40:43], v[144:147], v[76:79], v[52:55]
	v_mfma_f32_16x16x32_bf16 v[44:47], v[152:155], v[76:79], v[48:51]
	v_mfma_f32_16x16x32_bf16 v[48:51], v[144:147], v[84:87], v[230:233]
	v_mfma_f32_16x16x32_bf16 v[52:55], v[152:155], v[84:87], v[234:237]
	v_mfma_f32_16x16x32_bf16 v[56:59], v[144:147], v[92:95], v[140:143]
	v_mfma_f32_16x16x32_bf16 v[60:63], v[152:155], v[92:95], v[148:151]
	s_setprio 0
	s_setprio 1
	v_mfma_f32_16x16x32_bf16 v[28:31], v[136:139], v[64:67], v[28:31]
	v_mfma_f32_16x16x32_bf16 v[24:27], v[222:225], v[64:67], v[24:27]
	v_mfma_f32_16x16x32_bf16 v[20:23], v[136:139], v[72:75], v[20:23]
	v_mfma_f32_16x16x32_bf16 v[64:67], v[222:225], v[72:75], v[16:19]
	v_mfma_f32_16x16x32_bf16 v[12:15], v[136:139], v[80:83], v[12:15]
	v_mfma_f32_16x16x32_bf16 v[8:11], v[222:225], v[80:83], v[8:11]
	v_mfma_f32_16x16x32_bf16 v[72:75], v[136:139], v[88:91], v[4:7]
	v_mfma_f32_16x16x32_bf16 v[80:83], v[222:225], v[88:91], v[0:3]
	v_mfma_f32_16x16x32_bf16 v[0:3], v[218:221], v[68:71], v[28:31]
	v_mfma_f32_16x16x32_bf16 v[4:7], v[226:229], v[68:71], v[24:27]
	v_mfma_f32_16x16x32_bf16 v[16:19], v[218:221], v[76:79], v[20:23]
	v_mfma_f32_16x16x32_bf16 v[20:23], v[226:229], v[76:79], v[64:67]
	v_mfma_f32_16x16x32_bf16 v[24:27], v[218:221], v[84:87], v[12:15]
	v_mfma_f32_16x16x32_bf16 v[28:31], v[226:229], v[84:87], v[8:11]
	v_mfma_f32_16x16x32_bf16 v[64:67], v[218:221], v[92:95], v[72:75]
	v_mfma_f32_16x16x32_bf16 v[68:71], v[226:229], v[92:95], v[80:83]
	s_setprio 0
	s_barrier
	ds_read_b128 v[12:15], v130
	ds_read_b128 v[8:11], v130 offset:1024
	ds_read_b128 v[76:79], v130 offset:2048
	ds_read_b128 v[72:75], v130 offset:3072
	ds_read_b128 v[140:143], v193 offset:32768
	ds_read_b128 v[148:151], v193 offset:33792
	ds_read_b128 v[218:221], v192 offset:32768
	ds_read_b128 v[222:225], v192 offset:33792
	ds_read_b128 v[226:229], v191 offset:32768
	ds_read_b128 v[230:233], v191 offset:33792
	ds_read_b128 v[234:237], v190 offset:32768
	ds_read_b128 v[238:241], v190 offset:33792
	s_waitcnt vmcnt(2)
	s_barrier
	s_waitcnt lgkmcnt(0)
	s_setprio 1
	s_waitcnt lgkmcnt(0)
	v_mfma_f32_16x16x32_bf16 v[80:83], v[12:15], v[140:143], v[124:127]
	v_mfma_f32_16x16x32_bf16 v[84:87], v[76:79], v[140:143], v[120:123]
	v_mfma_f32_16x16x32_bf16 v[88:91], v[12:15], v[218:221], v[116:119]
	v_mfma_f32_16x16x32_bf16 v[92:95], v[76:79], v[218:221], v[112:115]
	v_mfma_f32_16x16x32_bf16 v[108:111], v[12:15], v[226:229], v[108:111]
	v_mfma_f32_16x16x32_bf16 v[104:107], v[76:79], v[226:229], v[104:107]
	v_mfma_f32_16x16x32_bf16 v[100:103], v[12:15], v[234:237], v[100:103]
	v_mfma_f32_16x16x32_bf16 v[96:99], v[76:79], v[234:237], v[96:99]
	v_mfma_f32_16x16x32_bf16 v[152:155], v[8:11], v[148:151], v[80:83]
	v_mfma_f32_16x16x32_bf16 v[144:147], v[72:75], v[148:151], v[84:87]
	v_mfma_f32_16x16x32_bf16 v[136:139], v[8:11], v[222:225], v[88:91]
	v_mfma_f32_16x16x32_bf16 v[128:131], v[72:75], v[222:225], v[92:95]
	v_mfma_f32_16x16x32_bf16 v[120:123], v[8:11], v[230:233], v[108:111]
	v_mfma_f32_16x16x32_bf16 v[112:115], v[72:75], v[230:233], v[104:107]
	v_mfma_f32_16x16x32_bf16 v[104:107], v[8:11], v[238:241], v[100:103]
	v_mfma_f32_16x16x32_bf16 v[96:99], v[72:75], v[238:241], v[96:99]
	s_setprio 0
	s_barrier
	ds_read_b128 v[88:91], v132
	ds_read_b128 v[80:83], v132 offset:1024
	ds_read_b128 v[92:95], v132 offset:2048
	ds_read_b128 v[84:87], v132 offset:3072
	s_waitcnt vmcnt(0)
	s_barrier
	s_waitcnt lgkmcnt(0)
	s_setprio 1
	s_waitcnt lgkmcnt(0)
	v_mfma_f32_16x16x32_bf16 v[100:103], v[88:91], v[140:143], v[156:159]
	v_mfma_f32_16x16x32_bf16 v[108:111], v[92:95], v[140:143], v[160:163]
	v_mfma_f32_16x16x32_bf16 v[116:119], v[88:91], v[218:221], v[194:197]
	v_mfma_f32_16x16x32_bf16 v[124:127], v[92:95], v[218:221], v[198:201]
	v_mfma_f32_16x16x32_bf16 v[160:163], v[88:91], v[226:229], v[202:205]
	v_mfma_f32_16x16x32_bf16 v[194:197], v[92:95], v[226:229], v[206:209]
	v_mfma_f32_16x16x32_bf16 v[198:201], v[88:91], v[234:237], v[210:213]
	v_mfma_f32_16x16x32_bf16 v[202:205], v[92:95], v[234:237], v[214:217]
	v_mfma_f32_16x16x32_bf16 v[156:159], v[80:83], v[148:151], v[100:103]
	v_mfma_f32_16x16x32_bf16 v[148:151], v[84:87], v[148:151], v[108:111]
	v_mfma_f32_16x16x32_bf16 v[140:143], v[80:83], v[222:225], v[116:119]
	v_mfma_f32_16x16x32_bf16 v[132:135], v[84:87], v[222:225], v[124:127]
	v_mfma_f32_16x16x32_bf16 v[124:127], v[80:83], v[230:233], v[160:163]
	v_mfma_f32_16x16x32_bf16 v[116:119], v[84:87], v[230:233], v[194:197]
	v_mfma_f32_16x16x32_bf16 v[108:111], v[80:83], v[238:241], v[198:201]
	v_mfma_f32_16x16x32_bf16 v[100:103], v[84:87], v[238:241], v[202:205]
	s_setprio 0
	s_lshl_b64 s[58:59], s[56:57], 2
	s_barrier
	v_mbcnt_lo_u32_b32 v162, -1, 0
	v_mbcnt_hi_u32_b32 v162, -1, v162
	s_add_u32 s58, s87, s58
	v_add_u32_e32 v160, s64, v162
	s_addc_u32 s59, s88, s59
	v_and_b32_e32 v164, 0x100, v160
	v_and_b32_e32 v162, 15, v162
	v_lshl_add_u64 v[160:161], s[58:59], 0, v[164:165]
	v_lshlrev_b32_e32 v164, 2, v162
	v_lshl_add_u64 v[160:161], v[160:161], 0, v[164:165]
	global_load_dword v180, v[160:161], off
	global_load_dword v178, v[160:161], off offset:64
	global_load_dword v176, v[160:161], off offset:128
	global_load_dword v174, v[160:161], off offset:192
	global_load_dword v172, v[160:161], off offset:512
	global_load_dword v170, v[160:161], off offset:576
	global_load_dword v168, v[160:161], off offset:640
	global_load_dword v166, v[160:161], off offset:704
	v_mbcnt_lo_u32_b32 v194, -1, 0
	v_mbcnt_hi_u32_b32 v194, -1, v194
	s_cmp_lg_u32 s81, 0
	v_add_u32_e32 v160, s64, v194
	v_bfe_u32 v196, v160, 8, 1
	v_ashrrev_i32_e32 v199, 6, v160
	v_bfe_u32 v160, v194, 4, 2
	s_cselect_b64 s[58:59], -1, 0
	v_and_b32_e32 v197, 3, v199
	v_and_b32_e32 v195, 15, v194
	s_and_b64 vcc, exec, s[58:59]
	v_lshlrev_b32_e32 v198, 4, v160
	s_cbranch_vccz .LBB0_246
	s_lshl_b32 s14, s80, 22
	s_lshl_b32 s57, s82, 14
	s_add_i32 s57, s57, s14
	v_lshlrev_b32_e32 v160, 6, v195
	v_or3_b32 v160, s57, v160, v198
	v_lshl_add_u32 v160, v197, 20, v160
	v_lshl_or_b32 v164, v196, 12, v160
	s_waitcnt vmcnt(0)
	v_pk_mul_f32 v[160:161], v[154:155], v[180:181] op_sel_hi:[1,0]
	v_pk_mul_f32 v[200:201], v[146:147], v[180:181] op_sel_hi:[1,0]
	v_max_f32_e32 v160, 0, v160
	v_mul_f32_e32 v204, v160, v160
	v_max_f32_e32 v160, 0, v200
	v_pk_mul_f32 v[162:163], v[152:153], v[180:181] op_sel_hi:[1,0]
	v_mul_f32_e32 v200, v160, v160
	v_max_f32_e32 v160, 0, v161
	v_pk_mul_f32 v[202:203], v[144:145], v[180:181] op_sel_hi:[1,0]
	v_max_f32_e32 v162, 0, v162
	v_max_f32_e32 v163, 0, v163
	v_mul_f32_e32 v161, v160, v160
	v_max_f32_e32 v160, 0, v201
	v_mul_f32_e32 v162, v162, v162
	v_max_f32_e32 v202, 0, v202
	v_mul_f32_e32 v163, v163, v163
	v_max_f32_e32 v203, 0, v203
	v_mul_f32_e32 v201, v160, v160
	v_cvt_pk_bf16_f32 v160, v162, v163
	v_cvt_pk_bf16_f32 v161, v204, v161
	v_mul_f32_e32 v202, v202, v202
	v_mul_f32_e32 v203, v203, v203
	v_cvt_pk_bf16_f32 v162, v202, v203
	v_cvt_pk_bf16_f32 v163, v200, v201
	global_store_dwordx4 v164, v[160:163], s[0:1]
	v_pk_mul_f32 v[202:203], v[150:151], v[180:181] op_sel_hi:[1,0]
	v_lshl_add_u64 v[200:201], s[0:1], 0, v[164:165]
	v_pk_mul_f32 v[160:161], v[158:159], v[180:181] op_sel_hi:[1,0]
	v_pk_mul_f32 v[162:163], v[156:157], v[180:181] op_sel_hi:[1,0]
	v_max_f32_e32 v160, 0, v160
	v_mul_f32_e32 v206, v160, v160
	v_max_f32_e32 v160, 0, v202
	v_mul_f32_e32 v202, v160, v160
	v_max_f32_e32 v160, 0, v161
	v_pk_mul_f32 v[204:205], v[148:149], v[180:181] op_sel_hi:[1,0]
	v_max_f32_e32 v162, 0, v162
	v_max_f32_e32 v163, 0, v163
	v_mul_f32_e32 v161, v160, v160
	v_max_f32_e32 v160, 0, v203
	v_add_co_u32_e32 v200, vcc, s74, v200
	v_mul_f32_e32 v162, v162, v162
	v_max_f32_e32 v204, 0, v204
	v_mul_f32_e32 v163, v163, v163
	v_max_f32_e32 v205, 0, v205
	v_mul_f32_e32 v203, v160, v160
	v_cvt_pk_bf16_f32 v160, v162, v163
	v_cvt_pk_bf16_f32 v161, v206, v161
	v_addc_co_u32_e32 v201, vcc, 0, v201, vcc
	v_mul_f32_e32 v204, v204, v204
	v_mul_f32_e32 v205, v205, v205
	v_cvt_pk_bf16_f32 v162, v204, v205
	v_cvt_pk_bf16_f32 v163, v202, v203
	global_store_dwordx4 v[200:201], v[160:163], off
	v_pk_mul_f32 v[202:203], v[130:131], v[178:179] op_sel_hi:[1,0]
	v_pk_mul_f32 v[204:205], v[128:129], v[178:179] op_sel_hi:[1,0]
	v_pk_mul_f32 v[160:161], v[138:139], v[178:179] op_sel_hi:[1,0]
	v_pk_mul_f32 v[162:163], v[136:137], v[178:179] op_sel_hi:[1,0]
	v_max_f32_e32 v160, 0, v160
	v_mul_f32_e32 v206, v160, v160
	v_max_f32_e32 v160, 0, v202
	v_mul_f32_e32 v202, v160, v160
	v_max_f32_e32 v160, 0, v161
	v_max_f32_e32 v162, 0, v162
	v_max_f32_e32 v163, 0, v163
	v_mul_f32_e32 v161, v160, v160
	v_max_f32_e32 v160, 0, v203
	v_mul_f32_e32 v162, v162, v162
	v_max_f32_e32 v204, 0, v204
	v_mul_f32_e32 v163, v163, v163
	v_max_f32_e32 v205, 0, v205
	v_mul_f32_e32 v203, v160, v160
	v_cvt_pk_bf16_f32 v160, v162, v163
	v_cvt_pk_bf16_f32 v161, v206, v161
	v_mul_f32_e32 v204, v204, v204
	v_mul_f32_e32 v205, v205, v205
	v_cvt_pk_bf16_f32 v162, v204, v205
	v_cvt_pk_bf16_f32 v163, v202, v203
	global_store_dwordx4 v164, v[160:163], s[0:1] offset:1024
	v_pk_mul_f32 v[202:203], v[134:135], v[178:179] op_sel_hi:[1,0]
	v_pk_mul_f32 v[204:205], v[132:133], v[178:179] op_sel_hi:[1,0]
	v_pk_mul_f32 v[160:161], v[142:143], v[178:179] op_sel_hi:[1,0]
	v_pk_mul_f32 v[162:163], v[140:141], v[178:179] op_sel_hi:[1,0]
	v_max_f32_e32 v160, 0, v160
	v_mul_f32_e32 v206, v160, v160
	v_max_f32_e32 v160, 0, v202
	v_mul_f32_e32 v202, v160, v160
	v_max_f32_e32 v160, 0, v161
	v_max_f32_e32 v162, 0, v162
	v_max_f32_e32 v163, 0, v163
	v_mul_f32_e32 v161, v160, v160
	v_max_f32_e32 v160, 0, v203
	v_mul_f32_e32 v162, v162, v162
	v_max_f32_e32 v204, 0, v204
	v_mul_f32_e32 v163, v163, v163
	v_max_f32_e32 v205, 0, v205
	v_mul_f32_e32 v203, v160, v160
	v_cvt_pk_bf16_f32 v160, v162, v163
	v_cvt_pk_bf16_f32 v161, v206, v161
	v_mul_f32_e32 v204, v204, v204
	v_mul_f32_e32 v205, v205, v205
	v_cvt_pk_bf16_f32 v162, v204, v205
	v_cvt_pk_bf16_f32 v163, v202, v203
	global_store_dwordx4 v[200:201], v[160:163], off offset:1024
	v_pk_mul_f32 v[202:203], v[114:115], v[176:177] op_sel_hi:[1,0]
	v_pk_mul_f32 v[204:205], v[112:113], v[176:177] op_sel_hi:[1,0]
	v_pk_mul_f32 v[160:161], v[122:123], v[176:177] op_sel_hi:[1,0]
	v_pk_mul_f32 v[162:163], v[120:121], v[176:177] op_sel_hi:[1,0]
	v_max_f32_e32 v160, 0, v160
	v_mul_f32_e32 v206, v160, v160
	v_max_f32_e32 v160, 0, v202
	v_mul_f32_e32 v202, v160, v160
	v_max_f32_e32 v160, 0, v161
	v_max_f32_e32 v162, 0, v162
	v_max_f32_e32 v163, 0, v163
	v_mul_f32_e32 v161, v160, v160
	v_max_f32_e32 v160, 0, v203
	v_mul_f32_e32 v162, v162, v162
	v_max_f32_e32 v204, 0, v204
	v_mul_f32_e32 v163, v163, v163
	v_max_f32_e32 v205, 0, v205
	v_mul_f32_e32 v203, v160, v160
	v_cvt_pk_bf16_f32 v160, v162, v163
	v_cvt_pk_bf16_f32 v161, v206, v161
	v_mul_f32_e32 v204, v204, v204
	v_mul_f32_e32 v205, v205, v205
	v_cvt_pk_bf16_f32 v162, v204, v205
	v_cvt_pk_bf16_f32 v163, v202, v203
	global_store_dwordx4 v164, v[160:163], s[0:1] offset:2048
	v_pk_mul_f32 v[202:203], v[118:119], v[176:177] op_sel_hi:[1,0]
	v_pk_mul_f32 v[204:205], v[116:117], v[176:177] op_sel_hi:[1,0]
	v_pk_mul_f32 v[160:161], v[126:127], v[176:177] op_sel_hi:[1,0]
	v_pk_mul_f32 v[162:163], v[124:125], v[176:177] op_sel_hi:[1,0]
	v_max_f32_e32 v160, 0, v160
	v_mul_f32_e32 v206, v160, v160
	v_max_f32_e32 v160, 0, v202
	v_mul_f32_e32 v202, v160, v160
	v_max_f32_e32 v160, 0, v161
	v_max_f32_e32 v162, 0, v162
	v_max_f32_e32 v163, 0, v163
	v_mul_f32_e32 v161, v160, v160
	v_max_f32_e32 v160, 0, v203
	v_mul_f32_e32 v162, v162, v162
	v_max_f32_e32 v204, 0, v204
	v_mul_f32_e32 v163, v163, v163
	v_max_f32_e32 v205, 0, v205
	v_mul_f32_e32 v203, v160, v160
	v_cvt_pk_bf16_f32 v160, v162, v163
	v_cvt_pk_bf16_f32 v161, v206, v161
	v_mul_f32_e32 v204, v204, v204
	v_mul_f32_e32 v205, v205, v205
	v_cvt_pk_bf16_f32 v162, v204, v205
	v_cvt_pk_bf16_f32 v163, v202, v203
	global_store_dwordx4 v[200:201], v[160:163], off offset:2048
	v_pk_mul_f32 v[200:201], v[98:99], v[174:175] op_sel_hi:[1,0]
	v_pk_mul_f32 v[202:203], v[96:97], v[174:175] op_sel_hi:[1,0]
	v_pk_mul_f32 v[160:161], v[106:107], v[174:175] op_sel_hi:[1,0]
	v_pk_mul_f32 v[162:163], v[104:105], v[174:175] op_sel_hi:[1,0]
	v_max_f32_e32 v160, 0, v160
	v_mul_f32_e32 v204, v160, v160
	v_max_f32_e32 v160, 0, v200
	v_mul_f32_e32 v200, v160, v160
	v_max_f32_e32 v160, 0, v161
	v_max_f32_e32 v162, 0, v162
	v_max_f32_e32 v163, 0, v163
	v_mul_f32_e32 v161, v160, v160
	v_max_f32_e32 v160, 0, v201
	v_mul_f32_e32 v162, v162, v162
	v_max_f32_e32 v202, 0, v202
	v_mul_f32_e32 v163, v163, v163
	v_max_f32_e32 v203, 0, v203
	v_mul_f32_e32 v201, v160, v160
	v_cvt_pk_bf16_f32 v160, v162, v163
	v_cvt_pk_bf16_f32 v161, v204, v161
	v_mul_f32_e32 v202, v202, v202
	v_mul_f32_e32 v203, v203, v203
	v_cvt_pk_bf16_f32 v162, v202, v203
	v_cvt_pk_bf16_f32 v163, v200, v201
	global_store_dwordx4 v164, v[160:163], s[0:1] offset:3072
	v_pk_mul_f32 v[200:201], v[102:103], v[174:175] op_sel_hi:[1,0]
	v_pk_mul_f32 v[202:203], v[100:101], v[174:175] op_sel_hi:[1,0]
	v_pk_mul_f32 v[160:161], v[110:111], v[174:175] op_sel_hi:[1,0]
	v_pk_mul_f32 v[162:163], v[108:109], v[174:175] op_sel_hi:[1,0]
	v_max_f32_e32 v160, 0, v160
	v_mul_f32_e32 v204, v160, v160
	v_max_f32_e32 v160, 0, v200
	v_max_f32_e32 v162, 0, v162
	v_max_f32_e32 v163, 0, v163
	v_mul_f32_e32 v200, v160, v160
	v_max_f32_e32 v160, 0, v161
	v_mul_f32_e32 v162, v162, v162
	v_max_f32_e32 v202, 0, v202
	v_mul_f32_e32 v163, v163, v163
	v_max_f32_e32 v203, 0, v203
	v_mul_f32_e32 v161, v160, v160
	v_max_f32_e32 v160, 0, v201
	v_mul_f32_e32 v202, v202, v202
	v_mul_f32_e32 v203, v203, v203
	v_mul_f32_e32 v201, v160, v160
	v_cvt_pk_bf16_f32 v160, v162, v163
	v_cvt_pk_bf16_f32 v161, v204, v161
	v_cvt_pk_bf16_f32 v162, v202, v203
	v_cvt_pk_bf16_f32 v163, v200, v201
	v_add_u32_e32 v164, 0x80c00, v164
	s_cbranch_execnz .LBB0_238

.LBB0_274:
	ds_read_b128 v[162:165], v161
	ds_read_b128 v[166:169], v161 offset:1024
	ds_read_b128 v[170:173], v161 offset:2048
	ds_read_b128 v[174:177], v161 offset:3072
	ds_read_b128 v[178:181], v152
	ds_read_b128 v[182:185], v152 offset:1024
	ds_read_b128 v[186:189], v151
	ds_read_b128 v[190:193], v151 offset:1024
	ds_read_b128 v[194:197], v150
	ds_read_b128 v[198:201], v150 offset:1024
	ds_read_b128 v[202:205], v149
	ds_read_b128 v[206:209], v149 offset:1024
	s_waitcnt lgkmcnt(8)
	s_waitcnt vmcnt(10)
	s_barrier
	s_waitcnt lgkmcnt(0)
	s_waitcnt lgkmcnt(0)
	v_mfma_f32_16x16x32_bf16 v[124:127], v[162:165], v[178:181], v[124:127]
	v_mfma_f32_16x16x32_bf16 v[120:123], v[170:173], v[178:181], v[120:123]
	v_mfma_f32_16x16x32_bf16 v[116:119], v[162:165], v[186:189], v[116:119]
	v_mfma_f32_16x16x32_bf16 v[112:115], v[170:173], v[186:189], v[112:115]
	v_mfma_f32_16x16x32_bf16 v[108:111], v[162:165], v[194:197], v[108:111]
	v_mfma_f32_16x16x32_bf16 v[104:107], v[170:173], v[194:197], v[104:107]
	v_mfma_f32_16x16x32_bf16 v[100:103], v[162:165], v[202:205], v[100:103]
	v_mfma_f32_16x16x32_bf16 v[96:99], v[170:173], v[202:205], v[96:99]
	v_mfma_f32_16x16x32_bf16 v[124:127], v[166:169], v[182:185], v[124:127]
	v_mfma_f32_16x16x32_bf16 v[120:123], v[174:177], v[182:185], v[120:123]
	v_mfma_f32_16x16x32_bf16 v[116:119], v[166:169], v[190:193], v[116:119]
	v_mfma_f32_16x16x32_bf16 v[112:115], v[174:177], v[190:193], v[112:115]
	v_mfma_f32_16x16x32_bf16 v[108:111], v[166:169], v[198:201], v[108:111]
	v_mfma_f32_16x16x32_bf16 v[104:107], v[174:177], v[198:201], v[104:107]
	v_mfma_f32_16x16x32_bf16 v[100:103], v[166:169], v[206:209], v[100:103]
	v_mfma_f32_16x16x32_bf16 v[96:99], v[174:177], v[206:209], v[96:99]
	s_barrier
	s_mov_b32 vcc_lo, 0xfffbd000
	s_mov_b32 vcc_hi, -1
	v_readfirstlane_b32 s67, v148
	v_lshl_add_u64 v[226:227], v[130:131], 0, vcc
	s_mov_b32 m0, s67
	v_readfirstlane_b32 s67, v147
	ds_read_b128 v[210:213], v158
	ds_read_b128 v[214:217], v158 offset:1024
	ds_read_b128 v[218:221], v158 offset:2048
	ds_read_b128 v[222:225], v158 offset:3072
	global_load_lds_dwordx4 v[226:227], off
	v_lshl_add_u64 v[226:227], v[130:131], 0, s[22:23]
	s_mov_b32 m0, s67
	s_add_i32 s66, s66, 2
	global_load_lds_dwordx4 v[226:227], off
	v_readfirstlane_b32 s67, v134
	v_lshl_add_u64 v[226:227], v[132:133], 0, s[24:25]
	s_mov_b32 m0, s67
	v_readfirstlane_b32 s67, v146
	global_load_lds_dwordx4 v[226:227], off
	v_lshl_add_u64 v[226:227], v[132:133], 0, s[26:27]
	s_mov_b32 m0, s67
	s_nop 0
	global_load_lds_dwordx4 v[226:227], off
	s_waitcnt vmcnt(12)
	s_barrier
	s_waitcnt lgkmcnt(0)
	s_waitcnt lgkmcnt(0)
	v_mfma_f32_16x16x32_bf16 v[92:95], v[210:213], v[178:181], v[92:95]
	v_mfma_f32_16x16x32_bf16 v[88:91], v[218:221], v[178:181], v[88:91]
	v_mfma_f32_16x16x32_bf16 v[84:87], v[210:213], v[186:189], v[84:87]
	v_mfma_f32_16x16x32_bf16 v[80:83], v[218:221], v[186:189], v[80:83]
	v_mfma_f32_16x16x32_bf16 v[76:79], v[210:213], v[194:197], v[76:79]
	v_mfma_f32_16x16x32_bf16 v[72:75], v[218:221], v[194:197], v[72:75]
	v_mfma_f32_16x16x32_bf16 v[68:71], v[210:213], v[202:205], v[68:71]
	v_mfma_f32_16x16x32_bf16 v[64:67], v[218:221], v[202:205], v[64:67]
	v_mfma_f32_16x16x32_bf16 v[92:95], v[214:217], v[182:185], v[92:95]
	v_mfma_f32_16x16x32_bf16 v[88:91], v[222:225], v[182:185], v[88:91]
	v_mfma_f32_16x16x32_bf16 v[84:87], v[214:217], v[190:193], v[84:87]
	v_mfma_f32_16x16x32_bf16 v[80:83], v[222:225], v[190:193], v[80:83]
	v_mfma_f32_16x16x32_bf16 v[76:79], v[214:217], v[198:201], v[76:79]
	v_mfma_f32_16x16x32_bf16 v[72:75], v[222:225], v[198:201], v[72:75]
	v_mfma_f32_16x16x32_bf16 v[68:71], v[214:217], v[206:209], v[68:71]
	v_mfma_f32_16x16x32_bf16 v[64:67], v[222:225], v[206:209], v[64:67]
	s_barrier
	ds_read_b128 v[178:181], v152 offset:16384
	ds_read_b128 v[182:185], v152 offset:17408
	ds_read_b128 v[186:189], v151 offset:16384
	ds_read_b128 v[190:193], v151 offset:17408
	ds_read_b128 v[194:197], v150 offset:16384
	ds_read_b128 v[198:201], v150 offset:17408
	ds_read_b128 v[202:205], v149 offset:16384
	ds_read_b128 v[206:209], v149 offset:17408
	v_readfirstlane_b32 s67, v145
	v_lshl_add_u64 v[226:227], v[130:131], 0, s[28:29]
	s_mov_b32 m0, s67
	v_readfirstlane_b32 s67, v144
	global_load_lds_dwordx4 v[226:227], off
	v_lshl_add_u64 v[226:227], v[130:131], 0, s[30:31]
	s_mov_b32 m0, s67
	s_nop 0
	global_load_lds_dwordx4 v[226:227], off
	s_barrier
	s_waitcnt lgkmcnt(0)
	s_waitcnt lgkmcnt(0)
	v_mfma_f32_16x16x32_bf16 v[60:63], v[162:165], v[178:181], v[60:63]
	v_mfma_f32_16x16x32_bf16 v[56:59], v[170:173], v[178:181], v[56:59]
	v_mfma_f32_16x16x32_bf16 v[52:55], v[162:165], v[186:189], v[52:55]
	v_mfma_f32_16x16x32_bf16 v[48:51], v[170:173], v[186:189], v[48:51]
	v_mfma_f32_16x16x32_bf16 v[44:47], v[162:165], v[194:197], v[44:47]
	v_mfma_f32_16x16x32_bf16 v[40:43], v[170:173], v[194:197], v[40:43]
	v_mfma_f32_16x16x32_bf16 v[36:39], v[162:165], v[202:205], v[36:39]
	v_mfma_f32_16x16x32_bf16 v[32:35], v[170:173], v[202:205], v[32:35]
	v_mfma_f32_16x16x32_bf16 v[60:63], v[166:169], v[182:185], v[60:63]
	v_mfma_f32_16x16x32_bf16 v[56:59], v[174:177], v[182:185], v[56:59]
	v_mfma_f32_16x16x32_bf16 v[52:55], v[166:169], v[190:193], v[52:55]
	v_mfma_f32_16x16x32_bf16 v[48:51], v[174:177], v[190:193], v[48:51]
	v_mfma_f32_16x16x32_bf16 v[44:47], v[166:169], v[198:201], v[44:47]
	v_mfma_f32_16x16x32_bf16 v[40:43], v[174:177], v[198:201], v[40:43]
	v_mfma_f32_16x16x32_bf16 v[36:39], v[166:169], v[206:209], v[36:39]
	v_mfma_f32_16x16x32_bf16 v[32:35], v[174:177], v[206:209], v[32:35]
	s_barrier
	v_readfirstlane_b32 s67, v143
	v_lshl_add_u64 v[164:165], v[132:133], 0, s[34:35]
	s_mov_b32 m0, s67
	v_readfirstlane_b32 s67, v142
	global_load_lds_dwordx4 v[164:165], off
	v_lshl_add_u64 v[164:165], v[132:133], 0, s[44:45]
	s_mov_b32 m0, s67
	s_nop 0
	global_load_lds_dwordx4 v[164:165], off
	s_waitcnt vmcnt(12)
	s_barrier
	v_mfma_f32_16x16x32_bf16 v[28:31], v[210:213], v[178:181], v[28:31]
	v_mfma_f32_16x16x32_bf16 v[24:27], v[218:221], v[178:181], v[24:27]
	v_mfma_f32_16x16x32_bf16 v[20:23], v[210:213], v[186:189], v[20:23]
	v_mfma_f32_16x16x32_bf16 v[16:19], v[218:221], v[186:189], v[16:19]
	v_mfma_f32_16x16x32_bf16 v[12:15], v[210:213], v[194:197], v[12:15]
	v_mfma_f32_16x16x32_bf16 v[8:11], v[218:221], v[194:197], v[8:11]
	v_mfma_f32_16x16x32_bf16 v[4:7], v[210:213], v[202:205], v[4:7]
	v_mfma_f32_16x16x32_bf16 v[0:3], v[218:221], v[202:205], v[0:3]
	v_mfma_f32_16x16x32_bf16 v[28:31], v[214:217], v[182:185], v[28:31]
	v_mfma_f32_16x16x32_bf16 v[24:27], v[222:225], v[182:185], v[24:27]
	v_mfma_f32_16x16x32_bf16 v[20:23], v[214:217], v[190:193], v[20:23]
	v_mfma_f32_16x16x32_bf16 v[16:19], v[222:225], v[190:193], v[16:19]
	v_mfma_f32_16x16x32_bf16 v[12:15], v[214:217], v[198:201], v[12:15]
	v_mfma_f32_16x16x32_bf16 v[8:11], v[222:225], v[198:201], v[8:11]
	v_mfma_f32_16x16x32_bf16 v[4:7], v[214:217], v[206:209], v[4:7]
	v_mfma_f32_16x16x32_bf16 v[0:3], v[222:225], v[206:209], v[0:3]
	s_barrier
	ds_read_b128 v[162:165], v154
	ds_read_b128 v[166:169], v154 offset:1024
	ds_read_b128 v[170:173], v154 offset:2048
	ds_read_b128 v[174:177], v154 offset:3072
	ds_read_b128 v[178:181], v152 offset:32768
	ds_read_b128 v[182:185], v152 offset:33792
	ds_read_b128 v[186:189], v151 offset:32768
	ds_read_b128 v[190:193], v151 offset:33792
	ds_read_b128 v[194:197], v150 offset:32768
	ds_read_b128 v[198:201], v150 offset:33792
	ds_read_b128 v[202:205], v149 offset:32768
	ds_read_b128 v[206:209], v149 offset:33792
	s_waitcnt lgkmcnt(8)
	s_waitcnt vmcnt(10)
	s_barrier
	s_waitcnt lgkmcnt(0)
	s_waitcnt lgkmcnt(0)
	v_mfma_f32_16x16x32_bf16 v[124:127], v[162:165], v[178:181], v[124:127]
	v_mfma_f32_16x16x32_bf16 v[120:123], v[170:173], v[178:181], v[120:123]
	v_mfma_f32_16x16x32_bf16 v[116:119], v[162:165], v[186:189], v[116:119]
	v_mfma_f32_16x16x32_bf16 v[112:115], v[170:173], v[186:189], v[112:115]
	v_mfma_f32_16x16x32_bf16 v[108:111], v[162:165], v[194:197], v[108:111]
	v_mfma_f32_16x16x32_bf16 v[104:107], v[170:173], v[194:197], v[104:107]
	v_mfma_f32_16x16x32_bf16 v[100:103], v[162:165], v[202:205], v[100:103]
	v_mfma_f32_16x16x32_bf16 v[96:99], v[170:173], v[202:205], v[96:99]
	v_mfma_f32_16x16x32_bf16 v[124:127], v[166:169], v[182:185], v[124:127]
	v_mfma_f32_16x16x32_bf16 v[120:123], v[174:177], v[182:185], v[120:123]
	v_mfma_f32_16x16x32_bf16 v[116:119], v[166:169], v[190:193], v[116:119]
	v_mfma_f32_16x16x32_bf16 v[112:115], v[174:177], v[190:193], v[112:115]
	v_mfma_f32_16x16x32_bf16 v[108:111], v[166:169], v[198:201], v[108:111]
	v_mfma_f32_16x16x32_bf16 v[104:107], v[174:177], v[198:201], v[104:107]
	v_mfma_f32_16x16x32_bf16 v[100:103], v[166:169], v[206:209], v[100:103]
	v_mfma_f32_16x16x32_bf16 v[96:99], v[174:177], v[206:209], v[96:99]
	s_barrier
	v_readfirstlane_b32 s67, v141
	v_lshl_add_u64 v[226:227], v[130:131], 0, s[46:47]
	s_mov_b32 m0, s67
	v_readfirstlane_b32 s67, v140
	ds_read_b128 v[210:213], v153
	ds_read_b128 v[214:217], v153 offset:1024
	ds_read_b128 v[218:221], v153 offset:2048
	ds_read_b128 v[222:225], v153 offset:3072
	global_load_lds_dwordx4 v[226:227], off
	v_lshl_add_u64 v[226:227], v[130:131], 0, s[56:57]
	s_mov_b32 m0, s67
	s_nop 0
	global_load_lds_dwordx4 v[226:227], off
	v_readfirstlane_b32 s67, v139
	v_lshl_add_u64 v[226:227], v[132:133], 0, s[58:59]
	s_mov_b32 m0, s67
	v_readfirstlane_b32 s67, v138
	global_load_lds_dwordx4 v[226:227], off
	s_mov_b32 m0, s67
	s_nop 0
	global_load_lds_dwordx4 v[132:133], off
	s_waitcnt vmcnt(12)
	s_barrier
	s_waitcnt lgkmcnt(0)
	s_waitcnt lgkmcnt(0)
	v_mfma_f32_16x16x32_bf16 v[92:95], v[210:213], v[178:181], v[92:95]
	v_mfma_f32_16x16x32_bf16 v[88:91], v[218:221], v[178:181], v[88:91]
	v_mfma_f32_16x16x32_bf16 v[84:87], v[210:213], v[186:189], v[84:87]
	v_mfma_f32_16x16x32_bf16 v[80:83], v[218:221], v[186:189], v[80:83]
	v_mfma_f32_16x16x32_bf16 v[76:79], v[210:213], v[194:197], v[76:79]
	v_mfma_f32_16x16x32_bf16 v[72:75], v[218:221], v[194:197], v[72:75]
	v_mfma_f32_16x16x32_bf16 v[68:71], v[210:213], v[202:205], v[68:71]
	v_mfma_f32_16x16x32_bf16 v[64:67], v[218:221], v[202:205], v[64:67]
	v_mfma_f32_16x16x32_bf16 v[92:95], v[214:217], v[182:185], v[92:95]
	v_mfma_f32_16x16x32_bf16 v[88:91], v[222:225], v[182:185], v[88:91]
	v_mfma_f32_16x16x32_bf16 v[84:87], v[214:217], v[190:193], v[84:87]
	v_mfma_f32_16x16x32_bf16 v[80:83], v[222:225], v[190:193], v[80:83]
	v_mfma_f32_16x16x32_bf16 v[76:79], v[214:217], v[198:201], v[76:79]
	v_mfma_f32_16x16x32_bf16 v[72:75], v[222:225], v[198:201], v[72:75]
	v_mfma_f32_16x16x32_bf16 v[68:71], v[214:217], v[206:209], v[68:71]
	v_mfma_f32_16x16x32_bf16 v[64:67], v[222:225], v[206:209], v[64:67]
	s_barrier
	ds_read_b128 v[178:181], v152 offset:49152
	ds_read_b128 v[182:185], v152 offset:50176
	ds_read_b128 v[186:189], v151 offset:49152
	ds_read_b128 v[190:193], v151 offset:50176
	ds_read_b128 v[194:197], v150 offset:49152
	ds_read_b128 v[198:201], v150 offset:50176
	ds_read_b128 v[202:205], v149 offset:49152
	ds_read_b128 v[206:209], v149 offset:50176
	v_readfirstlane_b32 s67, v137
	v_lshl_add_u64 v[226:227], v[130:131], 0, s[58:59]
	s_mov_b32 m0, s67
	v_readfirstlane_b32 s67, v136
	global_load_lds_dwordx4 v[226:227], off
	s_mov_b32 m0, s67
	s_nop 0
	global_load_lds_dwordx4 v[130:131], off
	s_barrier
	s_waitcnt lgkmcnt(0)
	s_waitcnt lgkmcnt(0)
	v_mfma_f32_16x16x32_bf16 v[60:63], v[162:165], v[178:181], v[60:63]
	v_mfma_f32_16x16x32_bf16 v[56:59], v[170:173], v[178:181], v[56:59]
	v_mfma_f32_16x16x32_bf16 v[52:55], v[162:165], v[186:189], v[52:55]
	v_mfma_f32_16x16x32_bf16 v[48:51], v[170:173], v[186:189], v[48:51]
	v_mfma_f32_16x16x32_bf16 v[44:47], v[162:165], v[194:197], v[44:47]
	v_mfma_f32_16x16x32_bf16 v[40:43], v[170:173], v[194:197], v[40:43]
	v_mfma_f32_16x16x32_bf16 v[36:39], v[162:165], v[202:205], v[36:39]
	v_mfma_f32_16x16x32_bf16 v[32:35], v[170:173], v[202:205], v[32:35]
	v_mfma_f32_16x16x32_bf16 v[60:63], v[166:169], v[182:185], v[60:63]
	v_mfma_f32_16x16x32_bf16 v[56:59], v[174:177], v[182:185], v[56:59]
	v_mfma_f32_16x16x32_bf16 v[52:55], v[166:169], v[190:193], v[52:55]
	v_mfma_f32_16x16x32_bf16 v[48:51], v[174:177], v[190:193], v[48:51]
	v_mfma_f32_16x16x32_bf16 v[44:47], v[166:169], v[198:201], v[44:47]
	v_mfma_f32_16x16x32_bf16 v[40:43], v[174:177], v[198:201], v[40:43]
	v_mfma_f32_16x16x32_bf16 v[36:39], v[166:169], v[206:209], v[36:39]
	v_mfma_f32_16x16x32_bf16 v[32:35], v[174:177], v[206:209], v[32:35]
	s_barrier
	v_lshl_add_u64 v[132:133], v[132:133], 0, s[62:63]
	s_mov_b32 vcc_lo, 0xffe01000
	s_mov_b32 vcc_hi, -1
	v_lshl_add_u64 v[164:165], v[132:133], 0, vcc
	v_readfirstlane_b32 s67, v160
	s_mov_b32 vcc_lo, 0xffe02000
	s_mov_b32 m0, s67
	s_mov_b32 vcc_hi, -1
	v_readfirstlane_b32 s67, v159
	global_load_lds_dwordx4 v[164:165], off
	v_lshl_add_u64 v[164:165], v[132:133], 0, vcc
	s_mov_b32 m0, s67
	s_nop 0
	global_load_lds_dwordx4 v[164:165], off
	s_waitcnt vmcnt(12)
	s_barrier
	v_mfma_f32_16x16x32_bf16 v[28:31], v[210:213], v[178:181], v[28:31]
	v_mfma_f32_16x16x32_bf16 v[24:27], v[218:221], v[178:181], v[24:27]
	v_mfma_f32_16x16x32_bf16 v[20:23], v[210:213], v[186:189], v[20:23]
	v_mfma_f32_16x16x32_bf16 v[16:19], v[218:221], v[186:189], v[16:19]
	v_mfma_f32_16x16x32_bf16 v[12:15], v[210:213], v[194:197], v[12:15]
	v_mfma_f32_16x16x32_bf16 v[8:11], v[218:221], v[194:197], v[8:11]
	v_mfma_f32_16x16x32_bf16 v[4:7], v[210:213], v[202:205], v[4:7]
	v_mfma_f32_16x16x32_bf16 v[0:3], v[218:221], v[202:205], v[0:3]
	v_mfma_f32_16x16x32_bf16 v[28:31], v[214:217], v[182:185], v[28:31]
	v_mfma_f32_16x16x32_bf16 v[24:27], v[222:225], v[182:185], v[24:27]
	v_mfma_f32_16x16x32_bf16 v[20:23], v[214:217], v[190:193], v[20:23]
	v_mfma_f32_16x16x32_bf16 v[16:19], v[222:225], v[190:193], v[16:19]
	v_mfma_f32_16x16x32_bf16 v[12:15], v[214:217], v[198:201], v[12:15]
	v_mfma_f32_16x16x32_bf16 v[8:11], v[222:225], v[198:201], v[8:11]
	v_mfma_f32_16x16x32_bf16 v[4:7], v[214:217], v[206:209], v[4:7]
	v_mfma_f32_16x16x32_bf16 v[0:3], v[222:225], v[206:209], v[0:3]
	v_lshl_add_u64 v[130:131], v[130:131], 0, s[60:61]
	s_cmp_lt_u32 s66, s65
	s_barrier
	s_cbranch_scc1 .LBB0_274
	s_lshl_b32 s65, s86, 5
	s_lshl_b32 s66, s86, 8
	s_and_b32 s65, s65, 0x1800
	s_and_b32 s66, s66, 0x700
	s_or_b32 s97, s66, s65
	s_lshl_b32 s65, s97, 6
	s_add_u32 s65, s68, s65
	s_addc_u32 s86, s69, 0
	s_add_i32 s20, s20, -1
	s_lshl_b64 s[66:67], s[20:21], 20
	v_add_u32_e32 v128, v156, v157
	s_add_u32 s66, s65, s66
	v_or_b32_e32 v128, v128, v155
	s_addc_u32 s67, s86, s67
	v_lshl_add_u64 v[156:157], s[66:67], 0, v[128:129]
	v_readfirstlane_b32 s20, v160
	v_lshl_add_u64 v[206:207], v[156:157], 0, s[4:5]
	s_mov_b32 m0, s20
	v_readfirstlane_b32 s20, v159
	ds_read_b128 v[130:133], v161
	ds_read_b128 v[162:165], v161 offset:1024
	ds_read_b128 v[166:169], v161 offset:2048
	ds_read_b128 v[170:173], v161 offset:3072
	ds_read_b128 v[174:177], v152
	ds_read_b128 v[178:181], v152 offset:1024
	ds_read_b128 v[182:185], v151
	ds_read_b128 v[186:189], v151 offset:1024
	ds_read_b128 v[190:193], v150
	ds_read_b128 v[194:197], v150 offset:1024
	ds_read_b128 v[198:201], v149
	ds_read_b128 v[202:205], v149 offset:1024
	global_load_lds_dwordx4 v[206:207], off
	v_lshl_add_u64 v[156:157], v[156:157], 0, s[6:7]
	s_mov_b32 m0, s20
	s_nop 0
	global_load_lds_dwordx4 v[156:157], off
	s_waitcnt vmcnt(10)
	s_barrier
	s_waitcnt lgkmcnt(0)
	s_setprio 1
	s_waitcnt lgkmcnt(0)
	v_mfma_f32_16x16x32_bf16 v[124:127], v[130:133], v[174:177], v[124:127]
	v_mfma_f32_16x16x32_bf16 v[120:123], v[166:169], v[174:177], v[120:123]
	v_mfma_f32_16x16x32_bf16 v[116:119], v[130:133], v[182:185], v[116:119]
	v_mfma_f32_16x16x32_bf16 v[112:115], v[166:169], v[182:185], v[112:115]
	v_mfma_f32_16x16x32_bf16 v[108:111], v[130:133], v[190:193], v[108:111]
	v_mfma_f32_16x16x32_bf16 v[104:107], v[166:169], v[190:193], v[104:107]
	v_mfma_f32_16x16x32_bf16 v[100:103], v[130:133], v[198:201], v[100:103]
	v_mfma_f32_16x16x32_bf16 v[96:99], v[166:169], v[198:201], v[96:99]
	v_mfma_f32_16x16x32_bf16 v[124:127], v[162:165], v[178:181], v[124:127]
	v_mfma_f32_16x16x32_bf16 v[120:123], v[170:173], v[178:181], v[120:123]
	v_mfma_f32_16x16x32_bf16 v[116:119], v[162:165], v[186:189], v[116:119]
	v_mfma_f32_16x16x32_bf16 v[112:115], v[170:173], v[186:189], v[112:115]
	v_mfma_f32_16x16x32_bf16 v[108:111], v[162:165], v[194:197], v[108:111]
	v_mfma_f32_16x16x32_bf16 v[104:107], v[170:173], v[194:197], v[104:107]
	v_mfma_f32_16x16x32_bf16 v[100:103], v[162:165], v[202:205], v[100:103]
	v_mfma_f32_16x16x32_bf16 v[96:99], v[170:173], v[202:205], v[96:99]
	s_setprio 0
	s_barrier
	ds_read_b128 v[206:209], v158
	ds_read_b128 v[210:213], v158 offset:1024
	ds_read_b128 v[214:217], v158 offset:2048
	ds_read_b128 v[156:159], v158 offset:3072
	s_barrier
	s_waitcnt lgkmcnt(0)
	s_setprio 1
	s_waitcnt lgkmcnt(0)
	v_mfma_f32_16x16x32_bf16 v[92:95], v[206:209], v[174:177], v[92:95]
	v_mfma_f32_16x16x32_bf16 v[88:91], v[214:217], v[174:177], v[88:91]
	v_mfma_f32_16x16x32_bf16 v[84:87], v[206:209], v[182:185], v[84:87]
	v_mfma_f32_16x16x32_bf16 v[80:83], v[214:217], v[182:185], v[80:83]
	v_mfma_f32_16x16x32_bf16 v[76:79], v[206:209], v[190:193], v[76:79]
	v_mfma_f32_16x16x32_bf16 v[72:75], v[214:217], v[190:193], v[72:75]
	v_mfma_f32_16x16x32_bf16 v[68:71], v[206:209], v[198:201], v[68:71]
	v_mfma_f32_16x16x32_bf16 v[64:67], v[214:217], v[198:201], v[64:67]
	v_mfma_f32_16x16x32_bf16 v[174:177], v[210:213], v[178:181], v[92:95]
	v_mfma_f32_16x16x32_bf16 v[178:181], v[156:159], v[178:181], v[88:91]
	v_mfma_f32_16x16x32_bf16 v[182:185], v[210:213], v[186:189], v[84:87]
	v_mfma_f32_16x16x32_bf16 v[186:189], v[156:159], v[186:189], v[80:83]
	v_mfma_f32_16x16x32_bf16 v[190:193], v[210:213], v[194:197], v[76:79]
	v_mfma_f32_16x16x32_bf16 v[194:197], v[156:159], v[194:197], v[72:75]
	v_mfma_f32_16x16x32_bf16 v[198:201], v[210:213], v[202:205], v[68:71]
	v_mfma_f32_16x16x32_bf16 v[202:205], v[156:159], v[202:205], v[64:67]
	s_setprio 0
	s_barrier
	s_nop 0
	ds_read_b128 v[64:67], v152 offset:16384
	ds_read_b128 v[68:71], v152 offset:17408
	ds_read_b128 v[72:75], v151 offset:16384
	ds_read_b128 v[76:79], v151 offset:17408
	ds_read_b128 v[80:83], v150 offset:16384
	ds_read_b128 v[84:87], v150 offset:17408
	ds_read_b128 v[88:91], v149 offset:16384
	ds_read_b128 v[92:95], v149 offset:17408
	s_waitcnt vmcnt(4)
	s_barrier
	s_waitcnt lgkmcnt(0)
	s_setprio 1
	s_waitcnt lgkmcnt(0)
	v_mfma_f32_16x16x32_bf16 v[60:63], v[130:133], v[64:67], v[60:63]
	v_mfma_f32_16x16x32_bf16 v[56:59], v[166:169], v[64:67], v[56:59]
	v_mfma_f32_16x16x32_bf16 v[52:55], v[130:133], v[72:75], v[52:55]
	v_mfma_f32_16x16x32_bf16 v[48:51], v[166:169], v[72:75], v[48:51]
	v_mfma_f32_16x16x32_bf16 v[218:221], v[130:133], v[80:83], v[44:47]
	v_mfma_f32_16x16x32_bf16 v[222:225], v[166:169], v[80:83], v[40:43]
	v_mfma_f32_16x16x32_bf16 v[130:133], v[130:133], v[88:91], v[36:39]
	v_mfma_f32_16x16x32_bf16 v[166:169], v[166:169], v[88:91], v[32:35]
	v_mfma_f32_16x16x32_bf16 v[32:35], v[162:165], v[68:71], v[60:63]
	v_mfma_f32_16x16x32_bf16 v[36:39], v[170:173], v[68:71], v[56:59]
	v_mfma_f32_16x16x32_bf16 v[40:43], v[162:165], v[76:79], v[52:55]
	v_mfma_f32_16x16x32_bf16 v[44:47], v[170:173], v[76:79], v[48:51]
	v_mfma_f32_16x16x32_bf16 v[48:51], v[162:165], v[84:87], v[218:221]
	v_mfma_f32_16x16x32_bf16 v[52:55], v[170:173], v[84:87], v[222:225]
	v_mfma_f32_16x16x32_bf16 v[56:59], v[162:165], v[92:95], v[130:133]
	v_mfma_f32_16x16x32_bf16 v[60:63], v[170:173], v[92:95], v[166:169]
	s_setprio 0
	s_setprio 1
	v_mfma_f32_16x16x32_bf16 v[28:31], v[206:209], v[64:67], v[28:31]
	v_mfma_f32_16x16x32_bf16 v[24:27], v[214:217], v[64:67], v[24:27]
	v_mfma_f32_16x16x32_bf16 v[20:23], v[206:209], v[72:75], v[20:23]
	v_mfma_f32_16x16x32_bf16 v[64:67], v[214:217], v[72:75], v[16:19]
	v_mfma_f32_16x16x32_bf16 v[72:75], v[206:209], v[80:83], v[12:15]
	v_mfma_f32_16x16x32_bf16 v[8:11], v[214:217], v[80:83], v[8:11]
	v_mfma_f32_16x16x32_bf16 v[80:83], v[206:209], v[88:91], v[4:7]
	v_mfma_f32_16x16x32_bf16 v[0:3], v[214:217], v[88:91], v[0:3]
	v_mfma_f32_16x16x32_bf16 v[4:7], v[210:213], v[68:71], v[28:31]
	v_mfma_f32_16x16x32_bf16 v[12:15], v[156:159], v[68:71], v[24:27]
	v_mfma_f32_16x16x32_bf16 v[16:19], v[210:213], v[76:79], v[20:23]
	v_mfma_f32_16x16x32_bf16 v[20:23], v[156:159], v[76:79], v[64:67]
	v_mfma_f32_16x16x32_bf16 v[24:27], v[210:213], v[84:87], v[72:75]
	v_mfma_f32_16x16x32_bf16 v[28:31], v[156:159], v[84:87], v[8:11]
	v_mfma_f32_16x16x32_bf16 v[64:67], v[210:213], v[92:95], v[80:83]
	v_mfma_f32_16x16x32_bf16 v[68:71], v[156:159], v[92:95], v[0:3]
	s_setprio 0
	s_barrier
	ds_read_b128 v[8:11], v154
	ds_read_b128 v[0:3], v154 offset:1024
	ds_read_b128 v[76:79], v154 offset:2048
	ds_read_b128 v[72:75], v154 offset:3072
	ds_read_b128 v[130:133], v152 offset:32768
	ds_read_b128 v[154:157], v152 offset:33792
	ds_read_b128 v[158:161], v151 offset:32768
	ds_read_b128 v[162:165], v151 offset:33792
	ds_read_b128 v[166:169], v150 offset:32768
	ds_read_b128 v[170:173], v150 offset:33792
	ds_read_b128 v[206:209], v149 offset:32768
	ds_read_b128 v[210:213], v149 offset:33792
	s_waitcnt vmcnt(2)
	s_barrier
	s_waitcnt lgkmcnt(0)
	s_setprio 1
	s_waitcnt lgkmcnt(0)
	v_mfma_f32_16x16x32_bf16 v[80:83], v[8:11], v[130:133], v[124:127]
	v_mfma_f32_16x16x32_bf16 v[84:87], v[76:79], v[130:133], v[120:123]
	v_mfma_f32_16x16x32_bf16 v[88:91], v[8:11], v[158:161], v[116:119]
	v_mfma_f32_16x16x32_bf16 v[92:95], v[76:79], v[158:161], v[112:115]
	v_mfma_f32_16x16x32_bf16 v[108:111], v[8:11], v[166:169], v[108:111]
	v_mfma_f32_16x16x32_bf16 v[104:107], v[76:79], v[166:169], v[104:107]
	v_mfma_f32_16x16x32_bf16 v[100:103], v[8:11], v[206:209], v[100:103]
	v_mfma_f32_16x16x32_bf16 v[96:99], v[76:79], v[206:209], v[96:99]
	v_mfma_f32_16x16x32_bf16 v[112:115], v[0:3], v[154:157], v[80:83]
	v_mfma_f32_16x16x32_bf16 v[116:119], v[72:75], v[154:157], v[84:87]
	v_mfma_f32_16x16x32_bf16 v[120:123], v[0:3], v[162:165], v[88:91]
	v_mfma_f32_16x16x32_bf16 v[124:127], v[72:75], v[162:165], v[92:95]
	v_mfma_f32_16x16x32_bf16 v[108:111], v[0:3], v[170:173], v[108:111]
	v_mfma_f32_16x16x32_bf16 v[104:107], v[72:75], v[170:173], v[104:107]
	v_mfma_f32_16x16x32_bf16 v[100:103], v[0:3], v[210:213], v[100:103]
	v_mfma_f32_16x16x32_bf16 v[96:99], v[72:75], v[210:213], v[96:99]
	s_setprio 0
	s_barrier
	ds_read_b128 v[88:91], v153
	ds_read_b128 v[80:83], v153 offset:1024
	ds_read_b128 v[92:95], v153 offset:2048
	ds_read_b128 v[84:87], v153 offset:3072
	s_waitcnt vmcnt(0)
	s_barrier
	s_waitcnt lgkmcnt(0)
	s_setprio 1
	s_waitcnt lgkmcnt(0)
	v_mfma_f32_16x16x32_bf16 v[174:177], v[88:91], v[130:133], v[174:177]
	v_mfma_f32_16x16x32_bf16 v[130:133], v[92:95], v[130:133], v[178:181]
	v_mfma_f32_16x16x32_bf16 v[178:181], v[88:91], v[158:161], v[182:185]
	v_mfma_f32_16x16x32_bf16 v[158:161], v[92:95], v[158:161], v[186:189]
	v_mfma_f32_16x16x32_bf16 v[182:185], v[88:91], v[166:169], v[190:193]
	v_mfma_f32_16x16x32_bf16 v[166:169], v[92:95], v[166:169], v[194:197]
	v_mfma_f32_16x16x32_bf16 v[186:189], v[88:91], v[206:209], v[198:201]
	v_mfma_f32_16x16x32_bf16 v[190:193], v[92:95], v[206:209], v[202:205]
	v_mfma_f32_16x16x32_bf16 v[174:177], v[80:83], v[154:157], v[174:177]
	v_mfma_f32_16x16x32_bf16 v[130:133], v[84:87], v[154:157], v[130:133]
	v_mfma_f32_16x16x32_bf16 v[154:157], v[80:83], v[162:165], v[178:181]
	v_mfma_f32_16x16x32_bf16 v[158:161], v[84:87], v[162:165], v[158:161]
	v_mfma_f32_16x16x32_bf16 v[162:165], v[80:83], v[170:173], v[182:185]
	v_mfma_f32_16x16x32_bf16 v[166:169], v[84:87], v[170:173], v[166:169]
	v_mfma_f32_16x16x32_bf16 v[170:173], v[80:83], v[210:213], v[186:189]
	v_mfma_f32_16x16x32_bf16 v[178:181], v[84:87], v[210:213], v[190:193]
	s_setprio 0
	s_barrier
	v_mbcnt_lo_u32_b32 v128, -1, 0
	v_mbcnt_hi_u32_b32 v128, -1, v128
	v_cvt_pk_bf16_f32 v112, v112, v113
	v_cvt_pk_bf16_f32 v113, v114, v115
	v_cvt_pk_bf16_f32 v114, v116, v117
	v_cvt_pk_bf16_f32 v115, v118, v119
	s_lshl_b32 s89, s64, 9
	v_add_u32_e32 v153, s72, v128
	v_ashrrev_i32_e32 v182, 6, v153
	v_and_b32_e32 v183, 15, v128
	v_and_b32_e32 v184, 48, v128
	v_mul_lo_u32 v185, v182, s77
	v_bfe_u32 v186, v128, 3, 3
	v_lshlrev_b32_e32 v128, 4, v128
	v_add_u32_e32 v185, 0x20000, v185
	v_lshrrev_b32_e32 v153, 2, v153
	v_and_b32_e32 v128, 0x70, v128
	v_mul_u32_u24_e32 v183, 0x90, v183
	v_and_b32_e32 v153, 64, v153
	v_add3_u32 v183, v185, v183, v184
	v_or_b32_e32 v184, v185, v128
	v_or3_b32 v153, s97, v153, v186
	v_mad_u32_u24 v184, v186, s79, v184
	ds_write_b128 v183, v[112:115]
	v_cvt_pk_bf16_f32 v112, v174, v175
	v_cvt_pk_bf16_f32 v113, v176, v177
	v_cvt_pk_bf16_f32 v114, v130, v131
	v_cvt_pk_bf16_f32 v115, v132, v133
	ds_write_b128 v183, v[112:115] offset:64
	v_lshlrev_b32_e32 v182, 7, v182
	ds_read_b128 v[112:115], v184
	v_lshlrev_b32_e32 v116, 12, v153
	v_and_or_b32 v116, v182, s80, v116
	v_or3_b32 v128, v116, s89, v128
	ds_read_b128 v[116:119], v184 offset:1152
	v_lshl_add_u64 v[130:131], s[0:1], 0, v[128:129]
	s_mov_b32 s20, 0x8000
	s_waitcnt lgkmcnt(0)
	global_store_dwordx4 v128, v[112:115], s[0:1]
	v_cvt_pk_bf16_f32 v108, v108, v109
	v_cvt_pk_bf16_f32 v109, v110, v111
	v_cvt_pk_bf16_f32 v110, v104, v105
	v_cvt_pk_bf16_f32 v111, v106, v107
	v_cvt_pk_bf16_f32 v104, v162, v163
	s_nop 1
	v_add_co_u32_e32 v112, vcc, s20, v130
	v_cvt_pk_bf16_f32 v114, v124, v125
	v_cvt_pk_bf16_f32 v115, v126, v127
	v_cvt_pk_bf16_f32 v105, v164, v165
	v_cvt_pk_bf16_f32 v106, v166, v167
	s_nop 1
	v_addc_co_u32_e32 v113, vcc, 0, v131, vcc
	global_store_dwordx4 v[112:113], v[116:119], off
	v_cvt_pk_bf16_f32 v112, v120, v121
	v_cvt_pk_bf16_f32 v113, v122, v123
	ds_write_b128 v183, v[112:115]
	v_cvt_pk_bf16_f32 v112, v154, v155
	v_cvt_pk_bf16_f32 v113, v156, v157
	v_cvt_pk_bf16_f32 v114, v158, v159
	v_cvt_pk_bf16_f32 v115, v160, v161
	ds_write_b128 v183, v[112:115] offset:64
	ds_read_b128 v[112:115], v184
	ds_read_b128 v[116:119], v184 offset:1152
	v_add_co_u32_e32 v120, vcc, s74, v130
	ds_write_b128 v183, v[108:111]
	v_cvt_pk_bf16_f32 v107, v168, v169
	ds_write_b128 v183, v[104:107] offset:64
	v_addc_co_u32_e32 v121, vcc, 0, v131, vcc
	ds_read_b128 v[104:107], v184
	ds_read_b128 v[108:111], v184 offset:1152
	s_waitcnt lgkmcnt(0)
	global_store_dwordx4 v[120:121], v[112:115], off
	v_cvt_pk_bf16_f32 v100, v100, v101
	v_cvt_pk_bf16_f32 v101, v102, v103
	v_cvt_pk_bf16_f32 v102, v96, v97
	v_cvt_pk_bf16_f32 v103, v98, v99
	ds_write_b128 v183, v[100:103]
	s_nop 0
	v_add_co_u32_e32 v112, vcc, s75, v130
	v_cvt_pk_bf16_f32 v96, v170, v171
	v_cvt_pk_bf16_f32 v97, v172, v173
	v_cvt_pk_bf16_f32 v98, v178, v179
	v_cvt_pk_bf16_f32 v99, v180, v181
	s_nop 1
	v_addc_co_u32_e32 v113, vcc, 0, v131, vcc
	global_store_dwordx4 v[112:113], v[116:119], off
	v_add_co_u32_e32 v112, vcc, s78, v130
	ds_write_b128 v183, v[96:99] offset:64
	s_nop 0
	v_addc_co_u32_e32 v113, vcc, 0, v131, vcc
	ds_read_b128 v[96:99], v184
	ds_read_b128 v[100:103], v184 offset:1152
	global_store_dwordx4 v[112:113], v[104:107], off
	s_nop 1
	v_add_co_u32_e32 v104, vcc, s81, v130
	s_nop 1
	v_addc_co_u32_e32 v105, vcc, 0, v131, vcc
	global_store_dwordx4 v[104:105], v[108:111], off
	v_add_co_u32_e32 v104, vcc, s82, v130
	s_nop 1
	v_addc_co_u32_e32 v105, vcc, 0, v131, vcc
	s_waitcnt lgkmcnt(0)
	global_store_dwordx4 v[104:105], v[96:99], off
	s_nop 1
	v_add_co_u32_e32 v96, vcc, s83, v130
	s_nop 1
	v_addc_co_u32_e32 v97, vcc, 0, v131, vcc
	global_store_dwordx4 v[96:97], v[100:103], off
	ds_read_b128 v[96:99], v152 offset:49152
	ds_read_b128 v[100:103], v152 offset:50176
	ds_read_b128 v[104:107], v151 offset:49152
	ds_read_b128 v[108:111], v151 offset:50176
	ds_read_b128 v[112:115], v150 offset:49152
	ds_read_b128 v[116:119], v150 offset:50176
	ds_read_b128 v[120:123], v149 offset:49152
	ds_read_b128 v[124:127], v149 offset:50176
	s_barrier
	s_waitcnt lgkmcnt(0)
	s_setprio 1
	s_waitcnt lgkmcnt(0)
	v_mfma_f32_16x16x32_bf16 v[32:35], v[8:11], v[96:99], v[32:35]
	v_mfma_f32_16x16x32_bf16 v[36:39], v[76:79], v[96:99], v[36:39]
	v_mfma_f32_16x16x32_bf16 v[40:43], v[8:11], v[104:107], v[40:43]
	v_mfma_f32_16x16x32_bf16 v[130:133], v[76:79], v[104:107], v[44:47]
	v_mfma_f32_16x16x32_bf16 v[150:153], v[8:11], v[112:115], v[48:51]
	v_mfma_f32_16x16x32_bf16 v[52:55], v[76:79], v[112:115], v[52:55]
	v_mfma_f32_16x16x32_bf16 v[8:11], v[8:11], v[120:123], v[56:59]
	v_mfma_f32_16x16x32_bf16 v[60:63], v[76:79], v[120:123], v[60:63]
	v_mfma_f32_16x16x32_bf16 v[56:59], v[0:3], v[100:103], v[32:35]
	v_mfma_f32_16x16x32_bf16 v[48:51], v[72:75], v[100:103], v[36:39]
	v_mfma_f32_16x16x32_bf16 v[44:47], v[0:3], v[108:111], v[40:43]
	v_mfma_f32_16x16x32_bf16 v[40:43], v[72:75], v[108:111], v[130:133]
	v_mfma_f32_16x16x32_bf16 v[36:39], v[0:3], v[116:119], v[150:153]
	v_mfma_f32_16x16x32_bf16 v[32:35], v[72:75], v[116:119], v[52:55]
	v_mfma_f32_16x16x32_bf16 v[8:11], v[0:3], v[124:127], v[8:11]
	v_mfma_f32_16x16x32_bf16 v[0:3], v[72:75], v[124:127], v[60:63]
	s_setprio 0
	s_setprio 1
	v_mfma_f32_16x16x32_bf16 v[4:7], v[88:91], v[96:99], v[4:7]
	v_mfma_f32_16x16x32_bf16 v[12:15], v[92:95], v[96:99], v[12:15]
	v_mfma_f32_16x16x32_bf16 v[16:19], v[88:91], v[104:107], v[16:19]
	v_mfma_f32_16x16x32_bf16 v[20:23], v[92:95], v[104:107], v[20:23]
	v_mfma_f32_16x16x32_bf16 v[72:75], v[88:91], v[112:115], v[24:27]
	v_mfma_f32_16x16x32_bf16 v[76:79], v[92:95], v[112:115], v[28:31]
	v_mfma_f32_16x16x32_bf16 v[64:67], v[88:91], v[120:123], v[64:67]
	v_mfma_f32_16x16x32_bf16 v[68:71], v[92:95], v[120:123], v[68:71]
	v_mfma_f32_16x16x32_bf16 v[60:63], v[80:83], v[100:103], v[4:7]
	v_mfma_f32_16x16x32_bf16 v[52:55], v[84:87], v[100:103], v[12:15]
	v_mfma_f32_16x16x32_bf16 v[28:31], v[80:83], v[108:111], v[16:19]
	v_mfma_f32_16x16x32_bf16 v[24:27], v[84:87], v[108:111], v[20:23]
	v_mfma_f32_16x16x32_bf16 v[20:23], v[80:83], v[116:119], v[72:75]
	v_mfma_f32_16x16x32_bf16 v[16:19], v[84:87], v[116:119], v[76:79]
	v_mfma_f32_16x16x32_bf16 v[12:15], v[80:83], v[124:127], v[64:67]
	v_mfma_f32_16x16x32_bf16 v[4:7], v[84:87], v[124:127], v[68:71]
	s_setprio 0
	v_cmp_gt_u32_e32 vcc, s85, v135
	s_barrier
	s_and_saveexec_b64 s[64:65], vcc
	s_cbranch_execz .LBB0_277
	s_barrier

.LBB0_356:
	ds_read_b128 v[138:141], v134
	ds_read_b128 v[142:145], v134 offset:1024
	ds_read_b128 v[146:149], v134 offset:2048
	ds_read_b128 v[150:153], v134 offset:3072
	ds_read_b128 v[154:157], v187
	ds_read_b128 v[158:161], v187 offset:1024
	ds_read_b128 v[188:191], v186
	ds_read_b128 v[192:195], v186 offset:1024
	ds_read_b128 v[196:199], v185
	ds_read_b128 v[200:203], v185 offset:1024
	ds_read_b128 v[204:207], v184
	ds_read_b128 v[208:211], v184 offset:1024
	s_waitcnt lgkmcnt(8)
	s_waitcnt vmcnt(10)
	s_barrier
	s_waitcnt lgkmcnt(0)
	s_waitcnt lgkmcnt(0)
	v_mfma_f32_16x16x32_bf16 v[124:127], v[138:141], v[154:157], v[124:127]
	v_mfma_f32_16x16x32_bf16 v[120:123], v[146:149], v[154:157], v[120:123]
	v_mfma_f32_16x16x32_bf16 v[116:119], v[138:141], v[188:191], v[116:119]
	v_mfma_f32_16x16x32_bf16 v[112:115], v[146:149], v[188:191], v[112:115]
	v_mfma_f32_16x16x32_bf16 v[108:111], v[138:141], v[196:199], v[108:111]
	v_mfma_f32_16x16x32_bf16 v[104:107], v[146:149], v[196:199], v[104:107]
	v_mfma_f32_16x16x32_bf16 v[100:103], v[138:141], v[204:207], v[100:103]
	v_mfma_f32_16x16x32_bf16 v[96:99], v[146:149], v[204:207], v[96:99]
	v_mfma_f32_16x16x32_bf16 v[124:127], v[142:145], v[158:161], v[124:127]
	v_mfma_f32_16x16x32_bf16 v[120:123], v[150:153], v[158:161], v[120:123]
	v_mfma_f32_16x16x32_bf16 v[116:119], v[142:145], v[192:195], v[116:119]
	v_mfma_f32_16x16x32_bf16 v[112:115], v[150:153], v[192:195], v[112:115]
	v_mfma_f32_16x16x32_bf16 v[108:111], v[142:145], v[200:203], v[108:111]
	v_mfma_f32_16x16x32_bf16 v[104:107], v[150:153], v[200:203], v[104:107]
	v_mfma_f32_16x16x32_bf16 v[100:103], v[142:145], v[208:211], v[100:103]
	v_mfma_f32_16x16x32_bf16 v[96:99], v[150:153], v[208:211], v[96:99]
	s_barrier
	s_add_u32 s70, s18, 1
	s_addc_u32 s71, s19, 0
	s_lshl_b64 s[72:73], s[70:71], s22
	s_add_u32 s74, s17, s72
	s_addc_u32 s75, s29, s73
	v_lshl_add_u64 v[162:163], s[74:75], 0, v[128:129]
	v_readfirstlane_b32 s23, v182
	s_add_u32 s74, s74, s25
	s_mov_b32 m0, s23
	s_addc_u32 s75, s75, 0
	v_readfirstlane_b32 s23, v181
	ds_read_b128 v[212:215], v131
	ds_read_b128 v[216:219], v131 offset:1024
	ds_read_b128 v[220:223], v131 offset:2048
	ds_read_b128 v[224:227], v131 offset:3072
	global_load_lds_dwordx4 v[162:163], off
	v_lshl_add_u64 v[162:163], s[74:75], 0, v[128:129]
	s_mov_b32 m0, s23
	s_nop 0
	global_load_lds_dwordx4 v[162:163], off
	s_lshl_b64 s[70:71], s[70:71], s28
	s_add_u32 s74, s15, s70
	s_addc_u32 s75, s30, s71
	v_lshl_add_u64 v[162:163], s[74:75], 0, v[164:165]
	v_readfirstlane_b32 s23, v169
	s_add_u32 s74, s74, s24
	s_mov_b32 m0, s23
	s_addc_u32 s75, s75, 0
	v_readfirstlane_b32 s23, v180
	global_load_lds_dwordx4 v[162:163], off
	v_lshl_add_u64 v[162:163], s[74:75], 0, v[164:165]
	s_mov_b32 m0, s23
	s_nop 0
	global_load_lds_dwordx4 v[162:163], off
	s_waitcnt vmcnt(12)
	s_barrier
	s_waitcnt lgkmcnt(0)
	s_waitcnt lgkmcnt(0)
	v_mfma_f32_16x16x32_bf16 v[92:95], v[212:215], v[154:157], v[92:95]
	v_mfma_f32_16x16x32_bf16 v[88:91], v[220:223], v[154:157], v[88:91]
	v_mfma_f32_16x16x32_bf16 v[84:87], v[212:215], v[188:191], v[84:87]
	v_mfma_f32_16x16x32_bf16 v[80:83], v[220:223], v[188:191], v[80:83]
	v_mfma_f32_16x16x32_bf16 v[76:79], v[212:215], v[196:199], v[76:79]
	v_mfma_f32_16x16x32_bf16 v[72:75], v[220:223], v[196:199], v[72:75]
	v_mfma_f32_16x16x32_bf16 v[68:71], v[212:215], v[204:207], v[68:71]
	v_mfma_f32_16x16x32_bf16 v[64:67], v[220:223], v[204:207], v[64:67]
	v_mfma_f32_16x16x32_bf16 v[92:95], v[216:219], v[158:161], v[92:95]
	v_mfma_f32_16x16x32_bf16 v[88:91], v[224:227], v[158:161], v[88:91]
	v_mfma_f32_16x16x32_bf16 v[84:87], v[216:219], v[192:195], v[84:87]
	v_mfma_f32_16x16x32_bf16 v[80:83], v[224:227], v[192:195], v[80:83]
	v_mfma_f32_16x16x32_bf16 v[76:79], v[216:219], v[200:203], v[76:79]
	v_mfma_f32_16x16x32_bf16 v[72:75], v[224:227], v[200:203], v[72:75]
	v_mfma_f32_16x16x32_bf16 v[68:71], v[216:219], v[208:211], v[68:71]
	v_mfma_f32_16x16x32_bf16 v[64:67], v[224:227], v[208:211], v[64:67]
	s_barrier
	ds_read_b128 v[154:157], v187 offset:16384
	ds_read_b128 v[158:161], v187 offset:17408
	ds_read_b128 v[188:191], v186 offset:16384
	ds_read_b128 v[192:195], v186 offset:17408
	ds_read_b128 v[196:199], v185 offset:16384
	ds_read_b128 v[200:203], v185 offset:17408
	ds_read_b128 v[204:207], v184 offset:16384
	ds_read_b128 v[208:211], v184 offset:17408
	s_add_u32 s72, s20, s72
	s_addc_u32 s73, s21, s73
	v_lshl_add_u64 v[162:163], s[72:73], 0, v[128:129]
	v_readfirstlane_b32 s23, v179
	s_add_u32 s72, s72, s25
	s_mov_b32 m0, s23
	s_addc_u32 s73, s73, 0
	v_readfirstlane_b32 s23, v178
	global_load_lds_dwordx4 v[162:163], off
	v_lshl_add_u64 v[162:163], s[72:73], 0, v[128:129]
	s_mov_b32 m0, s23
	s_nop 0
	global_load_lds_dwordx4 v[162:163], off
	s_barrier
	s_waitcnt lgkmcnt(0)
	s_waitcnt lgkmcnt(0)
	v_mfma_f32_16x16x32_bf16 v[60:63], v[138:141], v[154:157], v[60:63]
	v_mfma_f32_16x16x32_bf16 v[56:59], v[146:149], v[154:157], v[56:59]
	v_mfma_f32_16x16x32_bf16 v[52:55], v[138:141], v[188:191], v[52:55]
	v_mfma_f32_16x16x32_bf16 v[48:51], v[146:149], v[188:191], v[48:51]
	v_mfma_f32_16x16x32_bf16 v[44:47], v[138:141], v[196:199], v[44:47]
	v_mfma_f32_16x16x32_bf16 v[40:43], v[146:149], v[196:199], v[40:43]
	v_mfma_f32_16x16x32_bf16 v[36:39], v[138:141], v[204:207], v[36:39]
	v_mfma_f32_16x16x32_bf16 v[32:35], v[146:149], v[204:207], v[32:35]
	v_mfma_f32_16x16x32_bf16 v[60:63], v[142:145], v[158:161], v[60:63]
	v_mfma_f32_16x16x32_bf16 v[56:59], v[150:153], v[158:161], v[56:59]
	v_mfma_f32_16x16x32_bf16 v[52:55], v[142:145], v[192:195], v[52:55]
	v_mfma_f32_16x16x32_bf16 v[48:51], v[150:153], v[192:195], v[48:51]
	v_mfma_f32_16x16x32_bf16 v[44:47], v[142:145], v[200:203], v[44:47]
	v_mfma_f32_16x16x32_bf16 v[40:43], v[150:153], v[200:203], v[40:43]
	v_mfma_f32_16x16x32_bf16 v[36:39], v[142:145], v[208:211], v[36:39]
	v_mfma_f32_16x16x32_bf16 v[32:35], v[150:153], v[208:211], v[32:35]
	s_barrier
	s_add_u32 s70, s26, s70
	s_addc_u32 s71, s27, s71
	v_lshl_add_u64 v[162:163], s[70:71], 0, v[164:165]
	v_readfirstlane_b32 s23, v177
	s_add_u32 s70, s70, s24
	s_mov_b32 m0, s23
	s_addc_u32 s71, s71, 0
	v_readfirstlane_b32 s23, v176
	global_load_lds_dwordx4 v[162:163], off
	v_lshl_add_u64 v[162:163], s[70:71], 0, v[164:165]
	s_mov_b32 m0, s23
	s_nop 0
	global_load_lds_dwordx4 v[162:163], off
	s_waitcnt vmcnt(12)
	s_barrier
	v_mfma_f32_16x16x32_bf16 v[28:31], v[212:215], v[154:157], v[28:31]
	v_mfma_f32_16x16x32_bf16 v[24:27], v[220:223], v[154:157], v[24:27]
	v_mfma_f32_16x16x32_bf16 v[20:23], v[212:215], v[188:191], v[20:23]
	v_mfma_f32_16x16x32_bf16 v[16:19], v[220:223], v[188:191], v[16:19]
	v_mfma_f32_16x16x32_bf16 v[12:15], v[212:215], v[196:199], v[12:15]
	v_mfma_f32_16x16x32_bf16 v[8:11], v[220:223], v[196:199], v[8:11]
	v_mfma_f32_16x16x32_bf16 v[4:7], v[212:215], v[204:207], v[4:7]
	v_mfma_f32_16x16x32_bf16 v[0:3], v[220:223], v[204:207], v[0:3]
	v_mfma_f32_16x16x32_bf16 v[28:31], v[216:219], v[158:161], v[28:31]
	v_mfma_f32_16x16x32_bf16 v[24:27], v[224:227], v[158:161], v[24:27]
	v_mfma_f32_16x16x32_bf16 v[20:23], v[216:219], v[192:195], v[20:23]
	v_mfma_f32_16x16x32_bf16 v[16:19], v[224:227], v[192:195], v[16:19]
	v_mfma_f32_16x16x32_bf16 v[12:15], v[216:219], v[200:203], v[12:15]
	v_mfma_f32_16x16x32_bf16 v[8:11], v[224:227], v[200:203], v[8:11]
	v_mfma_f32_16x16x32_bf16 v[4:7], v[216:219], v[208:211], v[4:7]
	v_mfma_f32_16x16x32_bf16 v[0:3], v[224:227], v[208:211], v[0:3]
	s_barrier
	ds_read_b128 v[138:141], v130
	ds_read_b128 v[142:145], v130 offset:1024
	ds_read_b128 v[146:149], v130 offset:2048
	ds_read_b128 v[150:153], v130 offset:3072
	ds_read_b128 v[154:157], v187 offset:32768
	ds_read_b128 v[158:161], v187 offset:33792
	ds_read_b128 v[188:191], v186 offset:32768
	ds_read_b128 v[192:195], v186 offset:33792
	ds_read_b128 v[196:199], v185 offset:32768
	ds_read_b128 v[200:203], v185 offset:33792
	ds_read_b128 v[204:207], v184 offset:32768
	ds_read_b128 v[208:211], v184 offset:33792
	s_waitcnt lgkmcnt(8)
	s_waitcnt vmcnt(10)
	s_barrier
	s_waitcnt lgkmcnt(0)
	s_waitcnt lgkmcnt(0)
	v_mfma_f32_16x16x32_bf16 v[124:127], v[138:141], v[154:157], v[124:127]
	v_mfma_f32_16x16x32_bf16 v[120:123], v[146:149], v[154:157], v[120:123]
	v_mfma_f32_16x16x32_bf16 v[116:119], v[138:141], v[188:191], v[116:119]
	v_mfma_f32_16x16x32_bf16 v[112:115], v[146:149], v[188:191], v[112:115]
	v_mfma_f32_16x16x32_bf16 v[108:111], v[138:141], v[196:199], v[108:111]
	v_mfma_f32_16x16x32_bf16 v[104:107], v[146:149], v[196:199], v[104:107]
	v_mfma_f32_16x16x32_bf16 v[100:103], v[138:141], v[204:207], v[100:103]
	v_mfma_f32_16x16x32_bf16 v[96:99], v[146:149], v[204:207], v[96:99]
	v_mfma_f32_16x16x32_bf16 v[124:127], v[142:145], v[158:161], v[124:127]
	v_mfma_f32_16x16x32_bf16 v[120:123], v[150:153], v[158:161], v[120:123]
	v_mfma_f32_16x16x32_bf16 v[116:119], v[142:145], v[192:195], v[116:119]
	v_mfma_f32_16x16x32_bf16 v[112:115], v[150:153], v[192:195], v[112:115]
	v_mfma_f32_16x16x32_bf16 v[108:111], v[142:145], v[200:203], v[108:111]
	v_mfma_f32_16x16x32_bf16 v[104:107], v[150:153], v[200:203], v[104:107]
	v_mfma_f32_16x16x32_bf16 v[100:103], v[142:145], v[208:211], v[100:103]
	v_mfma_f32_16x16x32_bf16 v[96:99], v[150:153], v[208:211], v[96:99]
	s_barrier
	s_add_u32 s18, s18, 2
	s_addc_u32 s19, s19, 0
	s_lshl_b64 s[70:71], s[18:19], s22
	s_add_u32 s72, s17, s70
	s_addc_u32 s73, s29, s71
	v_lshl_add_u64 v[162:163], s[72:73], 0, v[128:129]
	v_readfirstlane_b32 s23, v175
	s_add_u32 s72, s72, s25
	s_mov_b32 m0, s23
	s_addc_u32 s73, s73, 0
	v_readfirstlane_b32 s23, v174
	ds_read_b128 v[212:215], v136
	ds_read_b128 v[216:219], v136 offset:1024
	ds_read_b128 v[220:223], v136 offset:2048
	ds_read_b128 v[224:227], v136 offset:3072
	global_load_lds_dwordx4 v[162:163], off
	v_lshl_add_u64 v[162:163], s[72:73], 0, v[128:129]
	s_mov_b32 m0, s23
	s_nop 0
	global_load_lds_dwordx4 v[162:163], off
	s_lshl_b64 s[72:73], s[18:19], s28
	s_add_u32 s72, s15, s72
	s_addc_u32 s73, s30, s73
	v_lshl_add_u64 v[162:163], s[72:73], 0, v[164:165]
	v_readfirstlane_b32 s23, v173
	s_add_u32 s72, s72, s24
	s_mov_b32 m0, s23
	s_addc_u32 s73, s73, 0
	v_readfirstlane_b32 s23, v172
	global_load_lds_dwordx4 v[162:163], off
	v_lshl_add_u64 v[162:163], s[72:73], 0, v[164:165]
	s_mov_b32 m0, s23
	s_nop 0
	global_load_lds_dwordx4 v[162:163], off
	s_waitcnt vmcnt(12)
	s_barrier
	s_waitcnt lgkmcnt(0)
	s_waitcnt lgkmcnt(0)
	v_mfma_f32_16x16x32_bf16 v[92:95], v[212:215], v[154:157], v[92:95]
	v_mfma_f32_16x16x32_bf16 v[88:91], v[220:223], v[154:157], v[88:91]
	v_mfma_f32_16x16x32_bf16 v[84:87], v[212:215], v[188:191], v[84:87]
	v_mfma_f32_16x16x32_bf16 v[80:83], v[220:223], v[188:191], v[80:83]
	v_mfma_f32_16x16x32_bf16 v[76:79], v[212:215], v[196:199], v[76:79]
	v_mfma_f32_16x16x32_bf16 v[72:75], v[220:223], v[196:199], v[72:75]
	v_mfma_f32_16x16x32_bf16 v[68:71], v[212:215], v[204:207], v[68:71]
	v_mfma_f32_16x16x32_bf16 v[64:67], v[220:223], v[204:207], v[64:67]
	v_mfma_f32_16x16x32_bf16 v[92:95], v[216:219], v[158:161], v[92:95]
	v_mfma_f32_16x16x32_bf16 v[88:91], v[224:227], v[158:161], v[88:91]
	v_mfma_f32_16x16x32_bf16 v[84:87], v[216:219], v[192:195], v[84:87]
	v_mfma_f32_16x16x32_bf16 v[80:83], v[224:227], v[192:195], v[80:83]
	v_mfma_f32_16x16x32_bf16 v[76:79], v[216:219], v[200:203], v[76:79]
	v_mfma_f32_16x16x32_bf16 v[72:75], v[224:227], v[200:203], v[72:75]
	v_mfma_f32_16x16x32_bf16 v[68:71], v[216:219], v[208:211], v[68:71]
	v_mfma_f32_16x16x32_bf16 v[64:67], v[224:227], v[208:211], v[64:67]
	s_barrier
	ds_read_b128 v[154:157], v187 offset:49152
	ds_read_b128 v[158:161], v187 offset:50176
	ds_read_b128 v[188:191], v186 offset:49152
	ds_read_b128 v[192:195], v186 offset:50176
	ds_read_b128 v[196:199], v185 offset:49152
	ds_read_b128 v[200:203], v185 offset:50176
	ds_read_b128 v[204:207], v184 offset:49152
	ds_read_b128 v[208:211], v184 offset:50176
	s_add_u32 s70, s20, s70
	s_addc_u32 s71, s21, s71
	v_lshl_add_u64 v[162:163], s[70:71], 0, v[128:129]
	v_readfirstlane_b32 s23, v171
	s_add_u32 s70, s70, s25
	s_mov_b32 m0, s23
	s_addc_u32 s71, s71, 0
	v_readfirstlane_b32 s23, v170
	global_load_lds_dwordx4 v[162:163], off
	v_lshl_add_u64 v[162:163], s[70:71], 0, v[128:129]
	s_mov_b32 m0, s23
	s_nop 0
	global_load_lds_dwordx4 v[162:163], off
	s_barrier
	s_waitcnt lgkmcnt(0)
	s_waitcnt lgkmcnt(0)
	v_mfma_f32_16x16x32_bf16 v[60:63], v[138:141], v[154:157], v[60:63]
	v_mfma_f32_16x16x32_bf16 v[56:59], v[146:149], v[154:157], v[56:59]
	v_mfma_f32_16x16x32_bf16 v[52:55], v[138:141], v[188:191], v[52:55]
	v_mfma_f32_16x16x32_bf16 v[48:51], v[146:149], v[188:191], v[48:51]
	v_mfma_f32_16x16x32_bf16 v[44:47], v[138:141], v[196:199], v[44:47]
	v_mfma_f32_16x16x32_bf16 v[40:43], v[146:149], v[196:199], v[40:43]
	v_mfma_f32_16x16x32_bf16 v[36:39], v[138:141], v[204:207], v[36:39]
	v_mfma_f32_16x16x32_bf16 v[32:35], v[146:149], v[204:207], v[32:35]
	v_mfma_f32_16x16x32_bf16 v[60:63], v[142:145], v[158:161], v[60:63]
	v_mfma_f32_16x16x32_bf16 v[56:59], v[150:153], v[158:161], v[56:59]
	v_mfma_f32_16x16x32_bf16 v[52:55], v[142:145], v[192:195], v[52:55]
	v_mfma_f32_16x16x32_bf16 v[48:51], v[150:153], v[192:195], v[48:51]
	v_mfma_f32_16x16x32_bf16 v[44:47], v[142:145], v[200:203], v[44:47]
	v_mfma_f32_16x16x32_bf16 v[40:43], v[150:153], v[200:203], v[40:43]
	v_mfma_f32_16x16x32_bf16 v[36:39], v[142:145], v[208:211], v[36:39]
	v_mfma_f32_16x16x32_bf16 v[32:35], v[150:153], v[208:211], v[32:35]
	s_barrier
	s_lshl_b64 s[70:71], s[18:19], s28
	s_add_u32 s70, s26, s70
	s_addc_u32 s71, s27, s71
	v_lshl_add_u64 v[162:163], s[70:71], 0, v[164:165]
	v_readfirstlane_b32 s23, v133
	s_add_u32 s70, s70, s24
	s_mov_b32 m0, s23
	s_addc_u32 s71, s71, 0
	v_readfirstlane_b32 s23, v132
	global_load_lds_dwordx4 v[162:163], off
	v_lshl_add_u64 v[162:163], s[70:71], 0, v[164:165]
	s_mov_b32 m0, s23
	s_nop 0
	global_load_lds_dwordx4 v[162:163], off
	s_waitcnt vmcnt(12)
	s_barrier
	v_mfma_f32_16x16x32_bf16 v[28:31], v[212:215], v[154:157], v[28:31]
	v_mfma_f32_16x16x32_bf16 v[24:27], v[220:223], v[154:157], v[24:27]
	v_mfma_f32_16x16x32_bf16 v[20:23], v[212:215], v[188:191], v[20:23]
	v_mfma_f32_16x16x32_bf16 v[16:19], v[220:223], v[188:191], v[16:19]
	v_mfma_f32_16x16x32_bf16 v[12:15], v[212:215], v[196:199], v[12:15]
	v_mfma_f32_16x16x32_bf16 v[8:11], v[220:223], v[196:199], v[8:11]
	v_mfma_f32_16x16x32_bf16 v[4:7], v[212:215], v[204:207], v[4:7]
	v_mfma_f32_16x16x32_bf16 v[0:3], v[220:223], v[204:207], v[0:3]
	v_mfma_f32_16x16x32_bf16 v[28:31], v[216:219], v[158:161], v[28:31]
	v_mfma_f32_16x16x32_bf16 v[24:27], v[224:227], v[158:161], v[24:27]
	v_mfma_f32_16x16x32_bf16 v[20:23], v[216:219], v[192:195], v[20:23]
	v_mfma_f32_16x16x32_bf16 v[16:19], v[224:227], v[192:195], v[16:19]
	v_mfma_f32_16x16x32_bf16 v[12:15], v[216:219], v[200:203], v[12:15]
	v_mfma_f32_16x16x32_bf16 v[8:11], v[224:227], v[200:203], v[8:11]
	v_mfma_f32_16x16x32_bf16 v[4:7], v[216:219], v[208:211], v[4:7]
	v_mfma_f32_16x16x32_bf16 v[0:3], v[224:227], v[208:211], v[0:3]
	s_add_i32 s23, s18, -3
	s_cmp_lt_u32 s23, 28
	s_barrier
	s_cbranch_scc1 .LBB0_356
	s_lshl_b64 s[18:19], 31, s28
	s_add_u32 s18, s26, s18
	s_addc_u32 s19, s27, s19
	v_lshl_add_u64 v[128:129], s[18:19], 0, v[164:165]
	v_readfirstlane_b32 s15, v133
	s_add_u32 s18, s18, s24
	s_mov_b32 m0, s15
	s_addc_u32 s19, s19, 0
	v_readfirstlane_b32 s15, v132
	ds_read_b128 v[138:141], v134
	ds_read_b128 v[142:145], v134 offset:1024
	ds_read_b128 v[146:149], v134 offset:2048
	ds_read_b128 v[150:153], v134 offset:3072
	ds_read_b128 v[154:157], v187
	ds_read_b128 v[158:161], v187 offset:1024
	ds_read_b128 v[188:191], v186
	ds_read_b128 v[192:195], v186 offset:1024
	ds_read_b128 v[196:199], v185
	ds_read_b128 v[200:203], v185 offset:1024
	ds_read_b128 v[204:207], v184
	ds_read_b128 v[208:211], v184 offset:1024
	global_load_lds_dwordx4 v[128:129], off
	v_lshl_add_u64 v[128:129], s[18:19], 0, v[164:165]
	s_mov_b32 m0, s15
	s_nop 0
	global_load_lds_dwordx4 v[128:129], off
	s_waitcnt vmcnt(10)
	s_barrier
	s_waitcnt lgkmcnt(0)
	s_setprio 1
	s_waitcnt lgkmcnt(0)
	v_mfma_f32_16x16x32_bf16 v[124:127], v[138:141], v[154:157], v[124:127]
	v_mfma_f32_16x16x32_bf16 v[120:123], v[146:149], v[154:157], v[120:123]
	v_mfma_f32_16x16x32_bf16 v[116:119], v[138:141], v[188:191], v[116:119]
	v_mfma_f32_16x16x32_bf16 v[112:115], v[146:149], v[188:191], v[112:115]
	v_mfma_f32_16x16x32_bf16 v[108:111], v[138:141], v[196:199], v[108:111]
	v_mfma_f32_16x16x32_bf16 v[104:107], v[146:149], v[196:199], v[104:107]
	v_mfma_f32_16x16x32_bf16 v[100:103], v[138:141], v[204:207], v[100:103]
	v_mfma_f32_16x16x32_bf16 v[96:99], v[146:149], v[204:207], v[96:99]
	v_mfma_f32_16x16x32_bf16 v[124:127], v[142:145], v[158:161], v[124:127]
	v_mfma_f32_16x16x32_bf16 v[120:123], v[150:153], v[158:161], v[120:123]
	v_mfma_f32_16x16x32_bf16 v[116:119], v[142:145], v[192:195], v[116:119]
	v_mfma_f32_16x16x32_bf16 v[112:115], v[150:153], v[192:195], v[112:115]
	v_mfma_f32_16x16x32_bf16 v[108:111], v[142:145], v[200:203], v[108:111]
	v_mfma_f32_16x16x32_bf16 v[104:107], v[150:153], v[200:203], v[104:107]
	v_mfma_f32_16x16x32_bf16 v[100:103], v[142:145], v[208:211], v[100:103]
	v_mfma_f32_16x16x32_bf16 v[96:99], v[150:153], v[208:211], v[96:99]
	s_setprio 0
	s_barrier
	ds_read_b128 v[132:135], v131
	ds_read_b128 v[212:215], v131 offset:1024
	ds_read_b128 v[216:219], v131 offset:2048
	ds_read_b128 v[220:223], v131 offset:3072
	s_barrier
	s_waitcnt lgkmcnt(0)
	s_setprio 1
	s_waitcnt lgkmcnt(0)
	v_mfma_f32_16x16x32_bf16 v[92:95], v[132:135], v[154:157], v[92:95]
	v_mfma_f32_16x16x32_bf16 v[88:91], v[216:219], v[154:157], v[88:91]
	v_mfma_f32_16x16x32_bf16 v[84:87], v[132:135], v[188:191], v[84:87]
	v_mfma_f32_16x16x32_bf16 v[80:83], v[216:219], v[188:191], v[80:83]
	v_mfma_f32_16x16x32_bf16 v[76:79], v[132:135], v[196:199], v[76:79]
	v_mfma_f32_16x16x32_bf16 v[72:75], v[216:219], v[196:199], v[72:75]
	v_mfma_f32_16x16x32_bf16 v[68:71], v[132:135], v[204:207], v[68:71]
	v_mfma_f32_16x16x32_bf16 v[64:67], v[216:219], v[204:207], v[64:67]
	v_mfma_f32_16x16x32_bf16 v[154:157], v[212:215], v[158:161], v[92:95]
	v_mfma_f32_16x16x32_bf16 v[158:161], v[220:223], v[158:161], v[88:91]
	v_mfma_f32_16x16x32_bf16 v[188:191], v[212:215], v[192:195], v[84:87]
	v_mfma_f32_16x16x32_bf16 v[192:195], v[220:223], v[192:195], v[80:83]
	v_mfma_f32_16x16x32_bf16 v[196:199], v[212:215], v[200:203], v[76:79]
	v_mfma_f32_16x16x32_bf16 v[200:203], v[220:223], v[200:203], v[72:75]
	v_mfma_f32_16x16x32_bf16 v[204:207], v[212:215], v[208:211], v[68:71]
	v_mfma_f32_16x16x32_bf16 v[208:211], v[220:223], v[208:211], v[64:67]
	s_setprio 0
	s_barrier
	s_nop 0
	ds_read_b128 v[64:67], v187 offset:16384
	ds_read_b128 v[68:71], v187 offset:17408
	ds_read_b128 v[72:75], v186 offset:16384
	ds_read_b128 v[76:79], v186 offset:17408
	ds_read_b128 v[80:83], v185 offset:16384
	ds_read_b128 v[84:87], v185 offset:17408
	ds_read_b128 v[88:91], v184 offset:16384
	ds_read_b128 v[92:95], v184 offset:17408
	s_waitcnt vmcnt(4)
	s_barrier
	s_waitcnt lgkmcnt(0)
	s_setprio 1
	s_waitcnt lgkmcnt(0)
	v_mfma_f32_16x16x32_bf16 v[60:63], v[138:141], v[64:67], v[60:63]
	v_mfma_f32_16x16x32_bf16 v[56:59], v[146:149], v[64:67], v[56:59]
	v_mfma_f32_16x16x32_bf16 v[52:55], v[138:141], v[72:75], v[52:55]
	v_mfma_f32_16x16x32_bf16 v[48:51], v[146:149], v[72:75], v[48:51]
	v_mfma_f32_16x16x32_bf16 v[224:227], v[138:141], v[80:83], v[44:47]
	v_mfma_f32_16x16x32_bf16 v[228:231], v[146:149], v[80:83], v[40:43]
	v_mfma_f32_16x16x32_bf16 v[138:141], v[138:141], v[88:91], v[36:39]
	v_mfma_f32_16x16x32_bf16 v[146:149], v[146:149], v[88:91], v[32:35]
	v_mfma_f32_16x16x32_bf16 v[32:35], v[142:145], v[68:71], v[60:63]
	v_mfma_f32_16x16x32_bf16 v[36:39], v[150:153], v[68:71], v[56:59]
	v_mfma_f32_16x16x32_bf16 v[40:43], v[142:145], v[76:79], v[52:55]
	v_mfma_f32_16x16x32_bf16 v[44:47], v[150:153], v[76:79], v[48:51]
	v_mfma_f32_16x16x32_bf16 v[48:51], v[142:145], v[84:87], v[224:227]
	v_mfma_f32_16x16x32_bf16 v[52:55], v[150:153], v[84:87], v[228:231]
	v_mfma_f32_16x16x32_bf16 v[56:59], v[142:145], v[92:95], v[138:141]
	v_mfma_f32_16x16x32_bf16 v[60:63], v[150:153], v[92:95], v[146:149]
	s_setprio 0
	s_setprio 1
	v_mfma_f32_16x16x32_bf16 v[28:31], v[132:135], v[64:67], v[28:31]
	v_mfma_f32_16x16x32_bf16 v[24:27], v[216:219], v[64:67], v[24:27]
	v_mfma_f32_16x16x32_bf16 v[20:23], v[132:135], v[72:75], v[20:23]
	v_mfma_f32_16x16x32_bf16 v[16:19], v[216:219], v[72:75], v[16:19]
	v_mfma_f32_16x16x32_bf16 v[64:67], v[132:135], v[80:83], v[12:15]
	v_mfma_f32_16x16x32_bf16 v[8:11], v[216:219], v[80:83], v[8:11]
	v_mfma_f32_16x16x32_bf16 v[72:75], v[132:135], v[88:91], v[4:7]
	v_mfma_f32_16x16x32_bf16 v[0:3], v[216:219], v[88:91], v[0:3]
	v_mfma_f32_16x16x32_bf16 v[4:7], v[212:215], v[68:71], v[28:31]
	v_mfma_f32_16x16x32_bf16 v[12:15], v[220:223], v[68:71], v[24:27]
	v_mfma_f32_16x16x32_bf16 v[20:23], v[212:215], v[76:79], v[20:23]
	v_mfma_f32_16x16x32_bf16 v[28:31], v[220:223], v[76:79], v[16:19]
	v_mfma_f32_16x16x32_bf16 v[64:67], v[212:215], v[84:87], v[64:67]
	v_mfma_f32_16x16x32_bf16 v[68:71], v[220:223], v[84:87], v[8:11]
	v_mfma_f32_16x16x32_bf16 v[72:75], v[212:215], v[92:95], v[72:75]
	v_mfma_f32_16x16x32_bf16 v[76:79], v[220:223], v[92:95], v[0:3]
	s_setprio 0
	s_barrier
	ds_read_b128 v[8:11], v130
	ds_read_b128 v[0:3], v130 offset:1024
	ds_read_b128 v[16:19], v130 offset:2048
	ds_read_b128 v[80:83], v130 offset:3072
	ds_read_b128 v[138:141], v187 offset:32768
	ds_read_b128 v[212:215], v187 offset:33792
	ds_read_b128 v[216:219], v186 offset:32768
	ds_read_b128 v[220:223], v186 offset:33792
	ds_read_b128 v[224:227], v185 offset:32768
	ds_read_b128 v[228:231], v185 offset:33792
	ds_read_b128 v[232:235], v184 offset:32768
	ds_read_b128 v[236:239], v184 offset:33792
	s_waitcnt vmcnt(2)
	s_barrier
	s_waitcnt lgkmcnt(0)
	s_setprio 1
	s_waitcnt lgkmcnt(0)
	v_mfma_f32_16x16x32_bf16 v[24:27], v[8:11], v[138:141], v[124:127]
	v_mfma_f32_16x16x32_bf16 v[84:87], v[16:19], v[138:141], v[120:123]
	v_mfma_f32_16x16x32_bf16 v[88:91], v[8:11], v[216:219], v[116:119]
	v_mfma_f32_16x16x32_bf16 v[92:95], v[16:19], v[216:219], v[112:115]
	v_mfma_f32_16x16x32_bf16 v[108:111], v[8:11], v[224:227], v[108:111]
	v_mfma_f32_16x16x32_bf16 v[104:107], v[16:19], v[224:227], v[104:107]
	v_mfma_f32_16x16x32_bf16 v[100:103], v[8:11], v[232:235], v[100:103]
	v_mfma_f32_16x16x32_bf16 v[96:99], v[16:19], v[232:235], v[96:99]
	v_mfma_f32_16x16x32_bf16 v[148:151], v[0:3], v[212:215], v[24:27]
	v_mfma_f32_16x16x32_bf16 v[144:147], v[80:83], v[212:215], v[84:87]
	v_mfma_f32_16x16x32_bf16 v[132:135], v[0:3], v[220:223], v[88:91]
	v_mfma_f32_16x16x32_bf16 v[128:131], v[80:83], v[220:223], v[92:95]
	v_mfma_f32_16x16x32_bf16 v[116:119], v[0:3], v[228:231], v[108:111]
	v_mfma_f32_16x16x32_bf16 v[112:115], v[80:83], v[228:231], v[104:107]
	v_mfma_f32_16x16x32_bf16 v[100:103], v[0:3], v[236:239], v[100:103]
	v_mfma_f32_16x16x32_bf16 v[24:27], v[80:83], v[236:239], v[96:99]
	s_setprio 0
	s_barrier
	ds_read_b128 v[92:95], v136
	ds_read_b128 v[84:87], v136 offset:1024
	ds_read_b128 v[96:99], v136 offset:2048
	ds_read_b128 v[88:91], v136 offset:3072
	s_waitcnt vmcnt(0)
	s_barrier
	s_waitcnt lgkmcnt(0)
	s_setprio 1
	s_waitcnt lgkmcnt(0)
	v_mfma_f32_16x16x32_bf16 v[104:107], v[92:95], v[138:141], v[154:157]
	v_mfma_f32_16x16x32_bf16 v[108:111], v[96:99], v[138:141], v[158:161]
	v_mfma_f32_16x16x32_bf16 v[120:123], v[92:95], v[216:219], v[188:191]
	v_mfma_f32_16x16x32_bf16 v[124:127], v[96:99], v[216:219], v[192:195]
	v_mfma_f32_16x16x32_bf16 v[160:163], v[92:95], v[224:227], v[196:199]
	v_mfma_f32_16x16x32_bf16 v[188:191], v[96:99], v[224:227], v[200:203]
	v_mfma_f32_16x16x32_bf16 v[192:195], v[92:95], v[232:235], v[204:207]
	v_mfma_f32_16x16x32_bf16 v[196:199], v[96:99], v[232:235], v[208:211]
	v_mfma_f32_16x16x32_bf16 v[156:159], v[84:87], v[212:215], v[104:107]
	v_mfma_f32_16x16x32_bf16 v[152:155], v[88:91], v[212:215], v[108:111]
	v_mfma_f32_16x16x32_bf16 v[140:143], v[84:87], v[220:223], v[120:123]
	v_mfma_f32_16x16x32_bf16 v[136:139], v[88:91], v[220:223], v[124:127]
	v_mfma_f32_16x16x32_bf16 v[124:127], v[84:87], v[228:231], v[160:163]
	v_mfma_f32_16x16x32_bf16 v[120:123], v[88:91], v[228:231], v[188:191]
	v_mfma_f32_16x16x32_bf16 v[108:111], v[84:87], v[236:239], v[192:195]
	v_mfma_f32_16x16x32_bf16 v[104:107], v[88:91], v[236:239], v[196:199]
	s_setprio 0
	s_barrier
	v_mbcnt_lo_u32_b32 v164, -1, 0
	v_mbcnt_hi_u32_b32 v164, -1, v164
	s_cmp_lt_i32 s64, 3
	v_add_u32_e32 v160, s34, v164
	v_ashrrev_i32_e32 v192, 6, v160
	v_bfe_u32 v190, v160, 8, 1
	v_and_b32_e32 v191, 3, v192
	v_and_b32_e32 v188, 15, v164
	v_bfe_u32 v189, v160, 4, 2
	s_mov_b64 s[18:19], 0
	s_cbranch_scc1 .LBB0_362
	v_lshrrev_b32_e32 v160, 4, v160
	v_lshlrev_b32_e32 v162, 9, v189
	v_lshlrev_b32_e32 v163, 9, v160
	s_mov_b64 s[20:21], -1
	s_cmp_gt_i32 s64, 3
	v_lshlrev_b32_e32 v161, 4, v188
	v_and_b32_e32 v160, 0x400, v162
	v_and_b32_e32 v162, 0x200, v163
	s_cbranch_scc0 .LBB0_360
	s_lshl_b32 s15, s66, 20
	s_lshl_b32 s20, s66, 16
	s_and_b32 s15, s15, 0xff000000
	s_and_b32 s20, s20, 0xf0000
	s_lshl_b32 s17, s68, 21
	s_or_b32 s15, s20, s15
	v_lshlrev_b32_e32 v163, 14, v191
	s_add_i32 s15, s15, s17
	v_lshlrev_b32_e32 v166, 12, v190
	v_or3_b32 v163, s15, v161, v163
	v_or3_b32 v163, v163, v166, v162
	v_add_u32_e32 v166, v163, v160
	s_mov_b64 s[20:21], 0

.LBB0_465:
	ds_read_b128 v[164:167], v162
	ds_read_b128 v[168:171], v162 offset:1024
	ds_read_b128 v[172:175], v162 offset:2048
	ds_read_b128 v[176:179], v162 offset:3072
	ds_read_b128 v[180:183], v153
	ds_read_b128 v[184:187], v153 offset:1024
	ds_read_b128 v[188:191], v152
	ds_read_b128 v[192:195], v152 offset:1024
	ds_read_b128 v[196:199], v151
	ds_read_b128 v[200:203], v151 offset:1024
	ds_read_b128 v[204:207], v150
	ds_read_b128 v[208:211], v150 offset:1024
	s_waitcnt lgkmcnt(8)
	s_waitcnt vmcnt(10)
	s_barrier
	s_waitcnt lgkmcnt(0)
	s_waitcnt lgkmcnt(0)
	v_mfma_f32_16x16x32_bf16 v[124:127], v[164:167], v[180:183], v[124:127]
	v_mfma_f32_16x16x32_bf16 v[120:123], v[172:175], v[180:183], v[120:123]
	v_mfma_f32_16x16x32_bf16 v[116:119], v[164:167], v[188:191], v[116:119]
	v_mfma_f32_16x16x32_bf16 v[112:115], v[172:175], v[188:191], v[112:115]
	v_mfma_f32_16x16x32_bf16 v[108:111], v[164:167], v[196:199], v[108:111]
	v_mfma_f32_16x16x32_bf16 v[104:107], v[172:175], v[196:199], v[104:107]
	v_mfma_f32_16x16x32_bf16 v[100:103], v[164:167], v[204:207], v[100:103]
	v_mfma_f32_16x16x32_bf16 v[96:99], v[172:175], v[204:207], v[96:99]
	v_mfma_f32_16x16x32_bf16 v[124:127], v[168:171], v[184:187], v[124:127]
	v_mfma_f32_16x16x32_bf16 v[120:123], v[176:179], v[184:187], v[120:123]
	v_mfma_f32_16x16x32_bf16 v[116:119], v[168:171], v[192:195], v[116:119]
	v_mfma_f32_16x16x32_bf16 v[112:115], v[176:179], v[192:195], v[112:115]
	v_mfma_f32_16x16x32_bf16 v[108:111], v[168:171], v[200:203], v[108:111]
	v_mfma_f32_16x16x32_bf16 v[104:107], v[176:179], v[200:203], v[104:107]
	v_mfma_f32_16x16x32_bf16 v[100:103], v[168:171], v[208:211], v[100:103]
	v_mfma_f32_16x16x32_bf16 v[96:99], v[176:179], v[208:211], v[96:99]
	s_barrier
	v_lshl_add_u64 v[230:231], s[50:51], 0, v[130:131]
	s_mov_b64 s[68:69], 0x3880000
	v_readfirstlane_b32 s36, v149
	v_lshl_add_u64 v[232:233], v[230:231], 0, s[68:69]
	s_mov_b32 m0, s36
	s_mov_b64 s[68:69], 0x3881000
	v_readfirstlane_b32 s36, v148
	ds_read_b128 v[212:215], v159
	ds_read_b128 v[216:219], v159 offset:1024
	ds_read_b128 v[220:223], v159 offset:2048
	ds_read_b128 v[224:227], v159 offset:3072
	global_load_lds_dwordx4 v[232:233], off
	v_lshl_add_u64 v[232:233], v[230:231], 0, s[68:69]
	s_mov_b32 m0, s36
	s_nop 0
	global_load_lds_dwordx4 v[232:233], off
	s_mov_b64 s[68:69], 0xe000100
	v_readfirstlane_b32 s36, v135
	v_lshl_add_u64 v[232:233], v[228:229], 0, s[68:69]
	s_mov_b32 m0, s36
	s_mov_b64 s[68:69], 0xe040100
	v_readfirstlane_b32 s36, v147
	global_load_lds_dwordx4 v[232:233], off
	v_lshl_add_u64 v[232:233], v[228:229], 0, s[68:69]
	s_mov_b32 m0, s36
	s_nop 0
	global_load_lds_dwordx4 v[232:233], off
	s_waitcnt vmcnt(12)
	s_barrier
	s_waitcnt lgkmcnt(0)
	s_waitcnt lgkmcnt(0)
	v_mfma_f32_16x16x32_bf16 v[92:95], v[212:215], v[180:183], v[92:95]
	v_mfma_f32_16x16x32_bf16 v[88:91], v[220:223], v[180:183], v[88:91]
	v_mfma_f32_16x16x32_bf16 v[84:87], v[212:215], v[188:191], v[84:87]
	v_mfma_f32_16x16x32_bf16 v[80:83], v[220:223], v[188:191], v[80:83]
	v_mfma_f32_16x16x32_bf16 v[76:79], v[212:215], v[196:199], v[76:79]
	v_mfma_f32_16x16x32_bf16 v[72:75], v[220:223], v[196:199], v[72:75]
	v_mfma_f32_16x16x32_bf16 v[68:71], v[212:215], v[204:207], v[68:71]
	v_mfma_f32_16x16x32_bf16 v[64:67], v[220:223], v[204:207], v[64:67]
	v_mfma_f32_16x16x32_bf16 v[92:95], v[216:219], v[184:187], v[92:95]
	v_mfma_f32_16x16x32_bf16 v[88:91], v[224:227], v[184:187], v[88:91]
	v_mfma_f32_16x16x32_bf16 v[84:87], v[216:219], v[192:195], v[84:87]
	v_mfma_f32_16x16x32_bf16 v[80:83], v[224:227], v[192:195], v[80:83]
	v_mfma_f32_16x16x32_bf16 v[76:79], v[216:219], v[200:203], v[76:79]
	v_mfma_f32_16x16x32_bf16 v[72:75], v[224:227], v[200:203], v[72:75]
	v_mfma_f32_16x16x32_bf16 v[68:71], v[216:219], v[208:211], v[68:71]
	v_mfma_f32_16x16x32_bf16 v[64:67], v[224:227], v[208:211], v[64:67]
	s_barrier
	ds_read_b128 v[180:183], v153 offset:16384
	ds_read_b128 v[184:187], v153 offset:17408
	ds_read_b128 v[188:191], v152 offset:16384
	ds_read_b128 v[192:195], v152 offset:17408
	ds_read_b128 v[196:199], v151 offset:16384
	ds_read_b128 v[200:203], v151 offset:17408
	ds_read_b128 v[204:207], v150 offset:16384
	ds_read_b128 v[208:211], v150 offset:17408
	s_mov_b64 s[68:69], 0x3882000
	v_readfirstlane_b32 s36, v146
	v_lshl_add_u64 v[232:233], v[230:231], 0, s[68:69]
	s_mov_b32 m0, s36
	s_mov_b64 s[68:69], 0x3883000
	v_readfirstlane_b32 s36, v145
	global_load_lds_dwordx4 v[232:233], off
	v_lshl_add_u64 v[232:233], v[230:231], 0, s[68:69]
	s_mov_b32 m0, s36
	s_nop 0
	global_load_lds_dwordx4 v[232:233], off
	s_barrier
	s_waitcnt lgkmcnt(0)
	s_waitcnt lgkmcnt(0)
	v_mfma_f32_16x16x32_bf16 v[60:63], v[164:167], v[180:183], v[60:63]
	v_mfma_f32_16x16x32_bf16 v[56:59], v[172:175], v[180:183], v[56:59]
	v_mfma_f32_16x16x32_bf16 v[52:55], v[164:167], v[188:191], v[52:55]
	v_mfma_f32_16x16x32_bf16 v[48:51], v[172:175], v[188:191], v[48:51]
	v_mfma_f32_16x16x32_bf16 v[44:47], v[164:167], v[196:199], v[44:47]
	v_mfma_f32_16x16x32_bf16 v[40:43], v[172:175], v[196:199], v[40:43]
	v_mfma_f32_16x16x32_bf16 v[36:39], v[164:167], v[204:207], v[36:39]
	v_mfma_f32_16x16x32_bf16 v[32:35], v[172:175], v[204:207], v[32:35]
	v_mfma_f32_16x16x32_bf16 v[60:63], v[168:171], v[184:187], v[60:63]
	v_mfma_f32_16x16x32_bf16 v[56:59], v[176:179], v[184:187], v[56:59]
	v_mfma_f32_16x16x32_bf16 v[52:55], v[168:171], v[192:195], v[52:55]
	v_mfma_f32_16x16x32_bf16 v[48:51], v[176:179], v[192:195], v[48:51]
	v_mfma_f32_16x16x32_bf16 v[44:47], v[168:171], v[200:203], v[44:47]
	v_mfma_f32_16x16x32_bf16 v[40:43], v[176:179], v[200:203], v[40:43]
	v_mfma_f32_16x16x32_bf16 v[36:39], v[168:171], v[208:211], v[36:39]
	v_mfma_f32_16x16x32_bf16 v[32:35], v[176:179], v[208:211], v[32:35]
	s_barrier
	v_readfirstlane_b32 s36, v144
	v_lshl_add_u64 v[166:167], v[228:229], 0, s[26:27]
	s_mov_b32 m0, s36
	v_readfirstlane_b32 s36, v143
	global_load_lds_dwordx4 v[166:167], off
	v_lshl_add_u64 v[166:167], v[228:229], 0, s[28:29]
	s_mov_b32 m0, s36
	s_nop 0
	global_load_lds_dwordx4 v[166:167], off
	s_waitcnt vmcnt(12)
	s_barrier
	v_mfma_f32_16x16x32_bf16 v[28:31], v[212:215], v[180:183], v[28:31]
	v_mfma_f32_16x16x32_bf16 v[24:27], v[220:223], v[180:183], v[24:27]
	v_mfma_f32_16x16x32_bf16 v[20:23], v[212:215], v[188:191], v[20:23]
	v_mfma_f32_16x16x32_bf16 v[16:19], v[220:223], v[188:191], v[16:19]
	v_mfma_f32_16x16x32_bf16 v[12:15], v[212:215], v[196:199], v[12:15]
	v_mfma_f32_16x16x32_bf16 v[8:11], v[220:223], v[196:199], v[8:11]
	v_mfma_f32_16x16x32_bf16 v[4:7], v[212:215], v[204:207], v[4:7]
	v_mfma_f32_16x16x32_bf16 v[0:3], v[220:223], v[204:207], v[0:3]
	v_mfma_f32_16x16x32_bf16 v[28:31], v[216:219], v[184:187], v[28:31]
	v_mfma_f32_16x16x32_bf16 v[24:27], v[224:227], v[184:187], v[24:27]
	v_mfma_f32_16x16x32_bf16 v[20:23], v[216:219], v[192:195], v[20:23]
	v_mfma_f32_16x16x32_bf16 v[16:19], v[224:227], v[192:195], v[16:19]
	v_mfma_f32_16x16x32_bf16 v[12:15], v[216:219], v[200:203], v[12:15]
	v_mfma_f32_16x16x32_bf16 v[8:11], v[224:227], v[200:203], v[8:11]
	v_mfma_f32_16x16x32_bf16 v[4:7], v[216:219], v[208:211], v[4:7]
	v_mfma_f32_16x16x32_bf16 v[0:3], v[224:227], v[208:211], v[0:3]
	s_barrier
	ds_read_b128 v[164:167], v155
	ds_read_b128 v[168:171], v155 offset:1024
	ds_read_b128 v[172:175], v155 offset:2048
	ds_read_b128 v[176:179], v155 offset:3072
	ds_read_b128 v[180:183], v153 offset:32768
	ds_read_b128 v[184:187], v153 offset:33792
	ds_read_b128 v[188:191], v152 offset:32768
	ds_read_b128 v[192:195], v152 offset:33792
	ds_read_b128 v[196:199], v151 offset:32768
	ds_read_b128 v[200:203], v151 offset:33792
	ds_read_b128 v[204:207], v150 offset:32768
	ds_read_b128 v[208:211], v150 offset:33792
	s_waitcnt lgkmcnt(8)
	s_waitcnt vmcnt(10)
	s_barrier
	s_waitcnt lgkmcnt(0)
	s_waitcnt lgkmcnt(0)
	v_mfma_f32_16x16x32_bf16 v[124:127], v[164:167], v[180:183], v[124:127]
	v_mfma_f32_16x16x32_bf16 v[120:123], v[172:175], v[180:183], v[120:123]
	v_mfma_f32_16x16x32_bf16 v[116:119], v[164:167], v[188:191], v[116:119]
	v_mfma_f32_16x16x32_bf16 v[112:115], v[172:175], v[188:191], v[112:115]
	v_mfma_f32_16x16x32_bf16 v[108:111], v[164:167], v[196:199], v[108:111]
	v_mfma_f32_16x16x32_bf16 v[104:107], v[172:175], v[196:199], v[104:107]
	v_mfma_f32_16x16x32_bf16 v[100:103], v[164:167], v[204:207], v[100:103]
	v_mfma_f32_16x16x32_bf16 v[96:99], v[172:175], v[204:207], v[96:99]
	v_mfma_f32_16x16x32_bf16 v[124:127], v[168:171], v[184:187], v[124:127]
	v_mfma_f32_16x16x32_bf16 v[120:123], v[176:179], v[184:187], v[120:123]
	v_mfma_f32_16x16x32_bf16 v[116:119], v[168:171], v[192:195], v[116:119]
	v_mfma_f32_16x16x32_bf16 v[112:115], v[176:179], v[192:195], v[112:115]
	v_mfma_f32_16x16x32_bf16 v[108:111], v[168:171], v[200:203], v[108:111]
	v_mfma_f32_16x16x32_bf16 v[104:107], v[176:179], v[200:203], v[104:107]
	v_mfma_f32_16x16x32_bf16 v[100:103], v[168:171], v[208:211], v[100:103]
	v_mfma_f32_16x16x32_bf16 v[96:99], v[176:179], v[208:211], v[96:99]
	s_barrier
	v_readfirstlane_b32 s36, v142
	v_lshl_add_u64 v[232:233], v[230:231], 0, s[30:31]
	s_mov_b32 m0, s36
	v_readfirstlane_b32 s36, v141
	ds_read_b128 v[212:215], v154
	ds_read_b128 v[216:219], v154 offset:1024
	ds_read_b128 v[220:223], v154 offset:2048
	ds_read_b128 v[224:227], v154 offset:3072
	global_load_lds_dwordx4 v[232:233], off
	v_lshl_add_u64 v[232:233], v[230:231], 0, s[34:35]
	s_mov_b32 m0, s36
	s_nop 0
	global_load_lds_dwordx4 v[232:233], off
	v_readfirstlane_b32 s36, v140
	v_lshl_add_u64 v[232:233], v[228:229], 0, s[44:45]
	s_mov_b32 m0, s36
	v_readfirstlane_b32 s36, v139
	global_load_lds_dwordx4 v[232:233], off
	v_lshl_add_u64 v[228:229], v[228:229], 0, s[46:47]
	s_mov_b32 m0, s36
	s_nop 0
	global_load_lds_dwordx4 v[228:229], off
	s_waitcnt vmcnt(12)
	s_barrier
	s_waitcnt lgkmcnt(0)
	s_waitcnt lgkmcnt(0)
	v_mfma_f32_16x16x32_bf16 v[92:95], v[212:215], v[180:183], v[92:95]
	v_mfma_f32_16x16x32_bf16 v[88:91], v[220:223], v[180:183], v[88:91]
	v_mfma_f32_16x16x32_bf16 v[84:87], v[212:215], v[188:191], v[84:87]
	v_mfma_f32_16x16x32_bf16 v[80:83], v[220:223], v[188:191], v[80:83]
	v_mfma_f32_16x16x32_bf16 v[76:79], v[212:215], v[196:199], v[76:79]
	v_mfma_f32_16x16x32_bf16 v[72:75], v[220:223], v[196:199], v[72:75]
	v_mfma_f32_16x16x32_bf16 v[68:71], v[212:215], v[204:207], v[68:71]
	v_mfma_f32_16x16x32_bf16 v[64:67], v[220:223], v[204:207], v[64:67]
	v_mfma_f32_16x16x32_bf16 v[92:95], v[216:219], v[184:187], v[92:95]
	v_mfma_f32_16x16x32_bf16 v[88:91], v[224:227], v[184:187], v[88:91]
	v_mfma_f32_16x16x32_bf16 v[84:87], v[216:219], v[192:195], v[84:87]
	v_mfma_f32_16x16x32_bf16 v[80:83], v[224:227], v[192:195], v[80:83]
	v_mfma_f32_16x16x32_bf16 v[76:79], v[216:219], v[200:203], v[76:79]
	v_mfma_f32_16x16x32_bf16 v[72:75], v[224:227], v[200:203], v[72:75]
	v_mfma_f32_16x16x32_bf16 v[68:71], v[216:219], v[208:211], v[68:71]
	v_mfma_f32_16x16x32_bf16 v[64:67], v[224:227], v[208:211], v[64:67]
	s_barrier
	ds_read_b128 v[180:183], v153 offset:49152
	ds_read_b128 v[184:187], v153 offset:50176
	ds_read_b128 v[188:191], v152 offset:49152
	ds_read_b128 v[192:195], v152 offset:50176
	ds_read_b128 v[196:199], v151 offset:49152
	ds_read_b128 v[200:203], v151 offset:50176
	ds_read_b128 v[204:207], v150 offset:49152
	ds_read_b128 v[208:211], v150 offset:50176
	v_readfirstlane_b32 s36, v138
	v_lshl_add_u64 v[232:233], v[230:231], 0, s[56:57]
	s_mov_b32 m0, s36
	v_readfirstlane_b32 s36, v137
	global_load_lds_dwordx4 v[232:233], off
	v_lshl_add_u64 v[232:233], v[230:231], 0, s[58:59]
	s_mov_b32 m0, s36
	s_nop 0
	global_load_lds_dwordx4 v[232:233], off
	s_barrier
	s_waitcnt lgkmcnt(0)
	s_waitcnt lgkmcnt(0)
	v_mfma_f32_16x16x32_bf16 v[60:63], v[164:167], v[180:183], v[60:63]
	v_mfma_f32_16x16x32_bf16 v[56:59], v[172:175], v[180:183], v[56:59]
	v_mfma_f32_16x16x32_bf16 v[52:55], v[164:167], v[188:191], v[52:55]
	v_mfma_f32_16x16x32_bf16 v[48:51], v[172:175], v[188:191], v[48:51]
	v_mfma_f32_16x16x32_bf16 v[44:47], v[164:167], v[196:199], v[44:47]
	v_mfma_f32_16x16x32_bf16 v[40:43], v[172:175], v[196:199], v[40:43]
	v_mfma_f32_16x16x32_bf16 v[36:39], v[164:167], v[204:207], v[36:39]
	v_mfma_f32_16x16x32_bf16 v[32:35], v[172:175], v[204:207], v[32:35]
	v_mfma_f32_16x16x32_bf16 v[60:63], v[168:171], v[184:187], v[60:63]
	v_mfma_f32_16x16x32_bf16 v[56:59], v[176:179], v[184:187], v[56:59]
	v_mfma_f32_16x16x32_bf16 v[52:55], v[168:171], v[192:195], v[52:55]
	v_mfma_f32_16x16x32_bf16 v[48:51], v[176:179], v[192:195], v[48:51]
	v_mfma_f32_16x16x32_bf16 v[44:47], v[168:171], v[200:203], v[44:47]
	v_mfma_f32_16x16x32_bf16 v[40:43], v[176:179], v[200:203], v[40:43]
	v_mfma_f32_16x16x32_bf16 v[36:39], v[168:171], v[208:211], v[36:39]
	v_mfma_f32_16x16x32_bf16 v[32:35], v[176:179], v[208:211], v[32:35]
	s_barrier
	v_lshl_add_u64 v[132:133], v[132:133], 0, s[60:61]
	v_lshl_add_u64 v[228:229], s[50:51], 0, v[132:133]
	s_mov_b64 s[68:69], 0xe080080
	v_readfirstlane_b32 s36, v161
	v_lshl_add_u64 v[166:167], v[228:229], 0, s[68:69]
	s_mov_b32 m0, s36
	s_mov_b64 s[68:69], 0xe0c0080
	v_readfirstlane_b32 s36, v160
	global_load_lds_dwordx4 v[166:167], off
	v_lshl_add_u64 v[166:167], v[228:229], 0, s[68:69]
	s_mov_b32 m0, s36
	s_nop 0
	global_load_lds_dwordx4 v[166:167], off
	s_waitcnt vmcnt(12)
	s_barrier
	v_mfma_f32_16x16x32_bf16 v[28:31], v[212:215], v[180:183], v[28:31]
	v_mfma_f32_16x16x32_bf16 v[24:27], v[220:223], v[180:183], v[24:27]
	v_mfma_f32_16x16x32_bf16 v[20:23], v[212:215], v[188:191], v[20:23]
	v_mfma_f32_16x16x32_bf16 v[16:19], v[220:223], v[188:191], v[16:19]
	v_mfma_f32_16x16x32_bf16 v[12:15], v[212:215], v[196:199], v[12:15]
	v_mfma_f32_16x16x32_bf16 v[8:11], v[220:223], v[196:199], v[8:11]
	v_mfma_f32_16x16x32_bf16 v[4:7], v[212:215], v[204:207], v[4:7]
	v_mfma_f32_16x16x32_bf16 v[0:3], v[220:223], v[204:207], v[0:3]
	v_mfma_f32_16x16x32_bf16 v[28:31], v[216:219], v[184:187], v[28:31]
	v_mfma_f32_16x16x32_bf16 v[24:27], v[224:227], v[184:187], v[24:27]
	v_mfma_f32_16x16x32_bf16 v[20:23], v[216:219], v[192:195], v[20:23]
	v_mfma_f32_16x16x32_bf16 v[16:19], v[224:227], v[192:195], v[16:19]
	v_mfma_f32_16x16x32_bf16 v[12:15], v[216:219], v[200:203], v[12:15]
	v_mfma_f32_16x16x32_bf16 v[8:11], v[224:227], v[200:203], v[8:11]
	v_mfma_f32_16x16x32_bf16 v[4:7], v[216:219], v[208:211], v[4:7]
	v_mfma_f32_16x16x32_bf16 v[0:3], v[224:227], v[208:211], v[0:3]
	s_add_i32 s24, s24, 2
	v_lshl_add_u64 v[130:131], v[130:131], 0, s[10:11]
	s_cmp_lt_u32 s24, 28
	s_barrier
	s_cbranch_scc1 .LBB0_465
	s_lshl_b32 s24, s86, 5
	s_lshl_b32 s36, s86, 8
	s_and_b32 s24, s24, 0x1800
	s_and_b32 s36, s36, 0x700
	s_or_b32 s24, s36, s24
	v_lshlrev_b32_e32 v128, 3, v156
	v_lshlrev_b32_e32 v130, 5, v156
	v_and_b32_e32 v128, 0xffff0, v128
	v_and_b32_e32 v130, 32, v130
	s_lshl_b32 s36, s24, 12
	v_add_u32_e32 v130, v130, v158
	v_add_lshl_u32 v128, v157, v128, 12
	s_add_u32 s68, s70, s36
	v_lshl_add_u32 v128, v130, 1, v128
	s_addc_u32 s69, s71, 0
	v_lshl_add_u64 v[156:157], s[68:69], 0, v[128:129]
	v_readfirstlane_b32 s36, v161
	ds_read_b128 v[130:133], v162
	ds_read_b128 v[164:167], v162 offset:1024
	ds_read_b128 v[168:171], v162 offset:2048
	ds_read_b128 v[172:175], v162 offset:3072
	ds_read_b128 v[176:179], v153
	ds_read_b128 v[180:183], v153 offset:1024
	ds_read_b128 v[184:187], v152
	ds_read_b128 v[188:191], v152 offset:1024
	ds_read_b128 v[192:195], v151
	ds_read_b128 v[196:199], v151 offset:1024
	ds_read_b128 v[200:203], v150
	ds_read_b128 v[204:207], v150 offset:1024
	v_lshl_add_u64 v[162:163], v[156:157], 0, s[62:63]
	s_mov_b32 m0, s36
	v_readfirstlane_b32 s36, v160
	global_load_lds_dwordx4 v[162:163], off
	v_lshl_add_u64 v[156:157], v[156:157], 0, s[64:65]
	s_mov_b32 m0, s36
	s_nop 0
	global_load_lds_dwordx4 v[156:157], off
	s_waitcnt vmcnt(10)
	s_barrier
	s_waitcnt lgkmcnt(0)
	s_setprio 1
	s_waitcnt lgkmcnt(0)
	v_mfma_f32_16x16x32_bf16 v[124:127], v[130:133], v[176:179], v[124:127]
	v_mfma_f32_16x16x32_bf16 v[120:123], v[168:171], v[176:179], v[120:123]
	v_mfma_f32_16x16x32_bf16 v[116:119], v[130:133], v[184:187], v[116:119]
	v_mfma_f32_16x16x32_bf16 v[112:115], v[168:171], v[184:187], v[112:115]
	v_mfma_f32_16x16x32_bf16 v[108:111], v[130:133], v[192:195], v[108:111]
	v_mfma_f32_16x16x32_bf16 v[104:107], v[168:171], v[192:195], v[104:107]
	v_mfma_f32_16x16x32_bf16 v[100:103], v[130:133], v[200:203], v[100:103]
	v_mfma_f32_16x16x32_bf16 v[96:99], v[168:171], v[200:203], v[96:99]
	v_mfma_f32_16x16x32_bf16 v[124:127], v[164:167], v[180:183], v[124:127]
	v_mfma_f32_16x16x32_bf16 v[120:123], v[172:175], v[180:183], v[120:123]
	v_mfma_f32_16x16x32_bf16 v[116:119], v[164:167], v[188:191], v[116:119]
	v_mfma_f32_16x16x32_bf16 v[112:115], v[172:175], v[188:191], v[112:115]
	v_mfma_f32_16x16x32_bf16 v[108:111], v[164:167], v[196:199], v[108:111]
	v_mfma_f32_16x16x32_bf16 v[104:107], v[172:175], v[196:199], v[104:107]
	v_mfma_f32_16x16x32_bf16 v[100:103], v[164:167], v[204:207], v[100:103]
	v_mfma_f32_16x16x32_bf16 v[96:99], v[172:175], v[204:207], v[96:99]
	s_setprio 0
	s_barrier
	ds_read_b128 v[160:163], v159
	ds_read_b128 v[208:211], v159 offset:1024
	ds_read_b128 v[212:215], v159 offset:2048
	ds_read_b128 v[156:159], v159 offset:3072
	s_barrier
	s_waitcnt lgkmcnt(0)
	s_setprio 1
	s_waitcnt lgkmcnt(0)
	v_mfma_f32_16x16x32_bf16 v[92:95], v[160:163], v[176:179], v[92:95]
	v_mfma_f32_16x16x32_bf16 v[88:91], v[212:215], v[176:179], v[88:91]
	v_mfma_f32_16x16x32_bf16 v[84:87], v[160:163], v[184:187], v[84:87]
	v_mfma_f32_16x16x32_bf16 v[80:83], v[212:215], v[184:187], v[80:83]
	v_mfma_f32_16x16x32_bf16 v[76:79], v[160:163], v[192:195], v[76:79]
	v_mfma_f32_16x16x32_bf16 v[72:75], v[212:215], v[192:195], v[72:75]
	v_mfma_f32_16x16x32_bf16 v[68:71], v[160:163], v[200:203], v[68:71]
	v_mfma_f32_16x16x32_bf16 v[64:67], v[212:215], v[200:203], v[64:67]
	v_mfma_f32_16x16x32_bf16 v[176:179], v[208:211], v[180:183], v[92:95]
	v_mfma_f32_16x16x32_bf16 v[180:183], v[156:159], v[180:183], v[88:91]
	v_mfma_f32_16x16x32_bf16 v[184:187], v[208:211], v[188:191], v[84:87]
	v_mfma_f32_16x16x32_bf16 v[188:191], v[156:159], v[188:191], v[80:83]
	v_mfma_f32_16x16x32_bf16 v[192:195], v[208:211], v[196:199], v[76:79]
	v_mfma_f32_16x16x32_bf16 v[196:199], v[156:159], v[196:199], v[72:75]
	v_mfma_f32_16x16x32_bf16 v[200:203], v[208:211], v[204:207], v[68:71]
	v_mfma_f32_16x16x32_bf16 v[204:207], v[156:159], v[204:207], v[64:67]
	s_setprio 0
	s_barrier
	s_nop 0
	ds_read_b128 v[64:67], v153 offset:16384
	ds_read_b128 v[68:71], v153 offset:17408
	ds_read_b128 v[72:75], v152 offset:16384
	ds_read_b128 v[76:79], v152 offset:17408
	ds_read_b128 v[80:83], v151 offset:16384
	ds_read_b128 v[84:87], v151 offset:17408
	ds_read_b128 v[88:91], v150 offset:16384
	ds_read_b128 v[92:95], v150 offset:17408
	s_waitcnt vmcnt(4)
	s_barrier
	s_waitcnt lgkmcnt(0)
	s_setprio 1
	s_waitcnt lgkmcnt(0)
	v_mfma_f32_16x16x32_bf16 v[60:63], v[130:133], v[64:67], v[60:63]
	v_mfma_f32_16x16x32_bf16 v[56:59], v[168:171], v[64:67], v[56:59]
	v_mfma_f32_16x16x32_bf16 v[52:55], v[130:133], v[72:75], v[52:55]
	v_mfma_f32_16x16x32_bf16 v[48:51], v[168:171], v[72:75], v[48:51]
	v_mfma_f32_16x16x32_bf16 v[216:219], v[130:133], v[80:83], v[44:47]
	v_mfma_f32_16x16x32_bf16 v[220:223], v[168:171], v[80:83], v[40:43]
	v_mfma_f32_16x16x32_bf16 v[130:133], v[130:133], v[88:91], v[36:39]
	v_mfma_f32_16x16x32_bf16 v[168:171], v[168:171], v[88:91], v[32:35]
	v_mfma_f32_16x16x32_bf16 v[32:35], v[164:167], v[68:71], v[60:63]
	v_mfma_f32_16x16x32_bf16 v[36:39], v[172:175], v[68:71], v[56:59]
	v_mfma_f32_16x16x32_bf16 v[40:43], v[164:167], v[76:79], v[52:55]
	v_mfma_f32_16x16x32_bf16 v[44:47], v[172:175], v[76:79], v[48:51]
	v_mfma_f32_16x16x32_bf16 v[48:51], v[164:167], v[84:87], v[216:219]
	v_mfma_f32_16x16x32_bf16 v[52:55], v[172:175], v[84:87], v[220:223]
	v_mfma_f32_16x16x32_bf16 v[56:59], v[164:167], v[92:95], v[130:133]
	v_mfma_f32_16x16x32_bf16 v[60:63], v[172:175], v[92:95], v[168:171]
	s_setprio 0
	s_setprio 1
	v_mfma_f32_16x16x32_bf16 v[28:31], v[160:163], v[64:67], v[28:31]
	v_mfma_f32_16x16x32_bf16 v[24:27], v[212:215], v[64:67], v[24:27]
	v_mfma_f32_16x16x32_bf16 v[20:23], v[160:163], v[72:75], v[20:23]
	v_mfma_f32_16x16x32_bf16 v[64:67], v[212:215], v[72:75], v[16:19]
	v_mfma_f32_16x16x32_bf16 v[72:75], v[160:163], v[80:83], v[12:15]
	v_mfma_f32_16x16x32_bf16 v[8:11], v[212:215], v[80:83], v[8:11]
	v_mfma_f32_16x16x32_bf16 v[80:83], v[160:163], v[88:91], v[4:7]
	v_mfma_f32_16x16x32_bf16 v[0:3], v[212:215], v[88:91], v[0:3]
	v_mfma_f32_16x16x32_bf16 v[4:7], v[208:211], v[68:71], v[28:31]
	v_mfma_f32_16x16x32_bf16 v[12:15], v[156:159], v[68:71], v[24:27]
	v_mfma_f32_16x16x32_bf16 v[16:19], v[208:211], v[76:79], v[20:23]
	v_mfma_f32_16x16x32_bf16 v[20:23], v[156:159], v[76:79], v[64:67]
	v_mfma_f32_16x16x32_bf16 v[24:27], v[208:211], v[84:87], v[72:75]
	v_mfma_f32_16x16x32_bf16 v[28:31], v[156:159], v[84:87], v[8:11]
	v_mfma_f32_16x16x32_bf16 v[64:67], v[208:211], v[92:95], v[80:83]
	v_mfma_f32_16x16x32_bf16 v[68:71], v[156:159], v[92:95], v[0:3]
	s_setprio 0
	s_barrier
	ds_read_b128 v[8:11], v155
	ds_read_b128 v[0:3], v155 offset:1024
	ds_read_b128 v[76:79], v155 offset:2048
	ds_read_b128 v[72:75], v155 offset:3072
	ds_read_b128 v[130:133], v153 offset:32768
	ds_read_b128 v[156:159], v153 offset:33792
	ds_read_b128 v[160:163], v152 offset:32768
	ds_read_b128 v[164:167], v152 offset:33792
	ds_read_b128 v[168:171], v151 offset:32768
	ds_read_b128 v[172:175], v151 offset:33792
	ds_read_b128 v[208:211], v150 offset:32768
	ds_read_b128 v[212:215], v150 offset:33792
	s_waitcnt vmcnt(2)
	s_barrier
	s_waitcnt lgkmcnt(0)
	s_setprio 1
	s_waitcnt lgkmcnt(0)
	v_mfma_f32_16x16x32_bf16 v[80:83], v[8:11], v[130:133], v[124:127]
	v_mfma_f32_16x16x32_bf16 v[84:87], v[76:79], v[130:133], v[120:123]
	v_mfma_f32_16x16x32_bf16 v[88:91], v[8:11], v[160:163], v[116:119]
	v_mfma_f32_16x16x32_bf16 v[92:95], v[76:79], v[160:163], v[112:115]
	v_mfma_f32_16x16x32_bf16 v[108:111], v[8:11], v[168:171], v[108:111]
	v_mfma_f32_16x16x32_bf16 v[104:107], v[76:79], v[168:171], v[104:107]
	v_mfma_f32_16x16x32_bf16 v[100:103], v[8:11], v[208:211], v[100:103]
	v_mfma_f32_16x16x32_bf16 v[96:99], v[76:79], v[208:211], v[96:99]
	v_mfma_f32_16x16x32_bf16 v[112:115], v[0:3], v[156:159], v[80:83]
	v_mfma_f32_16x16x32_bf16 v[116:119], v[72:75], v[156:159], v[84:87]
	v_mfma_f32_16x16x32_bf16 v[120:123], v[0:3], v[164:167], v[88:91]
	v_mfma_f32_16x16x32_bf16 v[124:127], v[72:75], v[164:167], v[92:95]
	v_mfma_f32_16x16x32_bf16 v[108:111], v[0:3], v[172:175], v[108:111]
	v_mfma_f32_16x16x32_bf16 v[104:107], v[72:75], v[172:175], v[104:107]
	v_mfma_f32_16x16x32_bf16 v[100:103], v[0:3], v[212:215], v[100:103]
	v_mfma_f32_16x16x32_bf16 v[96:99], v[72:75], v[212:215], v[96:99]
	s_setprio 0
	s_barrier
	ds_read_b128 v[88:91], v154
	ds_read_b128 v[80:83], v154 offset:1024
	ds_read_b128 v[92:95], v154 offset:2048
	ds_read_b128 v[84:87], v154 offset:3072
	s_waitcnt vmcnt(0)
	s_barrier
	s_waitcnt lgkmcnt(0)
	s_setprio 1
	s_waitcnt lgkmcnt(0)
	v_mfma_f32_16x16x32_bf16 v[176:179], v[88:91], v[130:133], v[176:179]
	v_mfma_f32_16x16x32_bf16 v[130:133], v[92:95], v[130:133], v[180:183]
	v_mfma_f32_16x16x32_bf16 v[180:183], v[88:91], v[160:163], v[184:187]
	v_mfma_f32_16x16x32_bf16 v[160:163], v[92:95], v[160:163], v[188:191]
	v_mfma_f32_16x16x32_bf16 v[184:187], v[88:91], v[168:171], v[192:195]
	v_mfma_f32_16x16x32_bf16 v[168:171], v[92:95], v[168:171], v[196:199]
	v_mfma_f32_16x16x32_bf16 v[188:191], v[88:91], v[208:211], v[200:203]
	v_mfma_f32_16x16x32_bf16 v[192:195], v[92:95], v[208:211], v[204:207]
	v_mfma_f32_16x16x32_bf16 v[176:179], v[80:83], v[156:159], v[176:179]
	v_mfma_f32_16x16x32_bf16 v[130:133], v[84:87], v[156:159], v[130:133]
	v_mfma_f32_16x16x32_bf16 v[154:157], v[80:83], v[164:167], v[180:183]
	v_mfma_f32_16x16x32_bf16 v[158:161], v[84:87], v[164:167], v[160:163]
	v_mfma_f32_16x16x32_bf16 v[162:165], v[80:83], v[172:175], v[184:187]
	v_mfma_f32_16x16x32_bf16 v[166:169], v[84:87], v[172:175], v[168:171]
	v_mfma_f32_16x16x32_bf16 v[170:173], v[80:83], v[212:215], v[188:191]
	v_mfma_f32_16x16x32_bf16 v[180:183], v[84:87], v[212:215], v[192:195]
	s_setprio 0
	s_barrier
	v_mbcnt_lo_u32_b32 v128, -1, 0
	v_mbcnt_hi_u32_b32 v128, -1, v128
	v_cvt_pk_bf16_f32 v112, v112, v113
	v_cvt_pk_bf16_f32 v113, v114, v115
	v_cvt_pk_bf16_f32 v114, v116, v117
	v_cvt_pk_bf16_f32 v115, v118, v119
	s_lshl_b32 s68, s66, 9
	v_add_u32_e32 v174, s74, v128
	v_ashrrev_i32_e32 v175, 6, v174
	v_and_b32_e32 v184, 15, v128
	v_and_b32_e32 v185, 48, v128
	v_mul_lo_u32 v186, v175, s79
	v_bfe_u32 v187, v128, 3, 3
	v_lshlrev_b32_e32 v128, 4, v128
	v_add_u32_e32 v186, 0x20000, v186
	v_lshrrev_b32_e32 v174, 2, v174
	v_and_b32_e32 v128, 0x70, v128
	v_mul_u32_u24_e32 v184, 0x90, v184
	v_and_b32_e32 v174, 64, v174
	v_add3_u32 v184, v186, v184, v185
	v_or_b32_e32 v185, v186, v128
	v_or3_b32 v174, s24, v174, v187
	v_mad_u32_u24 v185, v187, s80, v185
	ds_write_b128 v184, v[112:115]
	v_cvt_pk_bf16_f32 v112, v176, v177
	v_cvt_pk_bf16_f32 v113, v178, v179
	v_cvt_pk_bf16_f32 v114, v130, v131
	v_cvt_pk_bf16_f32 v115, v132, v133
	ds_write_b128 v184, v[112:115] offset:64
	v_lshlrev_b32_e32 v175, 7, v175
	ds_read_b128 v[112:115], v185
	v_lshlrev_b32_e32 v116, 12, v174
	v_and_or_b32 v116, v175, s81, v116
	v_or3_b32 v128, v116, s68, v128
	ds_read_b128 v[116:119], v185 offset:1152
	v_lshl_add_u64 v[130:131], s[0:1], 0, v[128:129]
	s_mov_b32 s36, 0x8000
	s_waitcnt lgkmcnt(0)
	global_store_dwordx4 v128, v[112:115], s[0:1]
	v_cvt_pk_bf16_f32 v108, v108, v109
	v_cvt_pk_bf16_f32 v109, v110, v111
	v_cvt_pk_bf16_f32 v110, v104, v105
	v_cvt_pk_bf16_f32 v111, v106, v107
	v_cvt_pk_bf16_f32 v104, v162, v163
	s_nop 1
	v_add_co_u32_e32 v112, vcc, s36, v130
	v_cvt_pk_bf16_f32 v114, v124, v125
	v_cvt_pk_bf16_f32 v115, v126, v127
	v_cvt_pk_bf16_f32 v105, v164, v165
	v_cvt_pk_bf16_f32 v106, v166, v167
	s_nop 1
	v_addc_co_u32_e32 v113, vcc, 0, v131, vcc
	global_store_dwordx4 v[112:113], v[116:119], off
	v_cvt_pk_bf16_f32 v112, v120, v121
	v_cvt_pk_bf16_f32 v113, v122, v123
	ds_write_b128 v184, v[112:115]
	v_cvt_pk_bf16_f32 v112, v154, v155
	v_cvt_pk_bf16_f32 v113, v156, v157
	v_cvt_pk_bf16_f32 v114, v158, v159
	v_cvt_pk_bf16_f32 v115, v160, v161
	ds_write_b128 v184, v[112:115] offset:64
	ds_read_b128 v[112:115], v185
	ds_read_b128 v[116:119], v185 offset:1152
	v_add_co_u32_e32 v120, vcc, s76, v130
	ds_write_b128 v184, v[108:111]
	v_cvt_pk_bf16_f32 v107, v168, v169
	ds_write_b128 v184, v[104:107] offset:64
	v_addc_co_u32_e32 v121, vcc, 0, v131, vcc
	ds_read_b128 v[104:107], v185
	ds_read_b128 v[108:111], v185 offset:1152
	s_waitcnt lgkmcnt(0)
	global_store_dwordx4 v[120:121], v[112:115], off
	v_cvt_pk_bf16_f32 v100, v100, v101
	v_cvt_pk_bf16_f32 v101, v102, v103
	v_cvt_pk_bf16_f32 v102, v96, v97
	v_cvt_pk_bf16_f32 v103, v98, v99
	ds_write_b128 v184, v[100:103]
	s_nop 0
	v_add_co_u32_e32 v112, vcc, s77, v130
	v_cvt_pk_bf16_f32 v96, v170, v171
	v_cvt_pk_bf16_f32 v97, v172, v173
	v_cvt_pk_bf16_f32 v98, v180, v181
	v_cvt_pk_bf16_f32 v99, v182, v183
	s_nop 1
	v_addc_co_u32_e32 v113, vcc, 0, v131, vcc
	global_store_dwordx4 v[112:113], v[116:119], off
	v_add_co_u32_e32 v112, vcc, s78, v130
	ds_write_b128 v184, v[96:99] offset:64
	s_nop 0
	v_addc_co_u32_e32 v113, vcc, 0, v131, vcc
	ds_read_b128 v[96:99], v185
	ds_read_b128 v[100:103], v185 offset:1152
	global_store_dwordx4 v[112:113], v[104:107], off
	s_nop 1
	v_add_co_u32_e32 v104, vcc, s82, v130
	s_nop 1
	v_addc_co_u32_e32 v105, vcc, 0, v131, vcc
	global_store_dwordx4 v[104:105], v[108:111], off
	v_add_co_u32_e32 v104, vcc, s83, v130
	s_nop 1
	v_addc_co_u32_e32 v105, vcc, 0, v131, vcc
	s_waitcnt lgkmcnt(0)
	global_store_dwordx4 v[104:105], v[96:99], off
	s_nop 1
	v_add_co_u32_e32 v96, vcc, s91, v130
	s_nop 1
	v_addc_co_u32_e32 v97, vcc, 0, v131, vcc
	global_store_dwordx4 v[96:97], v[100:103], off
	ds_read_b128 v[96:99], v153 offset:49152
	ds_read_b128 v[100:103], v153 offset:50176
	ds_read_b128 v[104:107], v152 offset:49152
	ds_read_b128 v[108:111], v152 offset:50176
	ds_read_b128 v[112:115], v151 offset:49152
	ds_read_b128 v[116:119], v151 offset:50176
	ds_read_b128 v[120:123], v150 offset:49152
	ds_read_b128 v[124:127], v150 offset:50176
	s_barrier
	s_waitcnt lgkmcnt(0)
	s_setprio 1
	s_waitcnt lgkmcnt(0)
	v_mfma_f32_16x16x32_bf16 v[32:35], v[8:11], v[96:99], v[32:35]
	v_mfma_f32_16x16x32_bf16 v[36:39], v[76:79], v[96:99], v[36:39]
	v_mfma_f32_16x16x32_bf16 v[40:43], v[8:11], v[104:107], v[40:43]
	v_mfma_f32_16x16x32_bf16 v[130:133], v[76:79], v[104:107], v[44:47]
	v_mfma_f32_16x16x32_bf16 v[150:153], v[8:11], v[112:115], v[48:51]
	v_mfma_f32_16x16x32_bf16 v[52:55], v[76:79], v[112:115], v[52:55]
	v_mfma_f32_16x16x32_bf16 v[8:11], v[8:11], v[120:123], v[56:59]
	v_mfma_f32_16x16x32_bf16 v[60:63], v[76:79], v[120:123], v[60:63]
	v_mfma_f32_16x16x32_bf16 v[56:59], v[0:3], v[100:103], v[32:35]
	v_mfma_f32_16x16x32_bf16 v[48:51], v[72:75], v[100:103], v[36:39]
	v_mfma_f32_16x16x32_bf16 v[44:47], v[0:3], v[108:111], v[40:43]
	v_mfma_f32_16x16x32_bf16 v[40:43], v[72:75], v[108:111], v[130:133]
	v_mfma_f32_16x16x32_bf16 v[36:39], v[0:3], v[116:119], v[150:153]
	v_mfma_f32_16x16x32_bf16 v[32:35], v[72:75], v[116:119], v[52:55]
	v_mfma_f32_16x16x32_bf16 v[8:11], v[0:3], v[124:127], v[8:11]
	v_mfma_f32_16x16x32_bf16 v[0:3], v[72:75], v[124:127], v[60:63]
	s_setprio 0
	s_setprio 1
	v_mfma_f32_16x16x32_bf16 v[4:7], v[88:91], v[96:99], v[4:7]
	v_mfma_f32_16x16x32_bf16 v[12:15], v[92:95], v[96:99], v[12:15]
	v_mfma_f32_16x16x32_bf16 v[16:19], v[88:91], v[104:107], v[16:19]
	v_mfma_f32_16x16x32_bf16 v[20:23], v[92:95], v[104:107], v[20:23]
	v_mfma_f32_16x16x32_bf16 v[72:75], v[88:91], v[112:115], v[24:27]
	v_mfma_f32_16x16x32_bf16 v[76:79], v[92:95], v[112:115], v[28:31]
	v_mfma_f32_16x16x32_bf16 v[64:67], v[88:91], v[120:123], v[64:67]
	v_mfma_f32_16x16x32_bf16 v[68:71], v[92:95], v[120:123], v[68:71]
	v_mfma_f32_16x16x32_bf16 v[60:63], v[80:83], v[100:103], v[4:7]
	v_mfma_f32_16x16x32_bf16 v[52:55], v[84:87], v[100:103], v[12:15]
	v_mfma_f32_16x16x32_bf16 v[28:31], v[80:83], v[108:111], v[16:19]
	v_mfma_f32_16x16x32_bf16 v[24:27], v[84:87], v[108:111], v[20:23]
	v_mfma_f32_16x16x32_bf16 v[20:23], v[80:83], v[116:119], v[72:75]
	v_mfma_f32_16x16x32_bf16 v[16:19], v[84:87], v[116:119], v[76:79]
	v_mfma_f32_16x16x32_bf16 v[12:15], v[80:83], v[124:127], v[64:67]
	v_mfma_f32_16x16x32_bf16 v[4:7], v[84:87], v[124:127], v[68:71]
	s_setprio 0
	v_cmp_gt_u32_e32 vcc, s92, v136
	s_barrier
	s_and_saveexec_b64 s[66:67], vcc
	s_cbranch_execz .LBB0_468
	s_barrier

.LBB0_521:
	ds_read_b128 v[140:143], v138
	ds_read_b128 v[144:147], v138 offset:1024
	ds_read_b128 v[148:151], v138 offset:2048
	ds_read_b128 v[152:155], v138 offset:3072
	ds_read_b128 v[156:159], v193
	ds_read_b128 v[160:163], v193 offset:1024
	ds_read_b128 v[194:197], v192
	ds_read_b128 v[198:201], v192 offset:1024
	ds_read_b128 v[202:205], v191
	ds_read_b128 v[206:209], v191 offset:1024
	ds_read_b128 v[210:213], v190
	ds_read_b128 v[214:217], v190 offset:1024
	s_waitcnt lgkmcnt(8)
	s_waitcnt vmcnt(10)
	s_barrier
	s_waitcnt lgkmcnt(0)
	s_waitcnt lgkmcnt(0)
	v_mfma_f32_16x16x32_bf16 v[124:127], v[140:143], v[156:159], v[124:127]
	v_mfma_f32_16x16x32_bf16 v[120:123], v[148:151], v[156:159], v[120:123]
	v_mfma_f32_16x16x32_bf16 v[116:119], v[140:143], v[194:197], v[116:119]
	v_mfma_f32_16x16x32_bf16 v[112:115], v[148:151], v[194:197], v[112:115]
	v_mfma_f32_16x16x32_bf16 v[108:111], v[140:143], v[202:205], v[108:111]
	v_mfma_f32_16x16x32_bf16 v[104:107], v[148:151], v[202:205], v[104:107]
	v_mfma_f32_16x16x32_bf16 v[100:103], v[140:143], v[210:213], v[100:103]
	v_mfma_f32_16x16x32_bf16 v[96:99], v[148:151], v[210:213], v[96:99]
	v_mfma_f32_16x16x32_bf16 v[124:127], v[144:147], v[160:163], v[124:127]
	v_mfma_f32_16x16x32_bf16 v[120:123], v[152:155], v[160:163], v[120:123]
	v_mfma_f32_16x16x32_bf16 v[116:119], v[144:147], v[198:201], v[116:119]
	v_mfma_f32_16x16x32_bf16 v[112:115], v[152:155], v[198:201], v[112:115]
	v_mfma_f32_16x16x32_bf16 v[108:111], v[144:147], v[206:209], v[108:111]
	v_mfma_f32_16x16x32_bf16 v[104:107], v[152:155], v[206:209], v[104:107]
	v_mfma_f32_16x16x32_bf16 v[100:103], v[144:147], v[214:217], v[100:103]
	v_mfma_f32_16x16x32_bf16 v[96:99], v[152:155], v[214:217], v[96:99]
	s_barrier
	v_readfirstlane_b32 s36, v189
	v_lshl_add_u64 v[234:235], s[58:59], 0, v[164:165]
	s_mov_b32 m0, s36
	v_readfirstlane_b32 s36, v188
	ds_read_b128 v[218:221], v135
	ds_read_b128 v[222:225], v135 offset:1024
	ds_read_b128 v[226:229], v135 offset:2048
	ds_read_b128 v[230:233], v135 offset:3072
	global_load_lds_dwordx4 v[234:235], off
	v_lshl_add_u64 v[236:237], v[234:235], 0, s[2:3]
	s_mov_b32 m0, s36
	s_nop 0
	global_load_lds_dwordx4 v[236:237], off
	v_readfirstlane_b32 s36, v169
	v_lshl_add_u64 v[236:237], v[128:129], 0, s[22:23]
	s_mov_b32 m0, s36
	v_readfirstlane_b32 s36, v187
	global_load_lds_dwordx4 v[236:237], off
	v_lshl_add_u64 v[236:237], v[128:129], 0, s[24:25]
	s_mov_b32 m0, s36
	s_nop 0
	global_load_lds_dwordx4 v[236:237], off
	s_waitcnt vmcnt(12)
	s_barrier
	s_waitcnt lgkmcnt(0)
	s_waitcnt lgkmcnt(0)
	v_mfma_f32_16x16x32_bf16 v[92:95], v[218:221], v[156:159], v[92:95]
	v_mfma_f32_16x16x32_bf16 v[88:91], v[226:229], v[156:159], v[88:91]
	v_mfma_f32_16x16x32_bf16 v[84:87], v[218:221], v[194:197], v[84:87]
	v_mfma_f32_16x16x32_bf16 v[80:83], v[226:229], v[194:197], v[80:83]
	v_mfma_f32_16x16x32_bf16 v[76:79], v[218:221], v[202:205], v[76:79]
	v_mfma_f32_16x16x32_bf16 v[72:75], v[226:229], v[202:205], v[72:75]
	v_mfma_f32_16x16x32_bf16 v[68:71], v[218:221], v[210:213], v[68:71]
	v_mfma_f32_16x16x32_bf16 v[64:67], v[226:229], v[210:213], v[64:67]
	v_mfma_f32_16x16x32_bf16 v[92:95], v[222:225], v[160:163], v[92:95]
	v_mfma_f32_16x16x32_bf16 v[88:91], v[230:233], v[160:163], v[88:91]
	v_mfma_f32_16x16x32_bf16 v[84:87], v[222:225], v[198:201], v[84:87]
	v_mfma_f32_16x16x32_bf16 v[80:83], v[230:233], v[198:201], v[80:83]
	v_mfma_f32_16x16x32_bf16 v[76:79], v[222:225], v[206:209], v[76:79]
	v_mfma_f32_16x16x32_bf16 v[72:75], v[230:233], v[206:209], v[72:75]
	v_mfma_f32_16x16x32_bf16 v[68:71], v[222:225], v[214:217], v[68:71]
	v_mfma_f32_16x16x32_bf16 v[64:67], v[230:233], v[214:217], v[64:67]
	s_barrier
	ds_read_b128 v[156:159], v193 offset:16384
	ds_read_b128 v[160:163], v193 offset:17408
	ds_read_b128 v[194:197], v192 offset:16384
	ds_read_b128 v[198:201], v192 offset:17408
	ds_read_b128 v[202:205], v191 offset:16384
	ds_read_b128 v[206:209], v191 offset:17408
	ds_read_b128 v[210:213], v190 offset:16384
	ds_read_b128 v[214:217], v190 offset:17408
	v_readfirstlane_b32 s36, v186
	v_lshl_add_u64 v[236:237], v[234:235], 0, s[6:7]
	s_mov_b32 m0, s36
	v_readfirstlane_b32 s36, v185
	global_load_lds_dwordx4 v[236:237], off
	v_lshl_add_u64 v[236:237], v[234:235], 0, s[8:9]
	s_mov_b32 m0, s36
	s_nop 0
	global_load_lds_dwordx4 v[236:237], off
	s_barrier
	s_waitcnt lgkmcnt(0)
	s_waitcnt lgkmcnt(0)
	v_mfma_f32_16x16x32_bf16 v[60:63], v[140:143], v[156:159], v[60:63]
	v_mfma_f32_16x16x32_bf16 v[56:59], v[148:151], v[156:159], v[56:59]
	v_mfma_f32_16x16x32_bf16 v[52:55], v[140:143], v[194:197], v[52:55]
	v_mfma_f32_16x16x32_bf16 v[48:51], v[148:151], v[194:197], v[48:51]
	v_mfma_f32_16x16x32_bf16 v[44:47], v[140:143], v[202:205], v[44:47]
	v_mfma_f32_16x16x32_bf16 v[40:43], v[148:151], v[202:205], v[40:43]
	v_mfma_f32_16x16x32_bf16 v[36:39], v[140:143], v[210:213], v[36:39]
	v_mfma_f32_16x16x32_bf16 v[32:35], v[148:151], v[210:213], v[32:35]
	v_mfma_f32_16x16x32_bf16 v[60:63], v[144:147], v[160:163], v[60:63]
	v_mfma_f32_16x16x32_bf16 v[56:59], v[152:155], v[160:163], v[56:59]
	v_mfma_f32_16x16x32_bf16 v[52:55], v[144:147], v[198:201], v[52:55]
	v_mfma_f32_16x16x32_bf16 v[48:51], v[152:155], v[198:201], v[48:51]
	v_mfma_f32_16x16x32_bf16 v[44:47], v[144:147], v[206:209], v[44:47]
	v_mfma_f32_16x16x32_bf16 v[40:43], v[152:155], v[206:209], v[40:43]
	v_mfma_f32_16x16x32_bf16 v[36:39], v[144:147], v[214:217], v[36:39]
	v_mfma_f32_16x16x32_bf16 v[32:35], v[152:155], v[214:217], v[32:35]
	s_barrier
	v_readfirstlane_b32 s36, v184
	v_lshl_add_u64 v[142:143], v[128:129], 0, s[26:27]
	s_mov_b32 m0, s36
	v_readfirstlane_b32 s36, v183
	global_load_lds_dwordx4 v[142:143], off
	s_mov_b32 m0, s36
	s_nop 0
	global_load_lds_dwordx4 v[128:129], off
	s_waitcnt vmcnt(12)
	s_barrier
	v_mfma_f32_16x16x32_bf16 v[28:31], v[218:221], v[156:159], v[28:31]
	v_mfma_f32_16x16x32_bf16 v[24:27], v[226:229], v[156:159], v[24:27]
	v_mfma_f32_16x16x32_bf16 v[20:23], v[218:221], v[194:197], v[20:23]
	v_mfma_f32_16x16x32_bf16 v[16:19], v[226:229], v[194:197], v[16:19]
	v_mfma_f32_16x16x32_bf16 v[12:15], v[218:221], v[202:205], v[12:15]
	v_mfma_f32_16x16x32_bf16 v[8:11], v[226:229], v[202:205], v[8:11]
	v_mfma_f32_16x16x32_bf16 v[4:7], v[218:221], v[210:213], v[4:7]
	v_mfma_f32_16x16x32_bf16 v[0:3], v[226:229], v[210:213], v[0:3]
	v_mfma_f32_16x16x32_bf16 v[28:31], v[222:225], v[160:163], v[28:31]
	v_mfma_f32_16x16x32_bf16 v[24:27], v[230:233], v[160:163], v[24:27]
	v_mfma_f32_16x16x32_bf16 v[20:23], v[222:225], v[198:201], v[20:23]
	v_mfma_f32_16x16x32_bf16 v[16:19], v[230:233], v[198:201], v[16:19]
	v_mfma_f32_16x16x32_bf16 v[12:15], v[222:225], v[206:209], v[12:15]
	v_mfma_f32_16x16x32_bf16 v[8:11], v[230:233], v[206:209], v[8:11]
	v_mfma_f32_16x16x32_bf16 v[4:7], v[222:225], v[214:217], v[4:7]
	v_mfma_f32_16x16x32_bf16 v[0:3], v[230:233], v[214:217], v[0:3]
	s_barrier
	ds_read_b128 v[140:143], v130
	ds_read_b128 v[144:147], v130 offset:1024
	ds_read_b128 v[148:151], v130 offset:2048
	ds_read_b128 v[152:155], v130 offset:3072
	ds_read_b128 v[156:159], v193 offset:32768
	ds_read_b128 v[160:163], v193 offset:33792
	ds_read_b128 v[194:197], v192 offset:32768
	ds_read_b128 v[198:201], v192 offset:33792
	ds_read_b128 v[202:205], v191 offset:32768
	ds_read_b128 v[206:209], v191 offset:33792
	ds_read_b128 v[210:213], v190 offset:32768
	ds_read_b128 v[214:217], v190 offset:33792
	s_waitcnt lgkmcnt(8)
	s_waitcnt vmcnt(10)
	s_barrier
	s_waitcnt lgkmcnt(0)
	s_waitcnt lgkmcnt(0)
	v_mfma_f32_16x16x32_bf16 v[124:127], v[140:143], v[156:159], v[124:127]
	v_mfma_f32_16x16x32_bf16 v[120:123], v[148:151], v[156:159], v[120:123]
	v_mfma_f32_16x16x32_bf16 v[116:119], v[140:143], v[194:197], v[116:119]
	v_mfma_f32_16x16x32_bf16 v[112:115], v[148:151], v[194:197], v[112:115]
	v_mfma_f32_16x16x32_bf16 v[108:111], v[140:143], v[202:205], v[108:111]
	v_mfma_f32_16x16x32_bf16 v[104:107], v[148:151], v[202:205], v[104:107]
	v_mfma_f32_16x16x32_bf16 v[100:103], v[140:143], v[210:213], v[100:103]
	v_mfma_f32_16x16x32_bf16 v[96:99], v[148:151], v[210:213], v[96:99]
	v_mfma_f32_16x16x32_bf16 v[124:127], v[144:147], v[160:163], v[124:127]
	v_mfma_f32_16x16x32_bf16 v[120:123], v[152:155], v[160:163], v[120:123]
	v_mfma_f32_16x16x32_bf16 v[116:119], v[144:147], v[198:201], v[116:119]
	v_mfma_f32_16x16x32_bf16 v[112:115], v[152:155], v[198:201], v[112:115]
	v_mfma_f32_16x16x32_bf16 v[108:111], v[144:147], v[206:209], v[108:111]
	v_mfma_f32_16x16x32_bf16 v[104:107], v[152:155], v[206:209], v[104:107]
	v_mfma_f32_16x16x32_bf16 v[100:103], v[144:147], v[214:217], v[100:103]
	v_mfma_f32_16x16x32_bf16 v[96:99], v[152:155], v[214:217], v[96:99]
	s_barrier
	v_readfirstlane_b32 s36, v182
	v_lshl_add_u64 v[234:235], s[46:47], 0, v[164:165]
	s_mov_b32 m0, s36
	v_readfirstlane_b32 s36, v181
	ds_read_b128 v[218:221], v132
	ds_read_b128 v[222:225], v132 offset:1024
	ds_read_b128 v[226:229], v132 offset:2048
	ds_read_b128 v[230:233], v132 offset:3072
	global_load_lds_dwordx4 v[234:235], off
	v_lshl_add_u64 v[236:237], v[234:235], 0, s[2:3]
	s_mov_b32 m0, s36
	s_nop 0
	global_load_lds_dwordx4 v[236:237], off
	v_readfirstlane_b32 s36, v177
	v_lshl_add_u64 v[236:237], v[128:129], 0, s[28:29]
	s_mov_b32 m0, s36
	v_readfirstlane_b32 s36, v175
	global_load_lds_dwordx4 v[236:237], off
	v_lshl_add_u64 v[236:237], v[128:129], 0, s[30:31]
	s_mov_b32 m0, s36
	s_nop 0
	global_load_lds_dwordx4 v[236:237], off
	s_waitcnt vmcnt(12)
	s_barrier
	s_waitcnt lgkmcnt(0)
	s_waitcnt lgkmcnt(0)
	v_mfma_f32_16x16x32_bf16 v[92:95], v[218:221], v[156:159], v[92:95]
	v_mfma_f32_16x16x32_bf16 v[88:91], v[226:229], v[156:159], v[88:91]
	v_mfma_f32_16x16x32_bf16 v[84:87], v[218:221], v[194:197], v[84:87]
	v_mfma_f32_16x16x32_bf16 v[80:83], v[226:229], v[194:197], v[80:83]
	v_mfma_f32_16x16x32_bf16 v[76:79], v[218:221], v[202:205], v[76:79]
	v_mfma_f32_16x16x32_bf16 v[72:75], v[226:229], v[202:205], v[72:75]
	v_mfma_f32_16x16x32_bf16 v[68:71], v[218:221], v[210:213], v[68:71]
	v_mfma_f32_16x16x32_bf16 v[64:67], v[226:229], v[210:213], v[64:67]
	v_mfma_f32_16x16x32_bf16 v[92:95], v[222:225], v[160:163], v[92:95]
	v_mfma_f32_16x16x32_bf16 v[88:91], v[230:233], v[160:163], v[88:91]
	v_mfma_f32_16x16x32_bf16 v[84:87], v[222:225], v[198:201], v[84:87]
	v_mfma_f32_16x16x32_bf16 v[80:83], v[230:233], v[198:201], v[80:83]
	v_mfma_f32_16x16x32_bf16 v[76:79], v[222:225], v[206:209], v[76:79]
	v_mfma_f32_16x16x32_bf16 v[72:75], v[230:233], v[206:209], v[72:75]
	v_mfma_f32_16x16x32_bf16 v[68:71], v[222:225], v[214:217], v[68:71]
	v_mfma_f32_16x16x32_bf16 v[64:67], v[230:233], v[214:217], v[64:67]
	s_barrier
	ds_read_b128 v[156:159], v193 offset:49152
	ds_read_b128 v[160:163], v193 offset:50176
	ds_read_b128 v[194:197], v192 offset:49152
	ds_read_b128 v[198:201], v192 offset:50176
	ds_read_b128 v[202:205], v191 offset:49152
	ds_read_b128 v[206:209], v191 offset:50176
	ds_read_b128 v[210:213], v190 offset:49152
	ds_read_b128 v[214:217], v190 offset:50176
	v_readfirstlane_b32 s36, v173
	v_lshl_add_u64 v[236:237], v[234:235], 0, s[6:7]
	s_mov_b32 m0, s36
	v_readfirstlane_b32 s36, v171
	global_load_lds_dwordx4 v[236:237], off
	v_lshl_add_u64 v[236:237], v[234:235], 0, s[8:9]
	s_mov_b32 m0, s36
	s_nop 0
	global_load_lds_dwordx4 v[236:237], off
	s_barrier
	s_waitcnt lgkmcnt(0)
	s_waitcnt lgkmcnt(0)
	v_mfma_f32_16x16x32_bf16 v[60:63], v[140:143], v[156:159], v[60:63]
	v_mfma_f32_16x16x32_bf16 v[56:59], v[148:151], v[156:159], v[56:59]
	v_mfma_f32_16x16x32_bf16 v[52:55], v[140:143], v[194:197], v[52:55]
	v_mfma_f32_16x16x32_bf16 v[48:51], v[148:151], v[194:197], v[48:51]
	v_mfma_f32_16x16x32_bf16 v[44:47], v[140:143], v[202:205], v[44:47]
	v_mfma_f32_16x16x32_bf16 v[40:43], v[148:151], v[202:205], v[40:43]
	v_mfma_f32_16x16x32_bf16 v[36:39], v[140:143], v[210:213], v[36:39]
	v_mfma_f32_16x16x32_bf16 v[32:35], v[148:151], v[210:213], v[32:35]
	v_mfma_f32_16x16x32_bf16 v[60:63], v[144:147], v[160:163], v[60:63]
	v_mfma_f32_16x16x32_bf16 v[56:59], v[152:155], v[160:163], v[56:59]
	v_mfma_f32_16x16x32_bf16 v[52:55], v[144:147], v[198:201], v[52:55]
	v_mfma_f32_16x16x32_bf16 v[48:51], v[152:155], v[198:201], v[48:51]
	v_mfma_f32_16x16x32_bf16 v[44:47], v[144:147], v[206:209], v[44:47]
	v_mfma_f32_16x16x32_bf16 v[40:43], v[152:155], v[206:209], v[40:43]
	v_mfma_f32_16x16x32_bf16 v[36:39], v[144:147], v[214:217], v[36:39]
	v_mfma_f32_16x16x32_bf16 v[32:35], v[152:155], v[214:217], v[32:35]
	s_barrier
	v_lshl_add_u64 v[128:129], v[128:129], 0, s[34:35]
	v_readfirstlane_b32 s36, v137
	v_lshl_add_u64 v[142:143], v[128:129], 0, s[18:19]
	s_mov_b32 m0, s36
	v_readfirstlane_b32 s36, v136
	global_load_lds_dwordx4 v[142:143], off
	v_lshl_add_u64 v[142:143], v[128:129], 0, s[20:21]
	s_mov_b32 m0, s36
	s_nop 0
	global_load_lds_dwordx4 v[142:143], off
	s_waitcnt vmcnt(12)
	s_barrier
	v_mfma_f32_16x16x32_bf16 v[28:31], v[218:221], v[156:159], v[28:31]
	v_mfma_f32_16x16x32_bf16 v[24:27], v[226:229], v[156:159], v[24:27]
	v_mfma_f32_16x16x32_bf16 v[20:23], v[218:221], v[194:197], v[20:23]
	v_mfma_f32_16x16x32_bf16 v[16:19], v[226:229], v[194:197], v[16:19]
	v_mfma_f32_16x16x32_bf16 v[12:15], v[218:221], v[202:205], v[12:15]
	v_mfma_f32_16x16x32_bf16 v[8:11], v[226:229], v[202:205], v[8:11]
	v_mfma_f32_16x16x32_bf16 v[4:7], v[218:221], v[210:213], v[4:7]
	v_mfma_f32_16x16x32_bf16 v[0:3], v[226:229], v[210:213], v[0:3]
	v_mfma_f32_16x16x32_bf16 v[28:31], v[222:225], v[160:163], v[28:31]
	v_mfma_f32_16x16x32_bf16 v[24:27], v[230:233], v[160:163], v[24:27]
	v_mfma_f32_16x16x32_bf16 v[20:23], v[222:225], v[198:201], v[20:23]
	v_mfma_f32_16x16x32_bf16 v[16:19], v[230:233], v[198:201], v[16:19]
	v_mfma_f32_16x16x32_bf16 v[12:15], v[222:225], v[206:209], v[12:15]
	v_mfma_f32_16x16x32_bf16 v[8:11], v[230:233], v[206:209], v[8:11]
	v_mfma_f32_16x16x32_bf16 v[4:7], v[222:225], v[214:217], v[4:7]
	v_mfma_f32_16x16x32_bf16 v[0:3], v[230:233], v[214:217], v[0:3]
	s_add_i32 s14, s14, 2
	s_add_u32 s46, s46, s56
	s_addc_u32 s47, s47, s57
	s_add_u32 s58, s58, s56
	s_addc_u32 s59, s59, s57
	s_cmp_lt_u32 s14, 28
	s_barrier
	s_cbranch_scc1 .LBB0_521
	s_lshl_b32 s14, s60, 3
	s_or_b32 s80, s61, s14
	s_lshl_b32 s46, s80, 8
	v_lshlrev_b32_e32 v128, 3, v131
	v_lshlrev_b32_e32 v129, 5, v131
	s_or_b32 s14, s46, 0x80
	v_and_b32_e32 v128, 0x7fff0, v128
	v_and_b32_e32 v129, 32, v129
	s_lshl_b64 s[56:57], s[14:15], 13
	v_add_u32_e32 v129, v129, v134
	v_add_lshl_u32 v128, v133, v128, 13
	s_add_u32 s56, s40, s56
	v_lshl_add_u32 v164, v129, 1, v128
	s_addc_u32 s57, s41, s57
	v_lshl_add_u64 v[128:129], s[56:57], 0, v[164:165]
	v_readfirstlane_b32 s14, v137
	ds_read_b128 v[140:143], v138
	ds_read_b128 v[144:147], v138 offset:1024
	ds_read_b128 v[148:151], v138 offset:2048
	ds_read_b128 v[152:155], v138 offset:3072
	ds_read_b128 v[156:159], v193
	ds_read_b128 v[160:163], v193 offset:1024
	ds_read_b128 v[194:197], v192
	ds_read_b128 v[198:201], v192 offset:1024
	ds_read_b128 v[202:205], v191
	ds_read_b128 v[206:209], v191 offset:1024
	ds_read_b128 v[210:213], v190
	ds_read_b128 v[214:217], v190 offset:1024
	v_lshl_add_u64 v[138:139], v[128:129], 0, s[38:39]
	s_mov_b32 m0, s14
	v_readfirstlane_b32 s14, v136
	global_load_lds_dwordx4 v[138:139], off
	v_lshl_add_u64 v[128:129], v[128:129], 0, s[44:45]
	s_mov_b32 m0, s14
	s_mov_b32 s47, s15
	global_load_lds_dwordx4 v[128:129], off
	s_waitcnt vmcnt(10)
	s_barrier
	s_waitcnt lgkmcnt(0)
	s_setprio 1
	s_waitcnt lgkmcnt(0)
	v_mfma_f32_16x16x32_bf16 v[124:127], v[140:143], v[156:159], v[124:127]
	v_mfma_f32_16x16x32_bf16 v[120:123], v[148:151], v[156:159], v[120:123]
	v_mfma_f32_16x16x32_bf16 v[116:119], v[140:143], v[194:197], v[116:119]
	v_mfma_f32_16x16x32_bf16 v[112:115], v[148:151], v[194:197], v[112:115]
	v_mfma_f32_16x16x32_bf16 v[108:111], v[140:143], v[202:205], v[108:111]
	v_mfma_f32_16x16x32_bf16 v[104:107], v[148:151], v[202:205], v[104:107]
	v_mfma_f32_16x16x32_bf16 v[100:103], v[140:143], v[210:213], v[100:103]
	v_mfma_f32_16x16x32_bf16 v[96:99], v[148:151], v[210:213], v[96:99]
	v_mfma_f32_16x16x32_bf16 v[124:127], v[144:147], v[160:163], v[124:127]
	v_mfma_f32_16x16x32_bf16 v[120:123], v[152:155], v[160:163], v[120:123]
	v_mfma_f32_16x16x32_bf16 v[116:119], v[144:147], v[198:201], v[116:119]
	v_mfma_f32_16x16x32_bf16 v[112:115], v[152:155], v[198:201], v[112:115]
	v_mfma_f32_16x16x32_bf16 v[108:111], v[144:147], v[206:209], v[108:111]
	v_mfma_f32_16x16x32_bf16 v[104:107], v[152:155], v[206:209], v[104:107]
	v_mfma_f32_16x16x32_bf16 v[100:103], v[144:147], v[214:217], v[100:103]
	v_mfma_f32_16x16x32_bf16 v[96:99], v[152:155], v[214:217], v[96:99]
	s_setprio 0
	s_barrier
	ds_read_b128 v[136:139], v135
	ds_read_b128 v[218:221], v135 offset:1024
	ds_read_b128 v[222:225], v135 offset:2048
	ds_read_b128 v[226:229], v135 offset:3072
	s_barrier
	s_waitcnt lgkmcnt(0)
	s_setprio 1
	s_waitcnt lgkmcnt(0)
	v_mfma_f32_16x16x32_bf16 v[92:95], v[136:139], v[156:159], v[92:95]
	v_mfma_f32_16x16x32_bf16 v[84:87], v[136:139], v[194:197], v[84:87]
	v_mfma_f32_16x16x32_bf16 v[80:83], v[222:225], v[194:197], v[80:83]
	v_mfma_f32_16x16x32_bf16 v[88:91], v[222:225], v[156:159], v[88:91]
	v_mfma_f32_16x16x32_bf16 v[76:79], v[136:139], v[202:205], v[76:79]
	v_mfma_f32_16x16x32_bf16 v[72:75], v[222:225], v[202:205], v[72:75]
	v_mfma_f32_16x16x32_bf16 v[68:71], v[136:139], v[210:213], v[68:71]
	v_mfma_f32_16x16x32_bf16 v[64:67], v[222:225], v[210:213], v[64:67]
	v_mfma_f32_16x16x32_bf16 v[156:159], v[218:221], v[160:163], v[92:95]
	v_mfma_f32_16x16x32_bf16 v[194:197], v[218:221], v[198:201], v[84:87]
	v_mfma_f32_16x16x32_bf16 v[198:201], v[226:229], v[198:201], v[80:83]
	v_mfma_f32_16x16x32_bf16 v[160:163], v[226:229], v[160:163], v[88:91]
	v_mfma_f32_16x16x32_bf16 v[202:205], v[218:221], v[206:209], v[76:79]
	v_mfma_f32_16x16x32_bf16 v[206:209], v[226:229], v[206:209], v[72:75]
	v_mfma_f32_16x16x32_bf16 v[210:213], v[218:221], v[214:217], v[68:71]
	v_mfma_f32_16x16x32_bf16 v[214:217], v[226:229], v[214:217], v[64:67]
	s_setprio 0
	s_barrier
	s_nop 0
	ds_read_b128 v[64:67], v193 offset:16384
	ds_read_b128 v[68:71], v193 offset:17408
	ds_read_b128 v[72:75], v192 offset:16384
	ds_read_b128 v[76:79], v192 offset:17408
	ds_read_b128 v[80:83], v191 offset:16384
	ds_read_b128 v[84:87], v191 offset:17408
	ds_read_b128 v[88:91], v190 offset:16384
	ds_read_b128 v[92:95], v190 offset:17408
	s_waitcnt vmcnt(4)
	s_barrier
	s_waitcnt lgkmcnt(0)
	s_setprio 1
	s_waitcnt lgkmcnt(0)
	v_mfma_f32_16x16x32_bf16 v[60:63], v[140:143], v[64:67], v[60:63]
	v_mfma_f32_16x16x32_bf16 v[56:59], v[148:151], v[64:67], v[56:59]
	v_mfma_f32_16x16x32_bf16 v[52:55], v[140:143], v[72:75], v[52:55]
	v_mfma_f32_16x16x32_bf16 v[48:51], v[148:151], v[72:75], v[48:51]
	v_mfma_f32_16x16x32_bf16 v[230:233], v[140:143], v[80:83], v[44:47]
	v_mfma_f32_16x16x32_bf16 v[234:237], v[148:151], v[80:83], v[40:43]
	v_mfma_f32_16x16x32_bf16 v[140:143], v[140:143], v[88:91], v[36:39]
	v_mfma_f32_16x16x32_bf16 v[148:151], v[148:151], v[88:91], v[32:35]
	v_mfma_f32_16x16x32_bf16 v[32:35], v[144:147], v[68:71], v[60:63]
	v_mfma_f32_16x16x32_bf16 v[36:39], v[152:155], v[68:71], v[56:59]
	v_mfma_f32_16x16x32_bf16 v[40:43], v[144:147], v[76:79], v[52:55]
	v_mfma_f32_16x16x32_bf16 v[44:47], v[152:155], v[76:79], v[48:51]
	v_mfma_f32_16x16x32_bf16 v[48:51], v[144:147], v[84:87], v[230:233]
	v_mfma_f32_16x16x32_bf16 v[52:55], v[152:155], v[84:87], v[234:237]
	v_mfma_f32_16x16x32_bf16 v[56:59], v[144:147], v[92:95], v[140:143]
	v_mfma_f32_16x16x32_bf16 v[60:63], v[152:155], v[92:95], v[148:151]
	s_setprio 0
	s_setprio 1
	v_mfma_f32_16x16x32_bf16 v[28:31], v[136:139], v[64:67], v[28:31]
	v_mfma_f32_16x16x32_bf16 v[24:27], v[222:225], v[64:67], v[24:27]
	v_mfma_f32_16x16x32_bf16 v[20:23], v[136:139], v[72:75], v[20:23]
	v_mfma_f32_16x16x32_bf16 v[64:67], v[222:225], v[72:75], v[16:19]
	v_mfma_f32_16x16x32_bf16 v[12:15], v[136:139], v[80:83], v[12:15]
	v_mfma_f32_16x16x32_bf16 v[8:11], v[222:225], v[80:83], v[8:11]
	v_mfma_f32_16x16x32_bf16 v[72:75], v[136:139], v[88:91], v[4:7]
	v_mfma_f32_16x16x32_bf16 v[80:83], v[222:225], v[88:91], v[0:3]
	v_mfma_f32_16x16x32_bf16 v[0:3], v[218:221], v[68:71], v[28:31]
	v_mfma_f32_16x16x32_bf16 v[4:7], v[226:229], v[68:71], v[24:27]
	v_mfma_f32_16x16x32_bf16 v[16:19], v[218:221], v[76:79], v[20:23]
	v_mfma_f32_16x16x32_bf16 v[20:23], v[226:229], v[76:79], v[64:67]
	v_mfma_f32_16x16x32_bf16 v[24:27], v[218:221], v[84:87], v[12:15]
	v_mfma_f32_16x16x32_bf16 v[28:31], v[226:229], v[84:87], v[8:11]
	v_mfma_f32_16x16x32_bf16 v[64:67], v[218:221], v[92:95], v[72:75]
	v_mfma_f32_16x16x32_bf16 v[68:71], v[226:229], v[92:95], v[80:83]
	s_setprio 0
	s_barrier
	ds_read_b128 v[12:15], v130
	ds_read_b128 v[8:11], v130 offset:1024
	ds_read_b128 v[76:79], v130 offset:2048
	ds_read_b128 v[72:75], v130 offset:3072
	ds_read_b128 v[140:143], v193 offset:32768
	ds_read_b128 v[148:151], v193 offset:33792
	ds_read_b128 v[218:221], v192 offset:32768
	ds_read_b128 v[222:225], v192 offset:33792
	ds_read_b128 v[226:229], v191 offset:32768
	ds_read_b128 v[230:233], v191 offset:33792
	ds_read_b128 v[234:237], v190 offset:32768
	ds_read_b128 v[238:241], v190 offset:33792
	s_waitcnt vmcnt(2)
	s_barrier
	s_waitcnt lgkmcnt(0)
	s_setprio 1
	s_waitcnt lgkmcnt(0)
	v_mfma_f32_16x16x32_bf16 v[80:83], v[12:15], v[140:143], v[124:127]
	v_mfma_f32_16x16x32_bf16 v[84:87], v[76:79], v[140:143], v[120:123]
	v_mfma_f32_16x16x32_bf16 v[88:91], v[12:15], v[218:221], v[116:119]
	v_mfma_f32_16x16x32_bf16 v[92:95], v[76:79], v[218:221], v[112:115]
	v_mfma_f32_16x16x32_bf16 v[108:111], v[12:15], v[226:229], v[108:111]
	v_mfma_f32_16x16x32_bf16 v[104:107], v[76:79], v[226:229], v[104:107]
	v_mfma_f32_16x16x32_bf16 v[100:103], v[12:15], v[234:237], v[100:103]
	v_mfma_f32_16x16x32_bf16 v[96:99], v[76:79], v[234:237], v[96:99]
	v_mfma_f32_16x16x32_bf16 v[152:155], v[8:11], v[148:151], v[80:83]
	v_mfma_f32_16x16x32_bf16 v[144:147], v[72:75], v[148:151], v[84:87]
	v_mfma_f32_16x16x32_bf16 v[136:139], v[8:11], v[222:225], v[88:91]
	v_mfma_f32_16x16x32_bf16 v[128:131], v[72:75], v[222:225], v[92:95]
	v_mfma_f32_16x16x32_bf16 v[120:123], v[8:11], v[230:233], v[108:111]
	v_mfma_f32_16x16x32_bf16 v[112:115], v[72:75], v[230:233], v[104:107]
	v_mfma_f32_16x16x32_bf16 v[104:107], v[8:11], v[238:241], v[100:103]
	v_mfma_f32_16x16x32_bf16 v[96:99], v[72:75], v[238:241], v[96:99]
	s_setprio 0
	s_barrier
	ds_read_b128 v[88:91], v132
	ds_read_b128 v[80:83], v132 offset:1024
	ds_read_b128 v[92:95], v132 offset:2048
	ds_read_b128 v[84:87], v132 offset:3072
	s_waitcnt vmcnt(0)
	s_barrier
	s_waitcnt lgkmcnt(0)
	s_setprio 1
	s_waitcnt lgkmcnt(0)
	v_mfma_f32_16x16x32_bf16 v[100:103], v[88:91], v[140:143], v[156:159]
	v_mfma_f32_16x16x32_bf16 v[108:111], v[92:95], v[140:143], v[160:163]
	v_mfma_f32_16x16x32_bf16 v[116:119], v[88:91], v[218:221], v[194:197]
	v_mfma_f32_16x16x32_bf16 v[124:127], v[92:95], v[218:221], v[198:201]
	v_mfma_f32_16x16x32_bf16 v[160:163], v[88:91], v[226:229], v[202:205]
	v_mfma_f32_16x16x32_bf16 v[194:197], v[92:95], v[226:229], v[206:209]
	v_mfma_f32_16x16x32_bf16 v[198:201], v[88:91], v[234:237], v[210:213]
	v_mfma_f32_16x16x32_bf16 v[202:205], v[92:95], v[234:237], v[214:217]
	v_mfma_f32_16x16x32_bf16 v[156:159], v[80:83], v[148:151], v[100:103]
	v_mfma_f32_16x16x32_bf16 v[148:151], v[84:87], v[148:151], v[108:111]
	v_mfma_f32_16x16x32_bf16 v[140:143], v[80:83], v[222:225], v[116:119]
	v_mfma_f32_16x16x32_bf16 v[132:135], v[84:87], v[222:225], v[124:127]
	v_mfma_f32_16x16x32_bf16 v[124:127], v[80:83], v[230:233], v[160:163]
	v_mfma_f32_16x16x32_bf16 v[116:119], v[84:87], v[230:233], v[194:197]
	v_mfma_f32_16x16x32_bf16 v[108:111], v[80:83], v[238:241], v[198:201]
	v_mfma_f32_16x16x32_bf16 v[100:103], v[84:87], v[238:241], v[202:205]
	s_setprio 0
	s_lshl_b64 s[56:57], s[46:47], 2
	s_barrier
	v_mbcnt_lo_u32_b32 v162, -1, 0
	v_mbcnt_hi_u32_b32 v162, -1, v162
	s_add_u32 s56, s87, s56
	v_add_u32_e32 v160, s64, v162
	s_addc_u32 s57, s88, s57
	v_and_b32_e32 v164, 0x100, v160
	v_and_b32_e32 v162, 15, v162
	v_lshl_add_u64 v[160:161], s[56:57], 0, v[164:165]
	v_lshlrev_b32_e32 v164, 2, v162
	v_lshl_add_u64 v[160:161], v[160:161], 0, v[164:165]
	global_load_dword v180, v[160:161], off
	global_load_dword v178, v[160:161], off offset:64
	global_load_dword v176, v[160:161], off offset:128
	global_load_dword v174, v[160:161], off offset:192
	global_load_dword v172, v[160:161], off offset:512
	global_load_dword v170, v[160:161], off offset:576
	global_load_dword v168, v[160:161], off offset:640
	global_load_dword v166, v[160:161], off offset:704
	v_mbcnt_lo_u32_b32 v194, -1, 0
	v_mbcnt_hi_u32_b32 v194, -1, v194
	s_cmp_lg_u32 s79, 0
	v_add_u32_e32 v160, s64, v194
	v_bfe_u32 v196, v160, 8, 1
	v_ashrrev_i32_e32 v199, 6, v160
	v_bfe_u32 v160, v194, 4, 2
	s_cselect_b64 s[56:57], -1, 0
	v_and_b32_e32 v197, 3, v199
	v_and_b32_e32 v195, 15, v194
	s_and_b64 vcc, exec, s[56:57]
	v_lshlrev_b32_e32 v198, 4, v160
	s_cbranch_vccz .LBB0_533
	s_lshl_b32 s14, s78, 22
	s_lshl_b32 s36, s80, 14
	s_add_i32 s36, s36, s14
	v_lshlrev_b32_e32 v160, 6, v195
	v_or3_b32 v160, s36, v160, v198
	v_lshl_add_u32 v160, v197, 20, v160
	v_lshl_or_b32 v164, v196, 12, v160
	s_waitcnt vmcnt(0)
	v_pk_mul_f32 v[160:161], v[154:155], v[180:181] op_sel_hi:[1,0]
	v_pk_mul_f32 v[200:201], v[146:147], v[180:181] op_sel_hi:[1,0]
	v_max_f32_e32 v160, 0, v160
	v_mul_f32_e32 v204, v160, v160
	v_max_f32_e32 v160, 0, v200
	v_pk_mul_f32 v[162:163], v[152:153], v[180:181] op_sel_hi:[1,0]
	v_mul_f32_e32 v200, v160, v160
	v_max_f32_e32 v160, 0, v161
	v_pk_mul_f32 v[202:203], v[144:145], v[180:181] op_sel_hi:[1,0]
	v_max_f32_e32 v162, 0, v162
	v_max_f32_e32 v163, 0, v163
	v_mul_f32_e32 v161, v160, v160
	v_max_f32_e32 v160, 0, v201
	v_mul_f32_e32 v162, v162, v162
	v_max_f32_e32 v202, 0, v202
	v_mul_f32_e32 v163, v163, v163
	v_max_f32_e32 v203, 0, v203
	v_mul_f32_e32 v201, v160, v160
	v_cvt_pk_bf16_f32 v160, v162, v163
	v_cvt_pk_bf16_f32 v161, v204, v161
	v_mul_f32_e32 v202, v202, v202
	v_mul_f32_e32 v203, v203, v203
	v_cvt_pk_bf16_f32 v162, v202, v203
	v_cvt_pk_bf16_f32 v163, v200, v201
	global_store_dwordx4 v164, v[160:163], s[0:1]
	v_pk_mul_f32 v[202:203], v[150:151], v[180:181] op_sel_hi:[1,0]
	v_lshl_add_u64 v[200:201], s[0:1], 0, v[164:165]
	v_pk_mul_f32 v[160:161], v[158:159], v[180:181] op_sel_hi:[1,0]
	v_pk_mul_f32 v[162:163], v[156:157], v[180:181] op_sel_hi:[1,0]
	v_max_f32_e32 v160, 0, v160
	v_mul_f32_e32 v206, v160, v160
	v_max_f32_e32 v160, 0, v202
	v_mul_f32_e32 v202, v160, v160
	v_max_f32_e32 v160, 0, v161
	v_pk_mul_f32 v[204:205], v[148:149], v[180:181] op_sel_hi:[1,0]
	v_max_f32_e32 v162, 0, v162
	v_max_f32_e32 v163, 0, v163
	v_mul_f32_e32 v161, v160, v160
	v_max_f32_e32 v160, 0, v203
	v_add_co_u32_e32 v200, vcc, s72, v200
	v_mul_f32_e32 v162, v162, v162
	v_max_f32_e32 v204, 0, v204
	v_mul_f32_e32 v163, v163, v163
	v_max_f32_e32 v205, 0, v205
	v_mul_f32_e32 v203, v160, v160
	v_cvt_pk_bf16_f32 v160, v162, v163
	v_cvt_pk_bf16_f32 v161, v206, v161
	v_addc_co_u32_e32 v201, vcc, 0, v201, vcc
	v_mul_f32_e32 v204, v204, v204
	v_mul_f32_e32 v205, v205, v205
	v_cvt_pk_bf16_f32 v162, v204, v205
	v_cvt_pk_bf16_f32 v163, v202, v203
	global_store_dwordx4 v[200:201], v[160:163], off
	v_pk_mul_f32 v[202:203], v[130:131], v[178:179] op_sel_hi:[1,0]
	v_pk_mul_f32 v[204:205], v[128:129], v[178:179] op_sel_hi:[1,0]
	v_pk_mul_f32 v[160:161], v[138:139], v[178:179] op_sel_hi:[1,0]
	v_pk_mul_f32 v[162:163], v[136:137], v[178:179] op_sel_hi:[1,0]
	v_max_f32_e32 v160, 0, v160
	v_mul_f32_e32 v206, v160, v160
	v_max_f32_e32 v160, 0, v202
	v_mul_f32_e32 v202, v160, v160
	v_max_f32_e32 v160, 0, v161
	v_max_f32_e32 v162, 0, v162
	v_max_f32_e32 v163, 0, v163
	v_mul_f32_e32 v161, v160, v160
	v_max_f32_e32 v160, 0, v203
	v_mul_f32_e32 v162, v162, v162
	v_max_f32_e32 v204, 0, v204
	v_mul_f32_e32 v163, v163, v163
	v_max_f32_e32 v205, 0, v205
	v_mul_f32_e32 v203, v160, v160
	v_cvt_pk_bf16_f32 v160, v162, v163
	v_cvt_pk_bf16_f32 v161, v206, v161
	v_mul_f32_e32 v204, v204, v204
	v_mul_f32_e32 v205, v205, v205
	v_cvt_pk_bf16_f32 v162, v204, v205
	v_cvt_pk_bf16_f32 v163, v202, v203
	global_store_dwordx4 v164, v[160:163], s[0:1] offset:1024
	v_pk_mul_f32 v[202:203], v[134:135], v[178:179] op_sel_hi:[1,0]
	v_pk_mul_f32 v[204:205], v[132:133], v[178:179] op_sel_hi:[1,0]
	v_pk_mul_f32 v[160:161], v[142:143], v[178:179] op_sel_hi:[1,0]
	v_pk_mul_f32 v[162:163], v[140:141], v[178:179] op_sel_hi:[1,0]
	v_max_f32_e32 v160, 0, v160
	v_mul_f32_e32 v206, v160, v160
	v_max_f32_e32 v160, 0, v202
	v_mul_f32_e32 v202, v160, v160
	v_max_f32_e32 v160, 0, v161
	v_max_f32_e32 v162, 0, v162
	v_max_f32_e32 v163, 0, v163
	v_mul_f32_e32 v161, v160, v160
	v_max_f32_e32 v160, 0, v203
	v_mul_f32_e32 v162, v162, v162
	v_max_f32_e32 v204, 0, v204
	v_mul_f32_e32 v163, v163, v163
	v_max_f32_e32 v205, 0, v205
	v_mul_f32_e32 v203, v160, v160
	v_cvt_pk_bf16_f32 v160, v162, v163
	v_cvt_pk_bf16_f32 v161, v206, v161
	v_mul_f32_e32 v204, v204, v204
	v_mul_f32_e32 v205, v205, v205
	v_cvt_pk_bf16_f32 v162, v204, v205
	v_cvt_pk_bf16_f32 v163, v202, v203
	global_store_dwordx4 v[200:201], v[160:163], off offset:1024
	v_pk_mul_f32 v[202:203], v[114:115], v[176:177] op_sel_hi:[1,0]
	v_pk_mul_f32 v[204:205], v[112:113], v[176:177] op_sel_hi:[1,0]
	v_pk_mul_f32 v[160:161], v[122:123], v[176:177] op_sel_hi:[1,0]
	v_pk_mul_f32 v[162:163], v[120:121], v[176:177] op_sel_hi:[1,0]
	v_max_f32_e32 v160, 0, v160
	v_mul_f32_e32 v206, v160, v160
	v_max_f32_e32 v160, 0, v202
	v_mul_f32_e32 v202, v160, v160
	v_max_f32_e32 v160, 0, v161
	v_max_f32_e32 v162, 0, v162
	v_max_f32_e32 v163, 0, v163
	v_mul_f32_e32 v161, v160, v160
	v_max_f32_e32 v160, 0, v203
	v_mul_f32_e32 v162, v162, v162
	v_max_f32_e32 v204, 0, v204
	v_mul_f32_e32 v163, v163, v163
	v_max_f32_e32 v205, 0, v205
	v_mul_f32_e32 v203, v160, v160
	v_cvt_pk_bf16_f32 v160, v162, v163
	v_cvt_pk_bf16_f32 v161, v206, v161
	v_mul_f32_e32 v204, v204, v204
	v_mul_f32_e32 v205, v205, v205
	v_cvt_pk_bf16_f32 v162, v204, v205
	v_cvt_pk_bf16_f32 v163, v202, v203
	global_store_dwordx4 v164, v[160:163], s[0:1] offset:2048
	v_pk_mul_f32 v[202:203], v[118:119], v[176:177] op_sel_hi:[1,0]
	v_pk_mul_f32 v[204:205], v[116:117], v[176:177] op_sel_hi:[1,0]
	v_pk_mul_f32 v[160:161], v[126:127], v[176:177] op_sel_hi:[1,0]
	v_pk_mul_f32 v[162:163], v[124:125], v[176:177] op_sel_hi:[1,0]
	v_max_f32_e32 v160, 0, v160
	v_mul_f32_e32 v206, v160, v160
	v_max_f32_e32 v160, 0, v202
	v_mul_f32_e32 v202, v160, v160
	v_max_f32_e32 v160, 0, v161
	v_max_f32_e32 v162, 0, v162
	v_max_f32_e32 v163, 0, v163
	v_mul_f32_e32 v161, v160, v160
	v_max_f32_e32 v160, 0, v203
	v_mul_f32_e32 v162, v162, v162
	v_max_f32_e32 v204, 0, v204
	v_mul_f32_e32 v163, v163, v163
	v_max_f32_e32 v205, 0, v205
	v_mul_f32_e32 v203, v160, v160
	v_cvt_pk_bf16_f32 v160, v162, v163
	v_cvt_pk_bf16_f32 v161, v206, v161
	v_mul_f32_e32 v204, v204, v204
	v_mul_f32_e32 v205, v205, v205
	v_cvt_pk_bf16_f32 v162, v204, v205
	v_cvt_pk_bf16_f32 v163, v202, v203
	global_store_dwordx4 v[200:201], v[160:163], off offset:2048
	v_pk_mul_f32 v[200:201], v[98:99], v[174:175] op_sel_hi:[1,0]
	v_pk_mul_f32 v[202:203], v[96:97], v[174:175] op_sel_hi:[1,0]
	v_pk_mul_f32 v[160:161], v[106:107], v[174:175] op_sel_hi:[1,0]
	v_pk_mul_f32 v[162:163], v[104:105], v[174:175] op_sel_hi:[1,0]
	v_max_f32_e32 v160, 0, v160
	v_mul_f32_e32 v204, v160, v160
	v_max_f32_e32 v160, 0, v200
	v_mul_f32_e32 v200, v160, v160
	v_max_f32_e32 v160, 0, v161
	v_max_f32_e32 v162, 0, v162
	v_max_f32_e32 v163, 0, v163
	v_mul_f32_e32 v161, v160, v160
	v_max_f32_e32 v160, 0, v201
	v_mul_f32_e32 v162, v162, v162
	v_max_f32_e32 v202, 0, v202
	v_mul_f32_e32 v163, v163, v163
	v_max_f32_e32 v203, 0, v203
	v_mul_f32_e32 v201, v160, v160
	v_cvt_pk_bf16_f32 v160, v162, v163
	v_cvt_pk_bf16_f32 v161, v204, v161
	v_mul_f32_e32 v202, v202, v202
	v_mul_f32_e32 v203, v203, v203
	v_cvt_pk_bf16_f32 v162, v202, v203
	v_cvt_pk_bf16_f32 v163, v200, v201
	global_store_dwordx4 v164, v[160:163], s[0:1] offset:3072
	v_pk_mul_f32 v[200:201], v[102:103], v[174:175] op_sel_hi:[1,0]
	v_pk_mul_f32 v[202:203], v[100:101], v[174:175] op_sel_hi:[1,0]
	v_pk_mul_f32 v[160:161], v[110:111], v[174:175] op_sel_hi:[1,0]
	v_pk_mul_f32 v[162:163], v[108:109], v[174:175] op_sel_hi:[1,0]
	v_max_f32_e32 v160, 0, v160
	v_mul_f32_e32 v204, v160, v160
	v_max_f32_e32 v160, 0, v200
	v_max_f32_e32 v162, 0, v162
	v_max_f32_e32 v163, 0, v163
	v_mul_f32_e32 v200, v160, v160
	v_max_f32_e32 v160, 0, v161
	v_mul_f32_e32 v162, v162, v162
	v_max_f32_e32 v202, 0, v202
	v_mul_f32_e32 v163, v163, v163
	v_max_f32_e32 v203, 0, v203
	v_mul_f32_e32 v161, v160, v160
	v_max_f32_e32 v160, 0, v201
	v_mul_f32_e32 v202, v202, v202
	v_mul_f32_e32 v203, v203, v203
	v_mul_f32_e32 v201, v160, v160
	v_cvt_pk_bf16_f32 v160, v162, v163
	v_cvt_pk_bf16_f32 v161, v204, v161
	v_cvt_pk_bf16_f32 v162, v202, v203
	v_cvt_pk_bf16_f32 v163, v200, v201
	v_add_u32_e32 v164, 0x80c00, v164
	s_cbranch_execnz .LBB0_525

.LBB0_561:
	ds_read_b128 v[162:165], v161
	ds_read_b128 v[166:169], v161 offset:1024
	ds_read_b128 v[170:173], v161 offset:2048
	ds_read_b128 v[174:177], v161 offset:3072
	ds_read_b128 v[178:181], v152
	ds_read_b128 v[182:185], v152 offset:1024
	ds_read_b128 v[186:189], v151
	ds_read_b128 v[190:193], v151 offset:1024
	ds_read_b128 v[194:197], v150
	ds_read_b128 v[198:201], v150 offset:1024
	ds_read_b128 v[202:205], v149
	ds_read_b128 v[206:209], v149 offset:1024
	s_waitcnt lgkmcnt(8)
	s_waitcnt vmcnt(10)
	s_barrier
	s_waitcnt lgkmcnt(0)
	s_waitcnt lgkmcnt(0)
	v_mfma_f32_16x16x32_bf16 v[124:127], v[162:165], v[178:181], v[124:127]
	v_mfma_f32_16x16x32_bf16 v[120:123], v[170:173], v[178:181], v[120:123]
	v_mfma_f32_16x16x32_bf16 v[116:119], v[162:165], v[186:189], v[116:119]
	v_mfma_f32_16x16x32_bf16 v[112:115], v[170:173], v[186:189], v[112:115]
	v_mfma_f32_16x16x32_bf16 v[108:111], v[162:165], v[194:197], v[108:111]
	v_mfma_f32_16x16x32_bf16 v[104:107], v[170:173], v[194:197], v[104:107]
	v_mfma_f32_16x16x32_bf16 v[100:103], v[162:165], v[202:205], v[100:103]
	v_mfma_f32_16x16x32_bf16 v[96:99], v[170:173], v[202:205], v[96:99]
	v_mfma_f32_16x16x32_bf16 v[124:127], v[166:169], v[182:185], v[124:127]
	v_mfma_f32_16x16x32_bf16 v[120:123], v[174:177], v[182:185], v[120:123]
	v_mfma_f32_16x16x32_bf16 v[116:119], v[166:169], v[190:193], v[116:119]
	v_mfma_f32_16x16x32_bf16 v[112:115], v[174:177], v[190:193], v[112:115]
	v_mfma_f32_16x16x32_bf16 v[108:111], v[166:169], v[198:201], v[108:111]
	v_mfma_f32_16x16x32_bf16 v[104:107], v[174:177], v[198:201], v[104:107]
	v_mfma_f32_16x16x32_bf16 v[100:103], v[166:169], v[206:209], v[100:103]
	v_mfma_f32_16x16x32_bf16 v[96:99], v[174:177], v[206:209], v[96:99]
	s_barrier
	v_readfirstlane_b32 s36, v148
	v_lshl_add_u64 v[226:227], v[130:131], 0, s[26:27]
	s_mov_b32 m0, s36
	v_readfirstlane_b32 s36, v147
	ds_read_b128 v[210:213], v158
	ds_read_b128 v[214:217], v158 offset:1024
	ds_read_b128 v[218:221], v158 offset:2048
	ds_read_b128 v[222:225], v158 offset:3072
	global_load_lds_dwordx4 v[226:227], off
	v_lshl_add_u64 v[226:227], v[130:131], 0, s[28:29]
	s_mov_b32 m0, s36
	s_add_i32 s68, s68, 2
	global_load_lds_dwordx4 v[226:227], off
	v_readfirstlane_b32 s36, v134
	v_lshl_add_u64 v[226:227], v[132:133], 0, s[30:31]
	s_mov_b32 m0, s36
	v_readfirstlane_b32 s36, v146
	global_load_lds_dwordx4 v[226:227], off
	v_lshl_add_u64 v[226:227], v[132:133], 0, s[34:35]
	s_mov_b32 m0, s36
	s_nop 0
	global_load_lds_dwordx4 v[226:227], off
	s_waitcnt vmcnt(12)
	s_barrier
	s_waitcnt lgkmcnt(0)
	s_waitcnt lgkmcnt(0)
	v_mfma_f32_16x16x32_bf16 v[92:95], v[210:213], v[178:181], v[92:95]
	v_mfma_f32_16x16x32_bf16 v[88:91], v[218:221], v[178:181], v[88:91]
	v_mfma_f32_16x16x32_bf16 v[84:87], v[210:213], v[186:189], v[84:87]
	v_mfma_f32_16x16x32_bf16 v[80:83], v[218:221], v[186:189], v[80:83]
	v_mfma_f32_16x16x32_bf16 v[76:79], v[210:213], v[194:197], v[76:79]
	v_mfma_f32_16x16x32_bf16 v[72:75], v[218:221], v[194:197], v[72:75]
	v_mfma_f32_16x16x32_bf16 v[68:71], v[210:213], v[202:205], v[68:71]
	v_mfma_f32_16x16x32_bf16 v[64:67], v[218:221], v[202:205], v[64:67]
	v_mfma_f32_16x16x32_bf16 v[92:95], v[214:217], v[182:185], v[92:95]
	v_mfma_f32_16x16x32_bf16 v[88:91], v[222:225], v[182:185], v[88:91]
	v_mfma_f32_16x16x32_bf16 v[84:87], v[214:217], v[190:193], v[84:87]
	v_mfma_f32_16x16x32_bf16 v[80:83], v[222:225], v[190:193], v[80:83]
	v_mfma_f32_16x16x32_bf16 v[76:79], v[214:217], v[198:201], v[76:79]
	v_mfma_f32_16x16x32_bf16 v[72:75], v[222:225], v[198:201], v[72:75]
	v_mfma_f32_16x16x32_bf16 v[68:71], v[214:217], v[206:209], v[68:71]
	v_mfma_f32_16x16x32_bf16 v[64:67], v[222:225], v[206:209], v[64:67]
	s_barrier
	ds_read_b128 v[178:181], v152 offset:16384
	ds_read_b128 v[182:185], v152 offset:17408
	ds_read_b128 v[186:189], v151 offset:16384
	ds_read_b128 v[190:193], v151 offset:17408
	ds_read_b128 v[194:197], v150 offset:16384
	ds_read_b128 v[198:201], v150 offset:17408
	ds_read_b128 v[202:205], v149 offset:16384
	ds_read_b128 v[206:209], v149 offset:17408
	v_readfirstlane_b32 s36, v145
	v_lshl_add_u64 v[226:227], v[130:131], 0, s[38:39]
	s_mov_b32 m0, s36
	v_readfirstlane_b32 s36, v144
	global_load_lds_dwordx4 v[226:227], off
	v_lshl_add_u64 v[226:227], v[130:131], 0, s[44:45]
	s_mov_b32 m0, s36
	s_nop 0
	global_load_lds_dwordx4 v[226:227], off
	s_barrier
	s_waitcnt lgkmcnt(0)
	s_waitcnt lgkmcnt(0)
	v_mfma_f32_16x16x32_bf16 v[60:63], v[162:165], v[178:181], v[60:63]
	v_mfma_f32_16x16x32_bf16 v[56:59], v[170:173], v[178:181], v[56:59]
	v_mfma_f32_16x16x32_bf16 v[52:55], v[162:165], v[186:189], v[52:55]
	v_mfma_f32_16x16x32_bf16 v[48:51], v[170:173], v[186:189], v[48:51]
	v_mfma_f32_16x16x32_bf16 v[44:47], v[162:165], v[194:197], v[44:47]
	v_mfma_f32_16x16x32_bf16 v[40:43], v[170:173], v[194:197], v[40:43]
	v_mfma_f32_16x16x32_bf16 v[36:39], v[162:165], v[202:205], v[36:39]
	v_mfma_f32_16x16x32_bf16 v[32:35], v[170:173], v[202:205], v[32:35]
	v_mfma_f32_16x16x32_bf16 v[60:63], v[166:169], v[182:185], v[60:63]
	v_mfma_f32_16x16x32_bf16 v[56:59], v[174:177], v[182:185], v[56:59]
	v_mfma_f32_16x16x32_bf16 v[52:55], v[166:169], v[190:193], v[52:55]
	v_mfma_f32_16x16x32_bf16 v[48:51], v[174:177], v[190:193], v[48:51]
	v_mfma_f32_16x16x32_bf16 v[44:47], v[166:169], v[198:201], v[44:47]
	v_mfma_f32_16x16x32_bf16 v[40:43], v[174:177], v[198:201], v[40:43]
	v_mfma_f32_16x16x32_bf16 v[36:39], v[166:169], v[206:209], v[36:39]
	v_mfma_f32_16x16x32_bf16 v[32:35], v[174:177], v[206:209], v[32:35]
	s_barrier
	v_readfirstlane_b32 s36, v143
	v_lshl_add_u64 v[164:165], v[132:133], 0, s[46:47]
	s_mov_b32 m0, s36
	v_readfirstlane_b32 s36, v142
	global_load_lds_dwordx4 v[164:165], off
	v_lshl_add_u64 v[164:165], v[132:133], 0, s[50:51]
	s_mov_b32 m0, s36
	s_nop 0
	global_load_lds_dwordx4 v[164:165], off
	s_waitcnt vmcnt(12)
	s_barrier
	v_mfma_f32_16x16x32_bf16 v[28:31], v[210:213], v[178:181], v[28:31]
	v_mfma_f32_16x16x32_bf16 v[24:27], v[218:221], v[178:181], v[24:27]
	v_mfma_f32_16x16x32_bf16 v[20:23], v[210:213], v[186:189], v[20:23]
	v_mfma_f32_16x16x32_bf16 v[16:19], v[218:221], v[186:189], v[16:19]
	v_mfma_f32_16x16x32_bf16 v[12:15], v[210:213], v[194:197], v[12:15]
	v_mfma_f32_16x16x32_bf16 v[8:11], v[218:221], v[194:197], v[8:11]
	v_mfma_f32_16x16x32_bf16 v[4:7], v[210:213], v[202:205], v[4:7]
	v_mfma_f32_16x16x32_bf16 v[0:3], v[218:221], v[202:205], v[0:3]
	v_mfma_f32_16x16x32_bf16 v[28:31], v[214:217], v[182:185], v[28:31]
	v_mfma_f32_16x16x32_bf16 v[24:27], v[222:225], v[182:185], v[24:27]
	v_mfma_f32_16x16x32_bf16 v[20:23], v[214:217], v[190:193], v[20:23]
	v_mfma_f32_16x16x32_bf16 v[16:19], v[222:225], v[190:193], v[16:19]
	v_mfma_f32_16x16x32_bf16 v[12:15], v[214:217], v[198:201], v[12:15]
	v_mfma_f32_16x16x32_bf16 v[8:11], v[222:225], v[198:201], v[8:11]
	v_mfma_f32_16x16x32_bf16 v[4:7], v[214:217], v[206:209], v[4:7]
	v_mfma_f32_16x16x32_bf16 v[0:3], v[222:225], v[206:209], v[0:3]
	s_barrier
	ds_read_b128 v[162:165], v154
	ds_read_b128 v[166:169], v154 offset:1024
	ds_read_b128 v[170:173], v154 offset:2048
	ds_read_b128 v[174:177], v154 offset:3072
	ds_read_b128 v[178:181], v152 offset:32768
	ds_read_b128 v[182:185], v152 offset:33792
	ds_read_b128 v[186:189], v151 offset:32768
	ds_read_b128 v[190:193], v151 offset:33792
	ds_read_b128 v[194:197], v150 offset:32768
	ds_read_b128 v[198:201], v150 offset:33792
	ds_read_b128 v[202:205], v149 offset:32768
	ds_read_b128 v[206:209], v149 offset:33792
	s_waitcnt lgkmcnt(8)
	s_waitcnt vmcnt(10)
	s_barrier
	s_waitcnt lgkmcnt(0)
	s_waitcnt lgkmcnt(0)
	v_mfma_f32_16x16x32_bf16 v[124:127], v[162:165], v[178:181], v[124:127]
	v_mfma_f32_16x16x32_bf16 v[120:123], v[170:173], v[178:181], v[120:123]
	v_mfma_f32_16x16x32_bf16 v[116:119], v[162:165], v[186:189], v[116:119]
	v_mfma_f32_16x16x32_bf16 v[112:115], v[170:173], v[186:189], v[112:115]
	v_mfma_f32_16x16x32_bf16 v[108:111], v[162:165], v[194:197], v[108:111]
	v_mfma_f32_16x16x32_bf16 v[104:107], v[170:173], v[194:197], v[104:107]
	v_mfma_f32_16x16x32_bf16 v[100:103], v[162:165], v[202:205], v[100:103]
	v_mfma_f32_16x16x32_bf16 v[96:99], v[170:173], v[202:205], v[96:99]
	v_mfma_f32_16x16x32_bf16 v[124:127], v[166:169], v[182:185], v[124:127]
	v_mfma_f32_16x16x32_bf16 v[120:123], v[174:177], v[182:185], v[120:123]
	v_mfma_f32_16x16x32_bf16 v[116:119], v[166:169], v[190:193], v[116:119]
	v_mfma_f32_16x16x32_bf16 v[112:115], v[174:177], v[190:193], v[112:115]
	v_mfma_f32_16x16x32_bf16 v[108:111], v[166:169], v[198:201], v[108:111]
	v_mfma_f32_16x16x32_bf16 v[104:107], v[174:177], v[198:201], v[104:107]
	v_mfma_f32_16x16x32_bf16 v[100:103], v[166:169], v[206:209], v[100:103]
	v_mfma_f32_16x16x32_bf16 v[96:99], v[174:177], v[206:209], v[96:99]
	s_barrier
	v_readfirstlane_b32 s36, v141
	v_lshl_add_u64 v[226:227], v[130:131], 0, s[56:57]
	s_mov_b32 m0, s36
	v_readfirstlane_b32 s36, v140
	ds_read_b128 v[210:213], v153
	ds_read_b128 v[214:217], v153 offset:1024
	ds_read_b128 v[218:221], v153 offset:2048
	ds_read_b128 v[222:225], v153 offset:3072
	global_load_lds_dwordx4 v[226:227], off
	v_lshl_add_u64 v[226:227], v[130:131], 0, s[58:59]
	s_mov_b32 m0, s36
	s_nop 0
	global_load_lds_dwordx4 v[226:227], off
	v_readfirstlane_b32 s36, v139
	v_lshl_add_u64 v[226:227], v[132:133], 0, s[60:61]
	s_mov_b32 m0, s36
	v_readfirstlane_b32 s36, v138
	global_load_lds_dwordx4 v[226:227], off
	s_mov_b32 m0, s36
	s_nop 0
	global_load_lds_dwordx4 v[132:133], off
	s_waitcnt vmcnt(12)
	s_barrier
	s_waitcnt lgkmcnt(0)
	s_waitcnt lgkmcnt(0)
	v_mfma_f32_16x16x32_bf16 v[92:95], v[210:213], v[178:181], v[92:95]
	v_mfma_f32_16x16x32_bf16 v[88:91], v[218:221], v[178:181], v[88:91]
	v_mfma_f32_16x16x32_bf16 v[84:87], v[210:213], v[186:189], v[84:87]
	v_mfma_f32_16x16x32_bf16 v[80:83], v[218:221], v[186:189], v[80:83]
	v_mfma_f32_16x16x32_bf16 v[76:79], v[210:213], v[194:197], v[76:79]
	v_mfma_f32_16x16x32_bf16 v[72:75], v[218:221], v[194:197], v[72:75]
	v_mfma_f32_16x16x32_bf16 v[68:71], v[210:213], v[202:205], v[68:71]
	v_mfma_f32_16x16x32_bf16 v[64:67], v[218:221], v[202:205], v[64:67]
	v_mfma_f32_16x16x32_bf16 v[92:95], v[214:217], v[182:185], v[92:95]
	v_mfma_f32_16x16x32_bf16 v[88:91], v[222:225], v[182:185], v[88:91]
	v_mfma_f32_16x16x32_bf16 v[84:87], v[214:217], v[190:193], v[84:87]
	v_mfma_f32_16x16x32_bf16 v[80:83], v[222:225], v[190:193], v[80:83]
	v_mfma_f32_16x16x32_bf16 v[76:79], v[214:217], v[198:201], v[76:79]
	v_mfma_f32_16x16x32_bf16 v[72:75], v[222:225], v[198:201], v[72:75]
	v_mfma_f32_16x16x32_bf16 v[68:71], v[214:217], v[206:209], v[68:71]
	v_mfma_f32_16x16x32_bf16 v[64:67], v[222:225], v[206:209], v[64:67]
	s_barrier
	ds_read_b128 v[178:181], v152 offset:49152
	ds_read_b128 v[182:185], v152 offset:50176
	ds_read_b128 v[186:189], v151 offset:49152
	ds_read_b128 v[190:193], v151 offset:50176
	ds_read_b128 v[194:197], v150 offset:49152
	ds_read_b128 v[198:201], v150 offset:50176
	ds_read_b128 v[202:205], v149 offset:49152
	ds_read_b128 v[206:209], v149 offset:50176
	v_readfirstlane_b32 s36, v137
	v_lshl_add_u64 v[226:227], v[130:131], 0, s[60:61]
	s_mov_b32 m0, s36
	v_readfirstlane_b32 s36, v136
	global_load_lds_dwordx4 v[226:227], off
	s_mov_b32 m0, s36
	s_nop 0
	global_load_lds_dwordx4 v[130:131], off
	s_barrier
	s_waitcnt lgkmcnt(0)
	s_waitcnt lgkmcnt(0)
	v_mfma_f32_16x16x32_bf16 v[60:63], v[162:165], v[178:181], v[60:63]
	v_mfma_f32_16x16x32_bf16 v[56:59], v[170:173], v[178:181], v[56:59]
	v_mfma_f32_16x16x32_bf16 v[52:55], v[162:165], v[186:189], v[52:55]
	v_mfma_f32_16x16x32_bf16 v[48:51], v[170:173], v[186:189], v[48:51]
	v_mfma_f32_16x16x32_bf16 v[44:47], v[162:165], v[194:197], v[44:47]
	v_mfma_f32_16x16x32_bf16 v[40:43], v[170:173], v[194:197], v[40:43]
	v_mfma_f32_16x16x32_bf16 v[36:39], v[162:165], v[202:205], v[36:39]
	v_mfma_f32_16x16x32_bf16 v[32:35], v[170:173], v[202:205], v[32:35]
	v_mfma_f32_16x16x32_bf16 v[60:63], v[166:169], v[182:185], v[60:63]
	v_mfma_f32_16x16x32_bf16 v[56:59], v[174:177], v[182:185], v[56:59]
	v_mfma_f32_16x16x32_bf16 v[52:55], v[166:169], v[190:193], v[52:55]
	v_mfma_f32_16x16x32_bf16 v[48:51], v[174:177], v[190:193], v[48:51]
	v_mfma_f32_16x16x32_bf16 v[44:47], v[166:169], v[198:201], v[44:47]
	v_mfma_f32_16x16x32_bf16 v[40:43], v[174:177], v[198:201], v[40:43]
	v_mfma_f32_16x16x32_bf16 v[36:39], v[166:169], v[206:209], v[36:39]
	v_mfma_f32_16x16x32_bf16 v[32:35], v[174:177], v[206:209], v[32:35]
	s_barrier
	v_lshl_add_u64 v[132:133], v[132:133], 0, s[64:65]
	v_readfirstlane_b32 s36, v160
	v_lshl_add_u64 v[164:165], v[132:133], 0, s[22:23]
	s_mov_b32 m0, s36
	v_readfirstlane_b32 s36, v159
	global_load_lds_dwordx4 v[164:165], off
	v_lshl_add_u64 v[164:165], v[132:133], 0, s[24:25]
	s_mov_b32 m0, s36
	s_nop 0
	global_load_lds_dwordx4 v[164:165], off
	s_waitcnt vmcnt(12)
	s_barrier
	v_mfma_f32_16x16x32_bf16 v[28:31], v[210:213], v[178:181], v[28:31]
	v_mfma_f32_16x16x32_bf16 v[24:27], v[218:221], v[178:181], v[24:27]
	v_mfma_f32_16x16x32_bf16 v[20:23], v[210:213], v[186:189], v[20:23]
	v_mfma_f32_16x16x32_bf16 v[16:19], v[218:221], v[186:189], v[16:19]
	v_mfma_f32_16x16x32_bf16 v[12:15], v[210:213], v[194:197], v[12:15]
	v_mfma_f32_16x16x32_bf16 v[8:11], v[218:221], v[194:197], v[8:11]
	v_mfma_f32_16x16x32_bf16 v[4:7], v[210:213], v[202:205], v[4:7]
	v_mfma_f32_16x16x32_bf16 v[0:3], v[218:221], v[202:205], v[0:3]
	v_mfma_f32_16x16x32_bf16 v[28:31], v[214:217], v[182:185], v[28:31]
	v_mfma_f32_16x16x32_bf16 v[24:27], v[222:225], v[182:185], v[24:27]
	v_mfma_f32_16x16x32_bf16 v[20:23], v[214:217], v[190:193], v[20:23]
	v_mfma_f32_16x16x32_bf16 v[16:19], v[222:225], v[190:193], v[16:19]
	v_mfma_f32_16x16x32_bf16 v[12:15], v[214:217], v[198:201], v[12:15]
	v_mfma_f32_16x16x32_bf16 v[8:11], v[222:225], v[198:201], v[8:11]
	v_mfma_f32_16x16x32_bf16 v[4:7], v[214:217], v[206:209], v[4:7]
	v_mfma_f32_16x16x32_bf16 v[0:3], v[222:225], v[206:209], v[0:3]
	v_lshl_add_u64 v[130:131], v[130:131], 0, s[62:63]
	s_cmp_lt_u32 s68, s67
	s_barrier
	s_cbranch_scc1 .LBB0_561
	s_lshl_b32 s36, s86, 5
	s_lshl_b32 s37, s86, 8
	s_and_b32 s36, s36, 0x1800
	s_and_b32 s37, s37, 0x700
	s_or_b32 s96, s37, s36
	s_lshl_b32 s36, s96, 6
	s_add_u32 s36, s70, s36
	s_addc_u32 s37, s71, 0
	s_add_i32 s20, s20, -1
	s_lshl_b64 s[68:69], s[20:21], 20
	v_add_u32_e32 v128, v156, v157
	s_add_u32 s68, s36, s68
	v_or_b32_e32 v128, v128, v155
	s_addc_u32 s69, s37, s69
	v_lshl_add_u64 v[156:157], s[68:69], 0, v[128:129]
	v_readfirstlane_b32 s20, v160
	v_lshl_add_u64 v[206:207], v[156:157], 0, s[4:5]
	s_mov_b32 m0, s20
	v_readfirstlane_b32 s20, v159
	ds_read_b128 v[130:133], v161
	ds_read_b128 v[162:165], v161 offset:1024
	ds_read_b128 v[166:169], v161 offset:2048
	ds_read_b128 v[170:173], v161 offset:3072
	ds_read_b128 v[174:177], v152
	ds_read_b128 v[178:181], v152 offset:1024
	ds_read_b128 v[182:185], v151
	ds_read_b128 v[186:189], v151 offset:1024
	ds_read_b128 v[190:193], v150
	ds_read_b128 v[194:197], v150 offset:1024
	ds_read_b128 v[198:201], v149
	ds_read_b128 v[202:205], v149 offset:1024
	global_load_lds_dwordx4 v[206:207], off
	v_lshl_add_u64 v[156:157], v[156:157], 0, s[6:7]
	s_mov_b32 m0, s20
	s_nop 0
	global_load_lds_dwordx4 v[156:157], off
	s_waitcnt vmcnt(10)
	s_barrier
	s_waitcnt lgkmcnt(0)
	s_setprio 1
	s_waitcnt lgkmcnt(0)
	v_mfma_f32_16x16x32_bf16 v[124:127], v[130:133], v[174:177], v[124:127]
	v_mfma_f32_16x16x32_bf16 v[120:123], v[166:169], v[174:177], v[120:123]
	v_mfma_f32_16x16x32_bf16 v[116:119], v[130:133], v[182:185], v[116:119]
	v_mfma_f32_16x16x32_bf16 v[112:115], v[166:169], v[182:185], v[112:115]
	v_mfma_f32_16x16x32_bf16 v[108:111], v[130:133], v[190:193], v[108:111]
	v_mfma_f32_16x16x32_bf16 v[104:107], v[166:169], v[190:193], v[104:107]
	v_mfma_f32_16x16x32_bf16 v[100:103], v[130:133], v[198:201], v[100:103]
	v_mfma_f32_16x16x32_bf16 v[96:99], v[166:169], v[198:201], v[96:99]
	v_mfma_f32_16x16x32_bf16 v[124:127], v[162:165], v[178:181], v[124:127]
	v_mfma_f32_16x16x32_bf16 v[120:123], v[170:173], v[178:181], v[120:123]
	v_mfma_f32_16x16x32_bf16 v[116:119], v[162:165], v[186:189], v[116:119]
	v_mfma_f32_16x16x32_bf16 v[112:115], v[170:173], v[186:189], v[112:115]
	v_mfma_f32_16x16x32_bf16 v[108:111], v[162:165], v[194:197], v[108:111]
	v_mfma_f32_16x16x32_bf16 v[104:107], v[170:173], v[194:197], v[104:107]
	v_mfma_f32_16x16x32_bf16 v[100:103], v[162:165], v[202:205], v[100:103]
	v_mfma_f32_16x16x32_bf16 v[96:99], v[170:173], v[202:205], v[96:99]
	s_setprio 0
	s_barrier
	ds_read_b128 v[206:209], v158
	ds_read_b128 v[210:213], v158 offset:1024
	ds_read_b128 v[214:217], v158 offset:2048
	ds_read_b128 v[156:159], v158 offset:3072
	s_barrier
	s_waitcnt lgkmcnt(0)
	s_setprio 1
	s_waitcnt lgkmcnt(0)
	v_mfma_f32_16x16x32_bf16 v[92:95], v[206:209], v[174:177], v[92:95]
	v_mfma_f32_16x16x32_bf16 v[88:91], v[214:217], v[174:177], v[88:91]
	v_mfma_f32_16x16x32_bf16 v[84:87], v[206:209], v[182:185], v[84:87]
	v_mfma_f32_16x16x32_bf16 v[80:83], v[214:217], v[182:185], v[80:83]
	v_mfma_f32_16x16x32_bf16 v[76:79], v[206:209], v[190:193], v[76:79]
	v_mfma_f32_16x16x32_bf16 v[72:75], v[214:217], v[190:193], v[72:75]
	v_mfma_f32_16x16x32_bf16 v[68:71], v[206:209], v[198:201], v[68:71]
	v_mfma_f32_16x16x32_bf16 v[64:67], v[214:217], v[198:201], v[64:67]
	v_mfma_f32_16x16x32_bf16 v[174:177], v[210:213], v[178:181], v[92:95]
	v_mfma_f32_16x16x32_bf16 v[178:181], v[156:159], v[178:181], v[88:91]
	v_mfma_f32_16x16x32_bf16 v[182:185], v[210:213], v[186:189], v[84:87]
	v_mfma_f32_16x16x32_bf16 v[186:189], v[156:159], v[186:189], v[80:83]
	v_mfma_f32_16x16x32_bf16 v[190:193], v[210:213], v[194:197], v[76:79]
	v_mfma_f32_16x16x32_bf16 v[194:197], v[156:159], v[194:197], v[72:75]
	v_mfma_f32_16x16x32_bf16 v[198:201], v[210:213], v[202:205], v[68:71]
	v_mfma_f32_16x16x32_bf16 v[202:205], v[156:159], v[202:205], v[64:67]
	s_setprio 0
	s_barrier
	s_nop 0
	ds_read_b128 v[64:67], v152 offset:16384
	ds_read_b128 v[68:71], v152 offset:17408
	ds_read_b128 v[72:75], v151 offset:16384
	ds_read_b128 v[76:79], v151 offset:17408
	ds_read_b128 v[80:83], v150 offset:16384
	ds_read_b128 v[84:87], v150 offset:17408
	ds_read_b128 v[88:91], v149 offset:16384
	ds_read_b128 v[92:95], v149 offset:17408
	s_waitcnt vmcnt(4)
	s_barrier
	s_waitcnt lgkmcnt(0)
	s_setprio 1
	s_waitcnt lgkmcnt(0)
	v_mfma_f32_16x16x32_bf16 v[60:63], v[130:133], v[64:67], v[60:63]
	v_mfma_f32_16x16x32_bf16 v[56:59], v[166:169], v[64:67], v[56:59]
	v_mfma_f32_16x16x32_bf16 v[52:55], v[130:133], v[72:75], v[52:55]
	v_mfma_f32_16x16x32_bf16 v[48:51], v[166:169], v[72:75], v[48:51]
	v_mfma_f32_16x16x32_bf16 v[218:221], v[130:133], v[80:83], v[44:47]
	v_mfma_f32_16x16x32_bf16 v[222:225], v[166:169], v[80:83], v[40:43]
	v_mfma_f32_16x16x32_bf16 v[130:133], v[130:133], v[88:91], v[36:39]
	v_mfma_f32_16x16x32_bf16 v[166:169], v[166:169], v[88:91], v[32:35]
	v_mfma_f32_16x16x32_bf16 v[32:35], v[162:165], v[68:71], v[60:63]
	v_mfma_f32_16x16x32_bf16 v[36:39], v[170:173], v[68:71], v[56:59]
	v_mfma_f32_16x16x32_bf16 v[40:43], v[162:165], v[76:79], v[52:55]
	v_mfma_f32_16x16x32_bf16 v[44:47], v[170:173], v[76:79], v[48:51]
	v_mfma_f32_16x16x32_bf16 v[48:51], v[162:165], v[84:87], v[218:221]
	v_mfma_f32_16x16x32_bf16 v[52:55], v[170:173], v[84:87], v[222:225]
	v_mfma_f32_16x16x32_bf16 v[56:59], v[162:165], v[92:95], v[130:133]
	v_mfma_f32_16x16x32_bf16 v[60:63], v[170:173], v[92:95], v[166:169]
	s_setprio 0
	s_setprio 1
	v_mfma_f32_16x16x32_bf16 v[28:31], v[206:209], v[64:67], v[28:31]
	v_mfma_f32_16x16x32_bf16 v[24:27], v[214:217], v[64:67], v[24:27]
	v_mfma_f32_16x16x32_bf16 v[20:23], v[206:209], v[72:75], v[20:23]
	v_mfma_f32_16x16x32_bf16 v[64:67], v[214:217], v[72:75], v[16:19]
	v_mfma_f32_16x16x32_bf16 v[72:75], v[206:209], v[80:83], v[12:15]
	v_mfma_f32_16x16x32_bf16 v[8:11], v[214:217], v[80:83], v[8:11]
	v_mfma_f32_16x16x32_bf16 v[80:83], v[206:209], v[88:91], v[4:7]
	v_mfma_f32_16x16x32_bf16 v[0:3], v[214:217], v[88:91], v[0:3]
	v_mfma_f32_16x16x32_bf16 v[4:7], v[210:213], v[68:71], v[28:31]
	v_mfma_f32_16x16x32_bf16 v[12:15], v[156:159], v[68:71], v[24:27]
	v_mfma_f32_16x16x32_bf16 v[16:19], v[210:213], v[76:79], v[20:23]
	v_mfma_f32_16x16x32_bf16 v[20:23], v[156:159], v[76:79], v[64:67]
	v_mfma_f32_16x16x32_bf16 v[24:27], v[210:213], v[84:87], v[72:75]
	v_mfma_f32_16x16x32_bf16 v[28:31], v[156:159], v[84:87], v[8:11]
	v_mfma_f32_16x16x32_bf16 v[64:67], v[210:213], v[92:95], v[80:83]
	v_mfma_f32_16x16x32_bf16 v[68:71], v[156:159], v[92:95], v[0:3]
	s_setprio 0
	s_barrier
	ds_read_b128 v[8:11], v154
	ds_read_b128 v[0:3], v154 offset:1024
	ds_read_b128 v[76:79], v154 offset:2048
	ds_read_b128 v[72:75], v154 offset:3072
	ds_read_b128 v[130:133], v152 offset:32768
	ds_read_b128 v[154:157], v152 offset:33792
	ds_read_b128 v[158:161], v151 offset:32768
	ds_read_b128 v[162:165], v151 offset:33792
	ds_read_b128 v[166:169], v150 offset:32768
	ds_read_b128 v[170:173], v150 offset:33792
	ds_read_b128 v[206:209], v149 offset:32768
	ds_read_b128 v[210:213], v149 offset:33792
	s_waitcnt vmcnt(2)
	s_barrier
	s_waitcnt lgkmcnt(0)
	s_setprio 1
	s_waitcnt lgkmcnt(0)
	v_mfma_f32_16x16x32_bf16 v[80:83], v[8:11], v[130:133], v[124:127]
	v_mfma_f32_16x16x32_bf16 v[84:87], v[76:79], v[130:133], v[120:123]
	v_mfma_f32_16x16x32_bf16 v[88:91], v[8:11], v[158:161], v[116:119]
	v_mfma_f32_16x16x32_bf16 v[92:95], v[76:79], v[158:161], v[112:115]
	v_mfma_f32_16x16x32_bf16 v[108:111], v[8:11], v[166:169], v[108:111]
	v_mfma_f32_16x16x32_bf16 v[104:107], v[76:79], v[166:169], v[104:107]
	v_mfma_f32_16x16x32_bf16 v[100:103], v[8:11], v[206:209], v[100:103]
	v_mfma_f32_16x16x32_bf16 v[96:99], v[76:79], v[206:209], v[96:99]
	v_mfma_f32_16x16x32_bf16 v[112:115], v[0:3], v[154:157], v[80:83]
	v_mfma_f32_16x16x32_bf16 v[116:119], v[72:75], v[154:157], v[84:87]
	v_mfma_f32_16x16x32_bf16 v[120:123], v[0:3], v[162:165], v[88:91]
	v_mfma_f32_16x16x32_bf16 v[124:127], v[72:75], v[162:165], v[92:95]
	v_mfma_f32_16x16x32_bf16 v[108:111], v[0:3], v[170:173], v[108:111]
	v_mfma_f32_16x16x32_bf16 v[104:107], v[72:75], v[170:173], v[104:107]
	v_mfma_f32_16x16x32_bf16 v[100:103], v[0:3], v[210:213], v[100:103]
	v_mfma_f32_16x16x32_bf16 v[96:99], v[72:75], v[210:213], v[96:99]
	s_setprio 0
	s_barrier
	ds_read_b128 v[88:91], v153
	ds_read_b128 v[80:83], v153 offset:1024
	ds_read_b128 v[92:95], v153 offset:2048
	ds_read_b128 v[84:87], v153 offset:3072
	s_waitcnt vmcnt(0)
	s_barrier
	s_waitcnt lgkmcnt(0)
	s_setprio 1
	s_waitcnt lgkmcnt(0)
	v_mfma_f32_16x16x32_bf16 v[174:177], v[88:91], v[130:133], v[174:177]
	v_mfma_f32_16x16x32_bf16 v[130:133], v[92:95], v[130:133], v[178:181]
	v_mfma_f32_16x16x32_bf16 v[178:181], v[88:91], v[158:161], v[182:185]
	v_mfma_f32_16x16x32_bf16 v[158:161], v[92:95], v[158:161], v[186:189]
	v_mfma_f32_16x16x32_bf16 v[182:185], v[88:91], v[166:169], v[190:193]
	v_mfma_f32_16x16x32_bf16 v[166:169], v[92:95], v[166:169], v[194:197]
	v_mfma_f32_16x16x32_bf16 v[186:189], v[88:91], v[206:209], v[198:201]
	v_mfma_f32_16x16x32_bf16 v[190:193], v[92:95], v[206:209], v[202:205]
	v_mfma_f32_16x16x32_bf16 v[174:177], v[80:83], v[154:157], v[174:177]
	v_mfma_f32_16x16x32_bf16 v[130:133], v[84:87], v[154:157], v[130:133]
	v_mfma_f32_16x16x32_bf16 v[154:157], v[80:83], v[162:165], v[178:181]
	v_mfma_f32_16x16x32_bf16 v[158:161], v[84:87], v[162:165], v[158:161]
	v_mfma_f32_16x16x32_bf16 v[162:165], v[80:83], v[170:173], v[182:185]
	v_mfma_f32_16x16x32_bf16 v[166:169], v[84:87], v[170:173], v[166:169]
	v_mfma_f32_16x16x32_bf16 v[170:173], v[80:83], v[210:213], v[186:189]
	v_mfma_f32_16x16x32_bf16 v[178:181], v[84:87], v[210:213], v[190:193]
	s_setprio 0
	s_barrier
	v_mbcnt_lo_u32_b32 v128, -1, 0
	v_mbcnt_hi_u32_b32 v128, -1, v128
	v_cvt_pk_bf16_f32 v112, v112, v113
	v_cvt_pk_bf16_f32 v113, v114, v115
	v_cvt_pk_bf16_f32 v114, v116, v117
	v_cvt_pk_bf16_f32 v115, v118, v119
	s_lshl_b32 s89, s66, 9
	v_add_u32_e32 v153, s74, v128
	v_ashrrev_i32_e32 v182, 6, v153
	v_and_b32_e32 v183, 15, v128
	v_and_b32_e32 v184, 48, v128
	v_mul_lo_u32 v185, v182, s79
	v_bfe_u32 v186, v128, 3, 3
	v_lshlrev_b32_e32 v128, 4, v128
	v_add_u32_e32 v185, 0x20000, v185
	v_lshrrev_b32_e32 v153, 2, v153
	v_and_b32_e32 v128, 0x70, v128
	v_mul_u32_u24_e32 v183, 0x90, v183
	v_and_b32_e32 v153, 64, v153
	v_add3_u32 v183, v185, v183, v184
	v_or_b32_e32 v184, v185, v128
	v_or3_b32 v153, s96, v153, v186
	v_mad_u32_u24 v184, v186, s81, v184
	ds_write_b128 v183, v[112:115]
	v_cvt_pk_bf16_f32 v112, v174, v175
	v_cvt_pk_bf16_f32 v113, v176, v177
	v_cvt_pk_bf16_f32 v114, v130, v131
	v_cvt_pk_bf16_f32 v115, v132, v133
	ds_write_b128 v183, v[112:115] offset:64
	v_lshlrev_b32_e32 v182, 7, v182
	ds_read_b128 v[112:115], v184
	v_lshlrev_b32_e32 v116, 12, v153
	v_and_or_b32 v116, v182, s82, v116
	v_or3_b32 v128, v116, s89, v128
	ds_read_b128 v[116:119], v184 offset:1152
	v_lshl_add_u64 v[130:131], s[0:1], 0, v[128:129]
	s_mov_b32 s20, 0x8000
	s_waitcnt lgkmcnt(0)
	global_store_dwordx4 v128, v[112:115], s[0:1]
	v_cvt_pk_bf16_f32 v108, v108, v109
	v_cvt_pk_bf16_f32 v109, v110, v111
	v_cvt_pk_bf16_f32 v110, v104, v105
	v_cvt_pk_bf16_f32 v111, v106, v107
	v_cvt_pk_bf16_f32 v104, v162, v163
	s_nop 1
	v_add_co_u32_e32 v112, vcc, s20, v130
	v_cvt_pk_bf16_f32 v114, v124, v125
	v_cvt_pk_bf16_f32 v115, v126, v127
	v_cvt_pk_bf16_f32 v105, v164, v165
	v_cvt_pk_bf16_f32 v106, v166, v167
	s_nop 1
	v_addc_co_u32_e32 v113, vcc, 0, v131, vcc
	global_store_dwordx4 v[112:113], v[116:119], off
	v_cvt_pk_bf16_f32 v112, v120, v121
	v_cvt_pk_bf16_f32 v113, v122, v123
	ds_write_b128 v183, v[112:115]
	v_cvt_pk_bf16_f32 v112, v154, v155
	v_cvt_pk_bf16_f32 v113, v156, v157
	v_cvt_pk_bf16_f32 v114, v158, v159
	v_cvt_pk_bf16_f32 v115, v160, v161
	ds_write_b128 v183, v[112:115] offset:64
	ds_read_b128 v[112:115], v184
	ds_read_b128 v[116:119], v184 offset:1152
	v_add_co_u32_e32 v120, vcc, s76, v130
	ds_write_b128 v183, v[108:111]
	v_cvt_pk_bf16_f32 v107, v168, v169
	ds_write_b128 v183, v[104:107] offset:64
	v_addc_co_u32_e32 v121, vcc, 0, v131, vcc
	ds_read_b128 v[104:107], v184
	ds_read_b128 v[108:111], v184 offset:1152
	s_waitcnt lgkmcnt(0)
	global_store_dwordx4 v[120:121], v[112:115], off
	v_cvt_pk_bf16_f32 v100, v100, v101
	v_cvt_pk_bf16_f32 v101, v102, v103
	v_cvt_pk_bf16_f32 v102, v96, v97
	v_cvt_pk_bf16_f32 v103, v98, v99
	ds_write_b128 v183, v[100:103]
	s_nop 0
	v_add_co_u32_e32 v112, vcc, s77, v130
	v_cvt_pk_bf16_f32 v96, v170, v171
	v_cvt_pk_bf16_f32 v97, v172, v173
	v_cvt_pk_bf16_f32 v98, v178, v179
	v_cvt_pk_bf16_f32 v99, v180, v181
	s_nop 1
	v_addc_co_u32_e32 v113, vcc, 0, v131, vcc
	global_store_dwordx4 v[112:113], v[116:119], off
	v_add_co_u32_e32 v112, vcc, s80, v130
	ds_write_b128 v183, v[96:99] offset:64
	s_nop 0
	v_addc_co_u32_e32 v113, vcc, 0, v131, vcc
	ds_read_b128 v[96:99], v184
	ds_read_b128 v[100:103], v184 offset:1152
	global_store_dwordx4 v[112:113], v[104:107], off
	s_nop 1
	v_add_co_u32_e32 v104, vcc, s83, v130
	s_nop 1
	v_addc_co_u32_e32 v105, vcc, 0, v131, vcc
	global_store_dwordx4 v[104:105], v[108:111], off
	v_add_co_u32_e32 v104, vcc, s85, v130
	s_nop 1
	v_addc_co_u32_e32 v105, vcc, 0, v131, vcc
	s_waitcnt lgkmcnt(0)
	global_store_dwordx4 v[104:105], v[96:99], off
	s_nop 1
	v_add_co_u32_e32 v96, vcc, s87, v130
	s_nop 1
	v_addc_co_u32_e32 v97, vcc, 0, v131, vcc
	global_store_dwordx4 v[96:97], v[100:103], off
	ds_read_b128 v[96:99], v152 offset:49152
	ds_read_b128 v[100:103], v152 offset:50176
	ds_read_b128 v[104:107], v151 offset:49152
	ds_read_b128 v[108:111], v151 offset:50176
	ds_read_b128 v[112:115], v150 offset:49152
	ds_read_b128 v[116:119], v150 offset:50176
	ds_read_b128 v[120:123], v149 offset:49152
	ds_read_b128 v[124:127], v149 offset:50176
	s_barrier
	s_waitcnt lgkmcnt(0)
	s_setprio 1
	s_waitcnt lgkmcnt(0)
	v_mfma_f32_16x16x32_bf16 v[32:35], v[8:11], v[96:99], v[32:35]
	v_mfma_f32_16x16x32_bf16 v[36:39], v[76:79], v[96:99], v[36:39]
	v_mfma_f32_16x16x32_bf16 v[40:43], v[8:11], v[104:107], v[40:43]
	v_mfma_f32_16x16x32_bf16 v[130:133], v[76:79], v[104:107], v[44:47]
	v_mfma_f32_16x16x32_bf16 v[150:153], v[8:11], v[112:115], v[48:51]
	v_mfma_f32_16x16x32_bf16 v[52:55], v[76:79], v[112:115], v[52:55]
	v_mfma_f32_16x16x32_bf16 v[8:11], v[8:11], v[120:123], v[56:59]
	v_mfma_f32_16x16x32_bf16 v[60:63], v[76:79], v[120:123], v[60:63]
	v_mfma_f32_16x16x32_bf16 v[56:59], v[0:3], v[100:103], v[32:35]
	v_mfma_f32_16x16x32_bf16 v[48:51], v[72:75], v[100:103], v[36:39]
	v_mfma_f32_16x16x32_bf16 v[44:47], v[0:3], v[108:111], v[40:43]
	v_mfma_f32_16x16x32_bf16 v[40:43], v[72:75], v[108:111], v[130:133]
	v_mfma_f32_16x16x32_bf16 v[36:39], v[0:3], v[116:119], v[150:153]
	v_mfma_f32_16x16x32_bf16 v[32:35], v[72:75], v[116:119], v[52:55]
	v_mfma_f32_16x16x32_bf16 v[8:11], v[0:3], v[124:127], v[8:11]
	v_mfma_f32_16x16x32_bf16 v[0:3], v[72:75], v[124:127], v[60:63]
	s_setprio 0
	s_setprio 1
	v_mfma_f32_16x16x32_bf16 v[4:7], v[88:91], v[96:99], v[4:7]
	v_mfma_f32_16x16x32_bf16 v[12:15], v[92:95], v[96:99], v[12:15]
	v_mfma_f32_16x16x32_bf16 v[16:19], v[88:91], v[104:107], v[16:19]
	v_mfma_f32_16x16x32_bf16 v[20:23], v[92:95], v[104:107], v[20:23]
	v_mfma_f32_16x16x32_bf16 v[72:75], v[88:91], v[112:115], v[24:27]
	v_mfma_f32_16x16x32_bf16 v[76:79], v[92:95], v[112:115], v[28:31]
	v_mfma_f32_16x16x32_bf16 v[64:67], v[88:91], v[120:123], v[64:67]
	v_mfma_f32_16x16x32_bf16 v[68:71], v[92:95], v[120:123], v[68:71]
	v_mfma_f32_16x16x32_bf16 v[60:63], v[80:83], v[100:103], v[4:7]
	v_mfma_f32_16x16x32_bf16 v[52:55], v[84:87], v[100:103], v[12:15]
	v_mfma_f32_16x16x32_bf16 v[28:31], v[80:83], v[108:111], v[16:19]
	v_mfma_f32_16x16x32_bf16 v[24:27], v[84:87], v[108:111], v[20:23]
	v_mfma_f32_16x16x32_bf16 v[20:23], v[80:83], v[116:119], v[72:75]
	v_mfma_f32_16x16x32_bf16 v[16:19], v[84:87], v[116:119], v[76:79]
	v_mfma_f32_16x16x32_bf16 v[12:15], v[80:83], v[124:127], v[64:67]
	v_mfma_f32_16x16x32_bf16 v[4:7], v[84:87], v[124:127], v[68:71]
	s_setprio 0
	v_cmp_gt_u32_e32 vcc, s88, v135
	s_barrier
	s_and_saveexec_b64 s[66:67], vcc
	s_cbranch_execz .LBB0_564
	s_barrier
